# v30 plus K-loop priority: per-segment s_setprio removed, waves 4-7 at static prio 1 inside GEMM K-loops
# speedup vs baseline: 1.0051x; 1.0051x over previous
.LBB0_115:
	s_ashr_i32 s93, s92, 31
	s_lshl_b64 s[18:19], s[92:93], 21
	s_add_u32 s22, s86, s18
	s_addc_u32 s23, s87, s19
	s_and_b64 s[18:19], s[8:9], exec
	s_cselect_b32 s89, s23, s95
	s_cselect_b32 s93, s22, s94
	s_ashr_i32 s85, s84, 31
	s_lshl_b64 s[18:19], s[84:85], 21
	s_add_u32 s18, s29, s18
	s_addc_u32 s19, s76, s19
	s_and_b64 s[34:35], s[8:9], exec
	s_cselect_b32 s85, s19, s97
	s_cselect_b32 s34, s18, s96
	s_add_u32 s35, s96, 0x100
	v_mov_b32_e32 v0, 0
	s_addc_u32 s36, s97, 0
	s_mov_b32 s37, -2
	v_mov_b32_e32 v1, v0
	v_mov_b32_e32 v2, v0
	v_mov_b32_e32 v3, v0
	v_mov_b32_e32 v4, v0
	v_mov_b32_e32 v5, v0
	v_mov_b32_e32 v6, v0
	v_mov_b32_e32 v7, v0
	v_mov_b32_e32 v16, v0
	v_mov_b32_e32 v17, v0
	v_mov_b32_e32 v18, v0
	v_mov_b32_e32 v19, v0
	v_mov_b32_e32 v20, v0
	v_mov_b32_e32 v21, v0
	v_mov_b32_e32 v22, v0
	v_mov_b32_e32 v23, v0
	v_mov_b32_e32 v32, v0
	v_mov_b32_e32 v33, v0
	v_mov_b32_e32 v34, v0
	v_mov_b32_e32 v35, v0
	v_mov_b32_e32 v36, v0
	v_mov_b32_e32 v37, v0
	v_mov_b32_e32 v38, v0
	v_mov_b32_e32 v39, v0
	v_mov_b32_e32 v48, v0
	v_mov_b32_e32 v49, v0
	v_mov_b32_e32 v50, v0
	v_mov_b32_e32 v51, v0
	v_mov_b32_e32 v52, v0
	v_mov_b32_e32 v53, v0
	v_mov_b32_e32 v54, v0
	v_mov_b32_e32 v55, v0
	v_mov_b32_e32 v8, v0
	v_mov_b32_e32 v9, v0
	v_mov_b32_e32 v10, v0
	v_mov_b32_e32 v11, v0
	v_mov_b32_e32 v12, v0
	v_mov_b32_e32 v13, v0
	v_mov_b32_e32 v14, v0
	v_mov_b32_e32 v15, v0
	v_mov_b32_e32 v24, v0
	v_mov_b32_e32 v25, v0
	v_mov_b32_e32 v26, v0
	v_mov_b32_e32 v27, v0
	v_mov_b32_e32 v28, v0
	v_mov_b32_e32 v29, v0
	v_mov_b32_e32 v30, v0
	v_mov_b32_e32 v31, v0
	v_mov_b32_e32 v40, v0
	v_mov_b32_e32 v41, v0
	v_mov_b32_e32 v42, v0
	v_mov_b32_e32 v43, v0
	v_mov_b32_e32 v44, v0
	v_mov_b32_e32 v45, v0
	v_mov_b32_e32 v46, v0
	v_mov_b32_e32 v47, v0
	v_mov_b32_e32 v56, v0
	v_mov_b32_e32 v57, v0
	v_mov_b32_e32 v58, v0
	v_mov_b32_e32 v59, v0
	v_mov_b32_e32 v60, v0
	v_mov_b32_e32 v61, v0
	v_mov_b32_e32 v62, v0
	v_mov_b32_e32 v63, v0
	v_mov_b32_e32 v64, v0
	v_mov_b32_e32 v65, v0
	v_mov_b32_e32 v66, v0
	v_mov_b32_e32 v67, v0
	v_mov_b32_e32 v68, v0
	v_mov_b32_e32 v69, v0
	v_mov_b32_e32 v70, v0
	v_mov_b32_e32 v71, v0
	v_mov_b32_e32 v76, v0
	v_mov_b32_e32 v77, v0
	v_mov_b32_e32 v78, v0
	v_mov_b32_e32 v79, v0
	v_mov_b32_e32 v84, v0
	v_mov_b32_e32 v85, v0
	v_mov_b32_e32 v86, v0
	v_mov_b32_e32 v87, v0
	v_mov_b32_e32 v92, v0
	v_mov_b32_e32 v93, v0
	v_mov_b32_e32 v94, v0
	v_mov_b32_e32 v95, v0
	v_mov_b32_e32 v100, v0
	v_mov_b32_e32 v101, v0
	v_mov_b32_e32 v102, v0
	v_mov_b32_e32 v103, v0
	v_mov_b32_e32 v108, v0
	v_mov_b32_e32 v109, v0
	v_mov_b32_e32 v110, v0
	v_mov_b32_e32 v111, v0
	v_mov_b32_e32 v116, v0
	v_mov_b32_e32 v117, v0
	v_mov_b32_e32 v118, v0
	v_mov_b32_e32 v119, v0
	v_mov_b32_e32 v72, v0
	v_mov_b32_e32 v73, v0
	v_mov_b32_e32 v74, v0
	v_mov_b32_e32 v75, v0
	v_mov_b32_e32 v80, v0
	v_mov_b32_e32 v81, v0
	v_mov_b32_e32 v82, v0
	v_mov_b32_e32 v83, v0
	v_mov_b32_e32 v88, v0
	v_mov_b32_e32 v89, v0
	v_mov_b32_e32 v90, v0
	v_mov_b32_e32 v91, v0
	v_mov_b32_e32 v96, v0
	v_mov_b32_e32 v97, v0
	v_mov_b32_e32 v98, v0
	v_mov_b32_e32 v99, v0
	v_mov_b32_e32 v104, v0
	v_mov_b32_e32 v105, v0
	v_mov_b32_e32 v106, v0
	v_mov_b32_e32 v107, v0
	v_mov_b32_e32 v112, v0
	v_mov_b32_e32 v113, v0
	v_mov_b32_e32 v114, v0
	v_mov_b32_e32 v115, v0
	v_mov_b32_e32 v120, v0
	v_mov_b32_e32 v121, v0
	v_mov_b32_e32 v122, v0
	v_mov_b32_e32 v123, v0
	v_mov_b32_e32 v124, v0
	v_mov_b32_e32 v125, v0
	v_mov_b32_e32 v126, v0
	v_mov_b32_e32 v127, v0
	s_cmpk_lt_u32 s97, 0x100
	s_cbranch_scc1 .Lmy_prio_skip0
	s_setprio 1
.Lmy_prio_skip0:
.LBB0_116:
	ds_read_b128 v[128:131], v229
	ds_read_b128 v[132:135], v229 offset:1024
	ds_read_b128 v[136:139], v229 offset:2048
	ds_read_b128 v[140:143], v229 offset:3072
	ds_read_b128 v[144:147], v230
	ds_read_b128 v[148:151], v230 offset:1024
	ds_read_b128 v[152:155], v230 offset:2048
	ds_read_b128 v[156:159], v230 offset:3072
	s_add_u32 vcc_lo, s94, 0x100
	s_addc_u32 vcc_hi, s95, 0
	s_cmp_eq_u32 s37, 60
	s_cselect_b32 s53, s89, vcc_hi
	s_cselect_b32 s52, s93, vcc_lo
	s_cselect_b32 s97, s85, s36
	s_cselect_b32 s96, s34, s35
	v_lshl_add_u64 v[210:211], s[94:95], 0, v[178:179]
	s_add_i32 m0, s67, 0xc000
	ds_read_b128 v[160:163], v231
	ds_read_b128 v[164:167], v231 offset:1024
	ds_read_b128 v[186:189], v231 offset:2048
	ds_read_b128 v[190:193], v231 offset:3072
	ds_read_b128 v[194:197], v231 offset:4096
	ds_read_b128 v[198:201], v231 offset:5120
	ds_read_b128 v[202:205], v231 offset:6144
	ds_read_b128 v[206:209], v231 offset:7168
	global_load_lds_dwordx4 v[210:211], off
	v_lshl_add_u64 v[210:211], s[94:95], 0, v[180:181]
	s_add_i32 m0, s67, 0xe000
	s_nop 0
	global_load_lds_dwordx4 v[210:211], off
	s_waitcnt vmcnt(8)
	s_waitcnt lgkmcnt(0)
	s_barrier
	s_waitcnt lgkmcnt(0)
	v_mfma_f32_16x16x32_bf16 v[124:127], v[128:131], v[160:163], v[124:127]
	v_mfma_f32_16x16x32_bf16 v[120:123], v[136:139], v[160:163], v[120:123]
	v_mfma_f32_16x16x32_bf16 v[112:115], v[128:131], v[186:189], v[112:115]
	v_mfma_f32_16x16x32_bf16 v[104:107], v[136:139], v[186:189], v[104:107]
	v_mfma_f32_16x16x32_bf16 v[96:99], v[128:131], v[194:197], v[96:99]
	v_mfma_f32_16x16x32_bf16 v[88:91], v[136:139], v[194:197], v[88:91]
	v_mfma_f32_16x16x32_bf16 v[80:83], v[128:131], v[202:205], v[80:83]
	v_mfma_f32_16x16x32_bf16 v[72:75], v[136:139], v[202:205], v[72:75]
	v_mfma_f32_16x16x32_bf16 v[124:127], v[132:135], v[164:167], v[124:127]
	v_mfma_f32_16x16x32_bf16 v[120:123], v[140:143], v[164:167], v[120:123]
	v_mfma_f32_16x16x32_bf16 v[112:115], v[132:135], v[190:193], v[112:115]
	v_mfma_f32_16x16x32_bf16 v[104:107], v[140:143], v[190:193], v[104:107]
	v_mfma_f32_16x16x32_bf16 v[96:99], v[132:135], v[198:201], v[96:99]
	v_mfma_f32_16x16x32_bf16 v[88:91], v[140:143], v[198:201], v[88:91]
	v_mfma_f32_16x16x32_bf16 v[80:83], v[132:135], v[206:209], v[80:83]
	v_mfma_f32_16x16x32_bf16 v[72:75], v[140:143], v[206:209], v[72:75]
	v_mfma_f32_16x16x32_bf16 v[116:119], v[144:147], v[160:163], v[116:119]
	v_mfma_f32_16x16x32_bf16 v[108:111], v[152:155], v[160:163], v[108:111]
	v_mfma_f32_16x16x32_bf16 v[100:103], v[144:147], v[186:189], v[100:103]
	v_mfma_f32_16x16x32_bf16 v[92:95], v[152:155], v[186:189], v[92:95]
	v_mfma_f32_16x16x32_bf16 v[84:87], v[144:147], v[194:197], v[84:87]
	v_mfma_f32_16x16x32_bf16 v[76:79], v[152:155], v[194:197], v[76:79]
	v_mfma_f32_16x16x32_bf16 v[68:71], v[144:147], v[202:205], v[68:71]
	v_mfma_f32_16x16x32_bf16 v[64:67], v[152:155], v[202:205], v[64:67]
	v_mfma_f32_16x16x32_bf16 v[116:119], v[148:151], v[164:167], v[116:119]
	v_mfma_f32_16x16x32_bf16 v[108:111], v[156:159], v[164:167], v[108:111]
	v_mfma_f32_16x16x32_bf16 v[100:103], v[148:151], v[190:193], v[100:103]
	v_mfma_f32_16x16x32_bf16 v[92:95], v[156:159], v[190:193], v[92:95]
	v_mfma_f32_16x16x32_bf16 v[84:87], v[148:151], v[198:201], v[84:87]
	v_mfma_f32_16x16x32_bf16 v[76:79], v[156:159], v[198:201], v[76:79]
	v_mfma_f32_16x16x32_bf16 v[68:71], v[148:151], v[206:209], v[68:71]
	v_mfma_f32_16x16x32_bf16 v[64:67], v[156:159], v[206:209], v[64:67]
	s_barrier
	s_add_i32 s38, s81, s91
	v_lshl_add_u64 v[210:211], s[96:97], 0, v[170:171]
	s_mov_b32 m0, s38
	ds_read_b128 v[160:163], v231 offset:16384
	ds_read_b128 v[164:167], v231 offset:17408
	ds_read_b128 v[186:189], v231 offset:18432
	ds_read_b128 v[190:193], v231 offset:19456
	ds_read_b128 v[194:197], v231 offset:20480
	ds_read_b128 v[198:201], v231 offset:21504
	ds_read_b128 v[202:205], v231 offset:22528
	ds_read_b128 v[206:209], v231 offset:23552
	global_load_lds_dwordx4 v[210:211], off
	s_add_i32 m0, s38, 0x2000
	s_add_u32 s38, s96, 0x100000
	v_lshl_add_u64 v[212:213], s[96:97], 0, v[174:175]
	s_addc_u32 s39, s97, 0
	s_add_i32 s40, s14, s91
	global_load_lds_dwordx4 v[212:213], off
	v_lshl_add_u64 v[214:215], s[38:39], 0, v[170:171]
	s_mov_b32 m0, s40
	v_lshl_add_u64 v[216:217], s[52:53], 0, v[172:173]
	global_load_lds_dwordx4 v[214:215], off
	v_lshl_add_u64 v[214:215], s[38:39], 0, v[174:175]
	s_add_i32 m0, s40, 0x2000
	s_nop 0
	global_load_lds_dwordx4 v[214:215], off
	v_lshl_add_u64 v[214:215], s[52:53], 0, v[168:169]
	s_mov_b32 m0, s67
	s_nop 0
	global_load_lds_dwordx4 v[214:215], off
	s_mov_b32 m0, s16
	s_nop 0
	global_load_lds_dwordx4 v[216:217], off
	s_waitcnt vmcnt(8)
	s_waitcnt lgkmcnt(0)
	s_barrier
	s_waitcnt lgkmcnt(0)
	v_mfma_f32_16x16x32_bf16 v[60:63], v[128:131], v[160:163], v[60:63]
	v_mfma_f32_16x16x32_bf16 v[56:59], v[136:139], v[160:163], v[56:59]
	v_mfma_f32_16x16x32_bf16 v[44:47], v[128:131], v[186:189], v[44:47]
	v_mfma_f32_16x16x32_bf16 v[40:43], v[136:139], v[186:189], v[40:43]
	v_mfma_f32_16x16x32_bf16 v[28:31], v[128:131], v[194:197], v[28:31]
	v_mfma_f32_16x16x32_bf16 v[24:27], v[136:139], v[194:197], v[24:27]
	v_mfma_f32_16x16x32_bf16 v[12:15], v[128:131], v[202:205], v[12:15]
	v_mfma_f32_16x16x32_bf16 v[8:11], v[136:139], v[202:205], v[8:11]
	v_mfma_f32_16x16x32_bf16 v[60:63], v[132:135], v[164:167], v[60:63]
	v_mfma_f32_16x16x32_bf16 v[56:59], v[140:143], v[164:167], v[56:59]
	v_mfma_f32_16x16x32_bf16 v[44:47], v[132:135], v[190:193], v[44:47]
	v_mfma_f32_16x16x32_bf16 v[40:43], v[140:143], v[190:193], v[40:43]
	v_mfma_f32_16x16x32_bf16 v[28:31], v[132:135], v[198:201], v[28:31]
	v_mfma_f32_16x16x32_bf16 v[24:27], v[140:143], v[198:201], v[24:27]
	v_mfma_f32_16x16x32_bf16 v[12:15], v[132:135], v[206:209], v[12:15]
	v_mfma_f32_16x16x32_bf16 v[8:11], v[140:143], v[206:209], v[8:11]
	v_mfma_f32_16x16x32_bf16 v[52:55], v[144:147], v[160:163], v[52:55]
	v_mfma_f32_16x16x32_bf16 v[48:51], v[152:155], v[160:163], v[48:51]
	v_mfma_f32_16x16x32_bf16 v[36:39], v[144:147], v[186:189], v[36:39]
	v_mfma_f32_16x16x32_bf16 v[32:35], v[152:155], v[186:189], v[32:35]
	v_mfma_f32_16x16x32_bf16 v[20:23], v[144:147], v[194:197], v[20:23]
	v_mfma_f32_16x16x32_bf16 v[16:19], v[152:155], v[194:197], v[16:19]
	v_mfma_f32_16x16x32_bf16 v[4:7], v[144:147], v[202:205], v[4:7]
	v_mfma_f32_16x16x32_bf16 v[0:3], v[152:155], v[202:205], v[0:3]
	v_mfma_f32_16x16x32_bf16 v[52:55], v[148:151], v[164:167], v[52:55]
	v_mfma_f32_16x16x32_bf16 v[48:51], v[156:159], v[164:167], v[48:51]
	v_mfma_f32_16x16x32_bf16 v[36:39], v[148:151], v[190:193], v[36:39]
	v_mfma_f32_16x16x32_bf16 v[32:35], v[156:159], v[190:193], v[32:35]
	v_mfma_f32_16x16x32_bf16 v[20:23], v[148:151], v[198:201], v[20:23]
	v_mfma_f32_16x16x32_bf16 v[16:19], v[156:159], v[198:201], v[16:19]
	v_mfma_f32_16x16x32_bf16 v[4:7], v[148:151], v[206:209], v[4:7]
	v_mfma_f32_16x16x32_bf16 v[0:3], v[156:159], v[206:209], v[0:3]
	s_barrier
	s_add_i32 s40, 0, 0x18000
	s_add_i32 s41, 0, 0x1c000
	v_add_u32_e32 v140, s40, v225
	v_add_u32_e32 v156, s41, v225
	ds_read_b128 v[128:131], v140
	ds_read_b128 v[132:135], v140 offset:1024
	ds_read_b128 v[136:139], v140 offset:2048
	ds_read_b128 v[140:143], v140 offset:3072
	ds_read_b128 v[144:147], v156
	ds_read_b128 v[148:151], v156 offset:1024
	ds_read_b128 v[152:155], v156 offset:2048
	ds_read_b128 v[156:159], v156 offset:3072
	s_add_u32 s38, s52, 0x100000
	s_addc_u32 s39, s53, 0
	s_mov_b32 m0, s17
	v_lshl_add_u64 v[218:219], s[38:39], 0, v[168:169]
	ds_read_b128 v[160:163], v231 offset:32768
	ds_read_b128 v[164:167], v231 offset:33792
	ds_read_b128 v[186:189], v231 offset:34816
	ds_read_b128 v[190:193], v231 offset:35840
	ds_read_b128 v[194:197], v231 offset:36864
	ds_read_b128 v[198:201], v231 offset:37888
	ds_read_b128 v[202:205], v231 offset:38912
	ds_read_b128 v[206:209], v231 offset:39936
	global_load_lds_dwordx4 v[218:219], off
	v_lshl_add_u64 v[218:219], s[38:39], 0, v[172:173]
	s_mov_b32 m0, s10
	s_nop 0
	global_load_lds_dwordx4 v[218:219], off
	s_waitcnt vmcnt(8)
	s_waitcnt lgkmcnt(0)
	s_barrier
	s_waitcnt lgkmcnt(0)
	v_mfma_f32_16x16x32_bf16 v[124:127], v[128:131], v[160:163], v[124:127]
	v_mfma_f32_16x16x32_bf16 v[120:123], v[136:139], v[160:163], v[120:123]
	v_mfma_f32_16x16x32_bf16 v[112:115], v[128:131], v[186:189], v[112:115]
	v_mfma_f32_16x16x32_bf16 v[104:107], v[136:139], v[186:189], v[104:107]
	v_mfma_f32_16x16x32_bf16 v[96:99], v[128:131], v[194:197], v[96:99]
	v_mfma_f32_16x16x32_bf16 v[88:91], v[136:139], v[194:197], v[88:91]
	v_mfma_f32_16x16x32_bf16 v[80:83], v[128:131], v[202:205], v[80:83]
	v_mfma_f32_16x16x32_bf16 v[72:75], v[136:139], v[202:205], v[72:75]
	v_mfma_f32_16x16x32_bf16 v[124:127], v[132:135], v[164:167], v[124:127]
	v_mfma_f32_16x16x32_bf16 v[120:123], v[140:143], v[164:167], v[120:123]
	v_mfma_f32_16x16x32_bf16 v[112:115], v[132:135], v[190:193], v[112:115]
	v_mfma_f32_16x16x32_bf16 v[104:107], v[140:143], v[190:193], v[104:107]
	v_mfma_f32_16x16x32_bf16 v[96:99], v[132:135], v[198:201], v[96:99]
	v_mfma_f32_16x16x32_bf16 v[88:91], v[140:143], v[198:201], v[88:91]
	v_mfma_f32_16x16x32_bf16 v[80:83], v[132:135], v[206:209], v[80:83]
	v_mfma_f32_16x16x32_bf16 v[72:75], v[140:143], v[206:209], v[72:75]
	v_mfma_f32_16x16x32_bf16 v[116:119], v[144:147], v[160:163], v[116:119]
	v_mfma_f32_16x16x32_bf16 v[108:111], v[152:155], v[160:163], v[108:111]
	v_mfma_f32_16x16x32_bf16 v[100:103], v[144:147], v[186:189], v[100:103]
	v_mfma_f32_16x16x32_bf16 v[92:95], v[152:155], v[186:189], v[92:95]
	v_mfma_f32_16x16x32_bf16 v[84:87], v[144:147], v[194:197], v[84:87]
	v_mfma_f32_16x16x32_bf16 v[76:79], v[152:155], v[194:197], v[76:79]
	v_mfma_f32_16x16x32_bf16 v[68:71], v[144:147], v[202:205], v[68:71]
	v_mfma_f32_16x16x32_bf16 v[64:67], v[152:155], v[202:205], v[64:67]
	v_mfma_f32_16x16x32_bf16 v[116:119], v[148:151], v[164:167], v[116:119]
	v_mfma_f32_16x16x32_bf16 v[108:111], v[156:159], v[164:167], v[108:111]
	v_mfma_f32_16x16x32_bf16 v[100:103], v[148:151], v[190:193], v[100:103]
	v_mfma_f32_16x16x32_bf16 v[92:95], v[156:159], v[190:193], v[92:95]
	v_mfma_f32_16x16x32_bf16 v[84:87], v[148:151], v[198:201], v[84:87]
	v_mfma_f32_16x16x32_bf16 v[76:79], v[156:159], v[198:201], v[76:79]
	v_mfma_f32_16x16x32_bf16 v[68:71], v[148:151], v[206:209], v[68:71]
	v_mfma_f32_16x16x32_bf16 v[64:67], v[156:159], v[206:209], v[64:67]
	s_barrier
	s_add_i32 s38, s40, s91
	v_lshl_add_u64 v[210:211], v[210:211], 0, s[56:57]
	s_mov_b32 m0, s38
	ds_read_b128 v[160:163], v231 offset:49152
	ds_read_b128 v[164:167], v231 offset:50176
	ds_read_b128 v[186:189], v231 offset:51200
	ds_read_b128 v[190:193], v231 offset:52224
	ds_read_b128 v[194:197], v231 offset:53248
	ds_read_b128 v[198:201], v231 offset:54272
	ds_read_b128 v[202:205], v231 offset:55296
	ds_read_b128 v[206:209], v231 offset:56320
	global_load_lds_dwordx4 v[210:211], off
	s_add_i32 m0, s38, 0x2000
	s_add_u32 s38, s96, 0x100080
	v_lshl_add_u64 v[210:211], v[212:213], 0, s[56:57]
	s_addc_u32 s39, s97, 0
	s_add_i32 s40, s41, s91
	global_load_lds_dwordx4 v[210:211], off
	v_lshl_add_u64 v[210:211], s[38:39], 0, v[170:171]
	s_mov_b32 m0, s40
	s_nop 0
	global_load_lds_dwordx4 v[210:211], off
	v_lshl_add_u64 v[210:211], s[38:39], 0, v[174:175]
	s_add_i32 m0, s40, 0x2000
	s_nop 0
	global_load_lds_dwordx4 v[210:211], off
	v_lshl_add_u64 v[210:211], v[214:215], 0, s[56:57]
	s_mov_b32 m0, s13
	s_nop 0
	global_load_lds_dwordx4 v[210:211], off
	v_lshl_add_u64 v[210:211], v[216:217], 0, s[56:57]
	s_mov_b32 m0, s77
	s_nop 0
	global_load_lds_dwordx4 v[210:211], off
	s_waitcnt vmcnt(8)
	s_waitcnt lgkmcnt(0)
	s_barrier
	s_waitcnt lgkmcnt(0)
	v_mfma_f32_16x16x32_bf16 v[60:63], v[128:131], v[160:163], v[60:63]
	v_mfma_f32_16x16x32_bf16 v[56:59], v[136:139], v[160:163], v[56:59]
	v_mfma_f32_16x16x32_bf16 v[44:47], v[128:131], v[186:189], v[44:47]
	v_mfma_f32_16x16x32_bf16 v[40:43], v[136:139], v[186:189], v[40:43]
	v_mfma_f32_16x16x32_bf16 v[28:31], v[128:131], v[194:197], v[28:31]
	v_mfma_f32_16x16x32_bf16 v[24:27], v[136:139], v[194:197], v[24:27]
	v_mfma_f32_16x16x32_bf16 v[12:15], v[128:131], v[202:205], v[12:15]
	v_mfma_f32_16x16x32_bf16 v[8:11], v[136:139], v[202:205], v[8:11]
	v_mfma_f32_16x16x32_bf16 v[60:63], v[132:135], v[164:167], v[60:63]
	v_mfma_f32_16x16x32_bf16 v[56:59], v[140:143], v[164:167], v[56:59]
	v_mfma_f32_16x16x32_bf16 v[44:47], v[132:135], v[190:193], v[44:47]
	v_mfma_f32_16x16x32_bf16 v[40:43], v[140:143], v[190:193], v[40:43]
	v_mfma_f32_16x16x32_bf16 v[28:31], v[132:135], v[198:201], v[28:31]
	v_mfma_f32_16x16x32_bf16 v[24:27], v[140:143], v[198:201], v[24:27]
	v_mfma_f32_16x16x32_bf16 v[12:15], v[132:135], v[206:209], v[12:15]
	v_mfma_f32_16x16x32_bf16 v[8:11], v[140:143], v[206:209], v[8:11]
	v_mfma_f32_16x16x32_bf16 v[52:55], v[144:147], v[160:163], v[52:55]
	v_mfma_f32_16x16x32_bf16 v[48:51], v[152:155], v[160:163], v[48:51]
	v_mfma_f32_16x16x32_bf16 v[36:39], v[144:147], v[186:189], v[36:39]
	v_mfma_f32_16x16x32_bf16 v[32:35], v[152:155], v[186:189], v[32:35]
	v_mfma_f32_16x16x32_bf16 v[20:23], v[144:147], v[194:197], v[20:23]
	v_mfma_f32_16x16x32_bf16 v[16:19], v[152:155], v[194:197], v[16:19]
	v_mfma_f32_16x16x32_bf16 v[4:7], v[144:147], v[202:205], v[4:7]
	v_mfma_f32_16x16x32_bf16 v[0:3], v[152:155], v[202:205], v[0:3]
	v_mfma_f32_16x16x32_bf16 v[52:55], v[148:151], v[164:167], v[52:55]
	v_mfma_f32_16x16x32_bf16 v[48:51], v[156:159], v[164:167], v[48:51]
	v_mfma_f32_16x16x32_bf16 v[36:39], v[148:151], v[190:193], v[36:39]
	v_mfma_f32_16x16x32_bf16 v[32:35], v[156:159], v[190:193], v[32:35]
	v_mfma_f32_16x16x32_bf16 v[20:23], v[148:151], v[198:201], v[20:23]
	v_mfma_f32_16x16x32_bf16 v[16:19], v[156:159], v[198:201], v[16:19]
	v_mfma_f32_16x16x32_bf16 v[4:7], v[148:151], v[206:209], v[4:7]
	v_mfma_f32_16x16x32_bf16 v[0:3], v[156:159], v[206:209], v[0:3]
	s_barrier
	s_add_i32 s37, s37, 2
	s_add_u32 s35, s35, 0x100
	s_addc_u32 s36, s36, 0
	s_cmp_gt_u32 s37, 61
	s_mov_b64 s[94:95], vcc
	s_cbranch_scc0 .LBB0_116
	s_setprio 0
	s_and_b64 vcc, exec, s[64:65]
	s_cbranch_vccz .LBB0_119
	s_barrier

.LBB0_520:
	s_ashr_i32 s13, s12, 31
	s_lshl_b64 s[18:19], s[12:13], 20
	s_add_u32 s18, s33, s18
	s_addc_u32 s19, s52, s19
	s_and_b64 s[34:35], s[0:1], exec
	s_cselect_b32 s13, s19, s47
	s_cselect_b32 s64, s18, s46
	s_ashr_i32 s11, s10, 31
	s_lshl_b64 s[34:35], s[10:11], 20
	v_readlane_b32 s11, v254, 40
	s_add_u32 s44, s11, s34
	v_readlane_b32 s11, v254, 41
	s_addc_u32 s45, s11, s35
	s_and_b64 s[34:35], s[0:1], exec
	s_cselect_b32 s11, s45, s49
	s_cselect_b32 s65, s44, s48
	s_add_u32 s46, s46, 0x80080
	s_addc_u32 s47, s47, 0
	s_add_u32 s34, s48, 0x100
	v_mov_b32_e32 v0, 0
	s_addc_u32 s35, s49, 0
	s_mov_b32 s36, -2
	v_mov_b32_e32 v1, v0
	v_mov_b32_e32 v2, v0
	v_mov_b32_e32 v3, v0
	v_mov_b32_e32 v4, v0
	v_mov_b32_e32 v5, v0
	v_mov_b32_e32 v6, v0
	v_mov_b32_e32 v7, v0
	v_mov_b32_e32 v8, v0
	v_mov_b32_e32 v9, v0
	v_mov_b32_e32 v10, v0
	v_mov_b32_e32 v11, v0
	v_mov_b32_e32 v16, v0
	v_mov_b32_e32 v17, v0
	v_mov_b32_e32 v18, v0
	v_mov_b32_e32 v19, v0
	v_mov_b32_e32 v24, v0
	v_mov_b32_e32 v25, v0
	v_mov_b32_e32 v26, v0
	v_mov_b32_e32 v27, v0
	v_mov_b32_e32 v32, v0
	v_mov_b32_e32 v33, v0
	v_mov_b32_e32 v34, v0
	v_mov_b32_e32 v35, v0
	v_mov_b32_e32 v40, v0
	v_mov_b32_e32 v41, v0
	v_mov_b32_e32 v42, v0
	v_mov_b32_e32 v43, v0
	v_mov_b32_e32 v48, v0
	v_mov_b32_e32 v49, v0
	v_mov_b32_e32 v50, v0
	v_mov_b32_e32 v51, v0
	v_mov_b32_e32 v12, v0
	v_mov_b32_e32 v13, v0
	v_mov_b32_e32 v14, v0
	v_mov_b32_e32 v15, v0
	v_mov_b32_e32 v20, v0
	v_mov_b32_e32 v21, v0
	v_mov_b32_e32 v22, v0
	v_mov_b32_e32 v23, v0
	v_mov_b32_e32 v28, v0
	v_mov_b32_e32 v29, v0
	v_mov_b32_e32 v30, v0
	v_mov_b32_e32 v31, v0
	v_mov_b32_e32 v36, v0
	v_mov_b32_e32 v37, v0
	v_mov_b32_e32 v38, v0
	v_mov_b32_e32 v39, v0
	v_mov_b32_e32 v44, v0
	v_mov_b32_e32 v45, v0
	v_mov_b32_e32 v46, v0
	v_mov_b32_e32 v47, v0
	v_mov_b32_e32 v52, v0
	v_mov_b32_e32 v53, v0
	v_mov_b32_e32 v54, v0
	v_mov_b32_e32 v55, v0
	v_mov_b32_e32 v56, v0
	v_mov_b32_e32 v57, v0
	v_mov_b32_e32 v58, v0
	v_mov_b32_e32 v59, v0
	v_mov_b32_e32 v60, v0
	v_mov_b32_e32 v61, v0
	v_mov_b32_e32 v62, v0
	v_mov_b32_e32 v63, v0
	v_mov_b32_e32 v64, v0
	v_mov_b32_e32 v65, v0
	v_mov_b32_e32 v66, v0
	v_mov_b32_e32 v67, v0
	v_mov_b32_e32 v68, v0
	v_mov_b32_e32 v69, v0
	v_mov_b32_e32 v70, v0
	v_mov_b32_e32 v71, v0
	v_mov_b32_e32 v72, v0
	v_mov_b32_e32 v73, v0
	v_mov_b32_e32 v74, v0
	v_mov_b32_e32 v75, v0
	v_mov_b32_e32 v80, v0
	v_mov_b32_e32 v81, v0
	v_mov_b32_e32 v82, v0
	v_mov_b32_e32 v83, v0
	v_mov_b32_e32 v88, v0
	v_mov_b32_e32 v89, v0
	v_mov_b32_e32 v90, v0
	v_mov_b32_e32 v91, v0
	v_mov_b32_e32 v96, v0
	v_mov_b32_e32 v97, v0
	v_mov_b32_e32 v98, v0
	v_mov_b32_e32 v99, v0
	v_mov_b32_e32 v104, v0
	v_mov_b32_e32 v105, v0
	v_mov_b32_e32 v106, v0
	v_mov_b32_e32 v107, v0
	v_mov_b32_e32 v112, v0
	v_mov_b32_e32 v113, v0
	v_mov_b32_e32 v114, v0
	v_mov_b32_e32 v115, v0
	v_mov_b32_e32 v76, v0
	v_mov_b32_e32 v77, v0
	v_mov_b32_e32 v78, v0
	v_mov_b32_e32 v79, v0
	v_mov_b32_e32 v84, v0
	v_mov_b32_e32 v85, v0
	v_mov_b32_e32 v86, v0
	v_mov_b32_e32 v87, v0
	v_mov_b32_e32 v92, v0
	v_mov_b32_e32 v93, v0
	v_mov_b32_e32 v94, v0
	v_mov_b32_e32 v95, v0
	v_mov_b32_e32 v100, v0
	v_mov_b32_e32 v101, v0
	v_mov_b32_e32 v102, v0
	v_mov_b32_e32 v103, v0
	v_mov_b32_e32 v108, v0
	v_mov_b32_e32 v109, v0
	v_mov_b32_e32 v110, v0
	v_mov_b32_e32 v111, v0
	v_mov_b32_e32 v116, v0
	v_mov_b32_e32 v117, v0
	v_mov_b32_e32 v118, v0
	v_mov_b32_e32 v119, v0
	v_mov_b32_e32 v120, v0
	v_mov_b32_e32 v121, v0
	v_mov_b32_e32 v122, v0
	v_mov_b32_e32 v123, v0
	v_mov_b32_e32 v124, v0
	v_mov_b32_e32 v125, v0
	v_mov_b32_e32 v126, v0
	v_mov_b32_e32 v127, v0
	s_cmpk_lt_u32 s97, 0x100
	s_cbranch_scc1 .Lmy_prio_skip1
	s_setprio 1
.Lmy_prio_skip1:
.LBB0_521:
	ds_read_b128 v[152:155], v149
	ds_read_b128 v[156:159], v149 offset:1024
	ds_read_b128 v[160:163], v149 offset:2048
	ds_read_b128 v[164:167], v149 offset:3072
	ds_read_b128 v[168:171], v150
	ds_read_b128 v[172:175], v150 offset:1024
	ds_read_b128 v[176:179], v150 offset:2048
	ds_read_b128 v[180:183], v150 offset:3072
	s_add_u32 s37, s46, 0xfff80080
	s_addc_u32 s38, s47, -1
	s_cmp_eq_u32 s36, 28
	s_cselect_b32 s51, s13, s38
	s_cselect_b32 s50, s64, s37
	s_cselect_b32 s49, s11, s35
	s_cselect_b32 s48, s65, s34
	v_lshl_add_u64 v[144:145], s[46:47], 0, v[136:137]
	s_add_i32 m0, s17, 0xc000
	ds_read_b128 v[184:187], v151
	ds_read_b128 v[188:191], v151 offset:1024
	ds_read_b128 v[192:195], v151 offset:2048
	ds_read_b128 v[196:199], v151 offset:3072
	ds_read_b128 v[200:203], v151 offset:4096
	ds_read_b128 v[204:207], v151 offset:5120
	ds_read_b128 v[208:211], v151 offset:6144
	ds_read_b128 v[212:215], v151 offset:7168
	global_load_lds_dwordx4 v[144:145], off
	v_lshl_add_u64 v[144:145], s[46:47], 0, v[138:139]
	s_add_i32 m0, s17, 0xe000
	s_nop 0
	global_load_lds_dwordx4 v[144:145], off
	s_waitcnt vmcnt(8)
	s_waitcnt lgkmcnt(0)
	s_barrier
	s_waitcnt lgkmcnt(0)
	v_mfma_f32_16x16x32_bf16 v[124:127], v[152:155], v[184:187], v[124:127]
	v_mfma_f32_16x16x32_bf16 v[120:123], v[160:163], v[184:187], v[120:123]
	v_mfma_f32_16x16x32_bf16 v[116:119], v[152:155], v[192:195], v[116:119]
	v_mfma_f32_16x16x32_bf16 v[108:111], v[160:163], v[192:195], v[108:111]
	v_mfma_f32_16x16x32_bf16 v[100:103], v[152:155], v[200:203], v[100:103]
	v_mfma_f32_16x16x32_bf16 v[92:95], v[160:163], v[200:203], v[92:95]
	v_mfma_f32_16x16x32_bf16 v[84:87], v[152:155], v[208:211], v[84:87]
	v_mfma_f32_16x16x32_bf16 v[76:79], v[160:163], v[208:211], v[76:79]
	v_mfma_f32_16x16x32_bf16 v[124:127], v[156:159], v[188:191], v[124:127]
	v_mfma_f32_16x16x32_bf16 v[120:123], v[164:167], v[188:191], v[120:123]
	v_mfma_f32_16x16x32_bf16 v[116:119], v[156:159], v[196:199], v[116:119]
	v_mfma_f32_16x16x32_bf16 v[108:111], v[164:167], v[196:199], v[108:111]
	v_mfma_f32_16x16x32_bf16 v[100:103], v[156:159], v[204:207], v[100:103]
	v_mfma_f32_16x16x32_bf16 v[92:95], v[164:167], v[204:207], v[92:95]
	v_mfma_f32_16x16x32_bf16 v[84:87], v[156:159], v[212:215], v[84:87]
	v_mfma_f32_16x16x32_bf16 v[76:79], v[164:167], v[212:215], v[76:79]
	v_mfma_f32_16x16x32_bf16 v[112:115], v[168:171], v[184:187], v[112:115]
	v_mfma_f32_16x16x32_bf16 v[104:107], v[176:179], v[184:187], v[104:107]
	v_mfma_f32_16x16x32_bf16 v[96:99], v[168:171], v[192:195], v[96:99]
	v_mfma_f32_16x16x32_bf16 v[88:91], v[176:179], v[192:195], v[88:91]
	v_mfma_f32_16x16x32_bf16 v[80:83], v[168:171], v[200:203], v[80:83]
	v_mfma_f32_16x16x32_bf16 v[72:75], v[176:179], v[200:203], v[72:75]
	v_mfma_f32_16x16x32_bf16 v[68:71], v[168:171], v[208:211], v[68:71]
	v_mfma_f32_16x16x32_bf16 v[64:67], v[176:179], v[208:211], v[64:67]
	v_mfma_f32_16x16x32_bf16 v[112:115], v[172:175], v[188:191], v[112:115]
	v_mfma_f32_16x16x32_bf16 v[104:107], v[180:183], v[188:191], v[104:107]
	v_mfma_f32_16x16x32_bf16 v[96:99], v[172:175], v[196:199], v[96:99]
	v_mfma_f32_16x16x32_bf16 v[88:91], v[180:183], v[196:199], v[88:91]
	v_mfma_f32_16x16x32_bf16 v[80:83], v[172:175], v[204:207], v[80:83]
	v_mfma_f32_16x16x32_bf16 v[72:75], v[180:183], v[204:207], v[72:75]
	v_mfma_f32_16x16x32_bf16 v[68:71], v[172:175], v[212:215], v[68:71]
	v_mfma_f32_16x16x32_bf16 v[64:67], v[180:183], v[212:215], v[64:67]
	s_barrier
	s_add_i32 s37, s61, s53
	v_lshl_add_u64 v[144:145], s[48:49], 0, v[130:131]
	s_mov_b32 m0, s37
	ds_read_b128 v[184:187], v151 offset:16384
	ds_read_b128 v[188:191], v151 offset:17408
	ds_read_b128 v[192:195], v151 offset:18432
	ds_read_b128 v[196:199], v151 offset:19456
	ds_read_b128 v[200:203], v151 offset:20480
	ds_read_b128 v[204:207], v151 offset:21504
	ds_read_b128 v[208:211], v151 offset:22528
	ds_read_b128 v[212:215], v151 offset:23552
	global_load_lds_dwordx4 v[144:145], off
	s_add_i32 m0, s37, 0x2000
	s_add_u32 s38, s48, 0x80000
	v_lshl_add_u64 v[216:217], s[48:49], 0, v[134:135]
	s_addc_u32 s39, s49, 0
	s_add_i32 s37, s62, s53
	global_load_lds_dwordx4 v[216:217], off
	v_lshl_add_u64 v[218:219], s[38:39], 0, v[130:131]
	s_mov_b32 m0, s37
	v_lshl_add_u64 v[220:221], s[50:51], 0, v[132:133]
	global_load_lds_dwordx4 v[218:219], off
	v_lshl_add_u64 v[218:219], s[38:39], 0, v[134:135]
	s_add_i32 m0, s37, 0x2000
	s_nop 0
	global_load_lds_dwordx4 v[218:219], off
	v_lshl_add_u64 v[218:219], s[50:51], 0, v[128:129]
	s_mov_b32 m0, s17
	s_nop 0
	global_load_lds_dwordx4 v[218:219], off
	s_mov_b32 m0, s54
	s_nop 0
	global_load_lds_dwordx4 v[220:221], off
	s_waitcnt vmcnt(8)
	s_waitcnt lgkmcnt(0)
	s_barrier
	s_waitcnt lgkmcnt(0)
	v_mfma_f32_16x16x32_bf16 v[60:63], v[152:155], v[184:187], v[60:63]
	v_mfma_f32_16x16x32_bf16 v[56:59], v[160:163], v[184:187], v[56:59]
	v_mfma_f32_16x16x32_bf16 v[52:55], v[152:155], v[192:195], v[52:55]
	v_mfma_f32_16x16x32_bf16 v[44:47], v[160:163], v[192:195], v[44:47]
	v_mfma_f32_16x16x32_bf16 v[36:39], v[152:155], v[200:203], v[36:39]
	v_mfma_f32_16x16x32_bf16 v[28:31], v[160:163], v[200:203], v[28:31]
	v_mfma_f32_16x16x32_bf16 v[20:23], v[152:155], v[208:211], v[20:23]
	v_mfma_f32_16x16x32_bf16 v[12:15], v[160:163], v[208:211], v[12:15]
	v_mfma_f32_16x16x32_bf16 v[60:63], v[156:159], v[188:191], v[60:63]
	v_mfma_f32_16x16x32_bf16 v[56:59], v[164:167], v[188:191], v[56:59]
	v_mfma_f32_16x16x32_bf16 v[52:55], v[156:159], v[196:199], v[52:55]
	v_mfma_f32_16x16x32_bf16 v[44:47], v[164:167], v[196:199], v[44:47]
	v_mfma_f32_16x16x32_bf16 v[36:39], v[156:159], v[204:207], v[36:39]
	v_mfma_f32_16x16x32_bf16 v[28:31], v[164:167], v[204:207], v[28:31]
	v_mfma_f32_16x16x32_bf16 v[20:23], v[156:159], v[212:215], v[20:23]
	v_mfma_f32_16x16x32_bf16 v[12:15], v[164:167], v[212:215], v[12:15]
	v_mfma_f32_16x16x32_bf16 v[48:51], v[168:171], v[184:187], v[48:51]
	v_mfma_f32_16x16x32_bf16 v[40:43], v[176:179], v[184:187], v[40:43]
	v_mfma_f32_16x16x32_bf16 v[32:35], v[168:171], v[192:195], v[32:35]
	v_mfma_f32_16x16x32_bf16 v[24:27], v[176:179], v[192:195], v[24:27]
	v_mfma_f32_16x16x32_bf16 v[16:19], v[168:171], v[200:203], v[16:19]
	v_mfma_f32_16x16x32_bf16 v[8:11], v[176:179], v[200:203], v[8:11]
	v_mfma_f32_16x16x32_bf16 v[4:7], v[168:171], v[208:211], v[4:7]
	v_mfma_f32_16x16x32_bf16 v[0:3], v[176:179], v[208:211], v[0:3]
	v_mfma_f32_16x16x32_bf16 v[48:51], v[172:175], v[188:191], v[48:51]
	v_mfma_f32_16x16x32_bf16 v[40:43], v[180:183], v[188:191], v[40:43]
	v_mfma_f32_16x16x32_bf16 v[32:35], v[172:175], v[196:199], v[32:35]
	v_mfma_f32_16x16x32_bf16 v[24:27], v[180:183], v[196:199], v[24:27]
	v_mfma_f32_16x16x32_bf16 v[16:19], v[172:175], v[204:207], v[16:19]
	v_mfma_f32_16x16x32_bf16 v[8:11], v[180:183], v[204:207], v[8:11]
	v_mfma_f32_16x16x32_bf16 v[4:7], v[172:175], v[212:215], v[4:7]
	v_mfma_f32_16x16x32_bf16 v[0:3], v[180:183], v[212:215], v[0:3]
	s_barrier
	s_add_i32 s37, 0, 0x18000
	s_add_i32 s40, 0, 0x1c000
	v_add_u32_e32 v164, s37, v147
	v_add_u32_e32 v180, s40, v147
	ds_read_b128 v[152:155], v164
	ds_read_b128 v[156:159], v164 offset:1024
	ds_read_b128 v[160:163], v164 offset:2048
	ds_read_b128 v[164:167], v164 offset:3072
	ds_read_b128 v[168:171], v180
	ds_read_b128 v[172:175], v180 offset:1024
	ds_read_b128 v[176:179], v180 offset:2048
	ds_read_b128 v[180:183], v180 offset:3072
	s_add_u32 s38, s50, 0x80000
	s_addc_u32 s39, s51, 0
	s_mov_b32 m0, s55
	v_lshl_add_u64 v[222:223], s[38:39], 0, v[128:129]
	ds_read_b128 v[184:187], v151 offset:32768
	ds_read_b128 v[188:191], v151 offset:33792
	ds_read_b128 v[192:195], v151 offset:34816
	ds_read_b128 v[196:199], v151 offset:35840
	ds_read_b128 v[200:203], v151 offset:36864
	ds_read_b128 v[204:207], v151 offset:37888
	ds_read_b128 v[208:211], v151 offset:38912
	ds_read_b128 v[212:215], v151 offset:39936
	global_load_lds_dwordx4 v[222:223], off
	v_lshl_add_u64 v[222:223], s[38:39], 0, v[132:133]
	s_mov_b32 m0, s56
	s_nop 0
	global_load_lds_dwordx4 v[222:223], off
	s_waitcnt vmcnt(8)
	s_waitcnt lgkmcnt(0)
	s_barrier
	s_waitcnt lgkmcnt(0)
	v_mfma_f32_16x16x32_bf16 v[124:127], v[152:155], v[184:187], v[124:127]
	v_mfma_f32_16x16x32_bf16 v[120:123], v[160:163], v[184:187], v[120:123]
	v_mfma_f32_16x16x32_bf16 v[116:119], v[152:155], v[192:195], v[116:119]
	v_mfma_f32_16x16x32_bf16 v[108:111], v[160:163], v[192:195], v[108:111]
	v_mfma_f32_16x16x32_bf16 v[100:103], v[152:155], v[200:203], v[100:103]
	v_mfma_f32_16x16x32_bf16 v[92:95], v[160:163], v[200:203], v[92:95]
	v_mfma_f32_16x16x32_bf16 v[84:87], v[152:155], v[208:211], v[84:87]
	v_mfma_f32_16x16x32_bf16 v[76:79], v[160:163], v[208:211], v[76:79]
	v_mfma_f32_16x16x32_bf16 v[124:127], v[156:159], v[188:191], v[124:127]
	v_mfma_f32_16x16x32_bf16 v[120:123], v[164:167], v[188:191], v[120:123]
	v_mfma_f32_16x16x32_bf16 v[116:119], v[156:159], v[196:199], v[116:119]
	v_mfma_f32_16x16x32_bf16 v[108:111], v[164:167], v[196:199], v[108:111]
	v_mfma_f32_16x16x32_bf16 v[100:103], v[156:159], v[204:207], v[100:103]
	v_mfma_f32_16x16x32_bf16 v[92:95], v[164:167], v[204:207], v[92:95]
	v_mfma_f32_16x16x32_bf16 v[84:87], v[156:159], v[212:215], v[84:87]
	v_mfma_f32_16x16x32_bf16 v[76:79], v[164:167], v[212:215], v[76:79]
	v_mfma_f32_16x16x32_bf16 v[112:115], v[168:171], v[184:187], v[112:115]
	v_mfma_f32_16x16x32_bf16 v[104:107], v[176:179], v[184:187], v[104:107]
	v_mfma_f32_16x16x32_bf16 v[96:99], v[168:171], v[192:195], v[96:99]
	v_mfma_f32_16x16x32_bf16 v[88:91], v[176:179], v[192:195], v[88:91]
	v_mfma_f32_16x16x32_bf16 v[80:83], v[168:171], v[200:203], v[80:83]
	v_mfma_f32_16x16x32_bf16 v[72:75], v[176:179], v[200:203], v[72:75]
	v_mfma_f32_16x16x32_bf16 v[68:71], v[168:171], v[208:211], v[68:71]
	v_mfma_f32_16x16x32_bf16 v[64:67], v[176:179], v[208:211], v[64:67]
	v_mfma_f32_16x16x32_bf16 v[112:115], v[172:175], v[188:191], v[112:115]
	v_mfma_f32_16x16x32_bf16 v[104:107], v[180:183], v[188:191], v[104:107]
	v_mfma_f32_16x16x32_bf16 v[96:99], v[172:175], v[196:199], v[96:99]
	v_mfma_f32_16x16x32_bf16 v[88:91], v[180:183], v[196:199], v[88:91]
	v_mfma_f32_16x16x32_bf16 v[80:83], v[172:175], v[204:207], v[80:83]
	v_mfma_f32_16x16x32_bf16 v[72:75], v[180:183], v[204:207], v[72:75]
	v_mfma_f32_16x16x32_bf16 v[68:71], v[172:175], v[212:215], v[68:71]
	v_mfma_f32_16x16x32_bf16 v[64:67], v[180:183], v[212:215], v[64:67]
	s_barrier
	s_add_i32 s37, s37, s53
	v_lshl_add_u64 v[144:145], v[144:145], 0, s[6:7]
	s_mov_b32 m0, s37
	ds_read_b128 v[184:187], v151 offset:49152
	ds_read_b128 v[188:191], v151 offset:50176
	ds_read_b128 v[192:195], v151 offset:51200
	ds_read_b128 v[196:199], v151 offset:52224
	ds_read_b128 v[200:203], v151 offset:53248
	ds_read_b128 v[204:207], v151 offset:54272
	ds_read_b128 v[208:211], v151 offset:55296
	ds_read_b128 v[212:215], v151 offset:56320
	global_load_lds_dwordx4 v[144:145], off
	s_add_i32 m0, s37, 0x2000
	s_add_u32 s38, s48, 0x80080
	v_lshl_add_u64 v[144:145], v[216:217], 0, s[6:7]
	s_addc_u32 s39, s49, 0
	s_add_i32 s37, s40, s53
	global_load_lds_dwordx4 v[144:145], off
	v_lshl_add_u64 v[144:145], s[38:39], 0, v[130:131]
	s_mov_b32 m0, s37
	s_nop 0
	global_load_lds_dwordx4 v[144:145], off
	v_lshl_add_u64 v[144:145], s[38:39], 0, v[134:135]
	s_add_i32 m0, s37, 0x2000
	s_nop 0
	global_load_lds_dwordx4 v[144:145], off
	v_lshl_add_u64 v[144:145], v[218:219], 0, s[6:7]
	s_mov_b32 m0, s58
	s_nop 0
	global_load_lds_dwordx4 v[144:145], off
	v_lshl_add_u64 v[144:145], v[220:221], 0, s[6:7]
	s_mov_b32 m0, s59
	s_nop 0
	global_load_lds_dwordx4 v[144:145], off
	s_waitcnt vmcnt(8)
	s_waitcnt lgkmcnt(0)
	s_barrier
	s_waitcnt lgkmcnt(0)
	v_mfma_f32_16x16x32_bf16 v[60:63], v[152:155], v[184:187], v[60:63]
	v_mfma_f32_16x16x32_bf16 v[56:59], v[160:163], v[184:187], v[56:59]
	v_mfma_f32_16x16x32_bf16 v[52:55], v[152:155], v[192:195], v[52:55]
	v_mfma_f32_16x16x32_bf16 v[44:47], v[160:163], v[192:195], v[44:47]
	v_mfma_f32_16x16x32_bf16 v[36:39], v[152:155], v[200:203], v[36:39]
	v_mfma_f32_16x16x32_bf16 v[28:31], v[160:163], v[200:203], v[28:31]
	v_mfma_f32_16x16x32_bf16 v[20:23], v[152:155], v[208:211], v[20:23]
	v_mfma_f32_16x16x32_bf16 v[12:15], v[160:163], v[208:211], v[12:15]
	v_mfma_f32_16x16x32_bf16 v[60:63], v[156:159], v[188:191], v[60:63]
	v_mfma_f32_16x16x32_bf16 v[56:59], v[164:167], v[188:191], v[56:59]
	v_mfma_f32_16x16x32_bf16 v[52:55], v[156:159], v[196:199], v[52:55]
	v_mfma_f32_16x16x32_bf16 v[44:47], v[164:167], v[196:199], v[44:47]
	v_mfma_f32_16x16x32_bf16 v[36:39], v[156:159], v[204:207], v[36:39]
	v_mfma_f32_16x16x32_bf16 v[28:31], v[164:167], v[204:207], v[28:31]
	v_mfma_f32_16x16x32_bf16 v[20:23], v[156:159], v[212:215], v[20:23]
	v_mfma_f32_16x16x32_bf16 v[12:15], v[164:167], v[212:215], v[12:15]
	v_mfma_f32_16x16x32_bf16 v[48:51], v[168:171], v[184:187], v[48:51]
	v_mfma_f32_16x16x32_bf16 v[40:43], v[176:179], v[184:187], v[40:43]
	v_mfma_f32_16x16x32_bf16 v[32:35], v[168:171], v[192:195], v[32:35]
	v_mfma_f32_16x16x32_bf16 v[24:27], v[176:179], v[192:195], v[24:27]
	v_mfma_f32_16x16x32_bf16 v[16:19], v[168:171], v[200:203], v[16:19]
	v_mfma_f32_16x16x32_bf16 v[8:11], v[176:179], v[200:203], v[8:11]
	v_mfma_f32_16x16x32_bf16 v[4:7], v[168:171], v[208:211], v[4:7]
	v_mfma_f32_16x16x32_bf16 v[0:3], v[176:179], v[208:211], v[0:3]
	v_mfma_f32_16x16x32_bf16 v[48:51], v[172:175], v[188:191], v[48:51]
	v_mfma_f32_16x16x32_bf16 v[40:43], v[180:183], v[188:191], v[40:43]
	v_mfma_f32_16x16x32_bf16 v[32:35], v[172:175], v[196:199], v[32:35]
	v_mfma_f32_16x16x32_bf16 v[24:27], v[180:183], v[196:199], v[24:27]
	v_mfma_f32_16x16x32_bf16 v[16:19], v[172:175], v[204:207], v[16:19]
	v_mfma_f32_16x16x32_bf16 v[8:11], v[180:183], v[204:207], v[8:11]
	v_mfma_f32_16x16x32_bf16 v[4:7], v[172:175], v[212:215], v[4:7]
	v_mfma_f32_16x16x32_bf16 v[0:3], v[180:183], v[212:215], v[0:3]
	s_barrier
	s_add_i32 s36, s36, 2
	s_add_u32 s46, s46, 0x100
	s_addc_u32 s47, s47, 0
	s_add_u32 s34, s34, 0x100
	s_addc_u32 s35, s35, 0
	s_cmp_gt_u32 s36, 29
	s_cbranch_scc0 .LBB0_521
	s_setprio 0
	s_and_b64 vcc, exec, s[8:9]
	s_cbranch_vccz .LBB0_524
	s_barrier

.LBB0_599:
	s_ashr_i32 s17, s16, 31
	s_lshl_b64 s[34:35], s[16:17], 21
	s_add_u32 s44, s33, s34
	s_addc_u32 s45, s54, s35
	s_and_b64 s[34:35], s[0:1], exec
	s_cselect_b32 s17, s45, s49
	s_cselect_b32 s66, s44, s48
	s_ashr_i32 s13, s12, 31
	s_lshl_b64 s[34:35], s[12:13], 21
	s_add_u32 s46, s92, s34
	v_readlane_b32 s13, v254, 42
	s_addc_u32 s47, s13, s35
	s_and_b64 s[34:35], s[0:1], exec
	s_cselect_b32 s13, s47, s51
	s_cselect_b32 s67, s46, s50
	s_add_u32 s48, s48, 0x100080
	s_addc_u32 s49, s49, 0
	s_add_u32 s34, s50, 0x100
	v_mov_b32_e32 v0, 0
	s_addc_u32 s35, s51, 0
	s_mov_b32 s36, -2
	v_mov_b32_e32 v1, v0
	v_mov_b32_e32 v2, v0
	v_mov_b32_e32 v3, v0
	v_mov_b32_e32 v4, v0
	v_mov_b32_e32 v5, v0
	v_mov_b32_e32 v6, v0
	v_mov_b32_e32 v7, v0
	v_mov_b32_e32 v8, v0
	v_mov_b32_e32 v9, v0
	v_mov_b32_e32 v10, v0
	v_mov_b32_e32 v11, v0
	v_mov_b32_e32 v16, v0
	v_mov_b32_e32 v17, v0
	v_mov_b32_e32 v18, v0
	v_mov_b32_e32 v19, v0
	v_mov_b32_e32 v24, v0
	v_mov_b32_e32 v25, v0
	v_mov_b32_e32 v26, v0
	v_mov_b32_e32 v27, v0
	v_mov_b32_e32 v32, v0
	v_mov_b32_e32 v33, v0
	v_mov_b32_e32 v34, v0
	v_mov_b32_e32 v35, v0
	v_mov_b32_e32 v40, v0
	v_mov_b32_e32 v41, v0
	v_mov_b32_e32 v42, v0
	v_mov_b32_e32 v43, v0
	v_mov_b32_e32 v48, v0
	v_mov_b32_e32 v49, v0
	v_mov_b32_e32 v50, v0
	v_mov_b32_e32 v51, v0
	v_mov_b32_e32 v12, v0
	v_mov_b32_e32 v13, v0
	v_mov_b32_e32 v14, v0
	v_mov_b32_e32 v15, v0
	v_mov_b32_e32 v20, v0
	v_mov_b32_e32 v21, v0
	v_mov_b32_e32 v22, v0
	v_mov_b32_e32 v23, v0
	v_mov_b32_e32 v28, v0
	v_mov_b32_e32 v29, v0
	v_mov_b32_e32 v30, v0
	v_mov_b32_e32 v31, v0
	v_mov_b32_e32 v36, v0
	v_mov_b32_e32 v37, v0
	v_mov_b32_e32 v38, v0
	v_mov_b32_e32 v39, v0
	v_mov_b32_e32 v44, v0
	v_mov_b32_e32 v45, v0
	v_mov_b32_e32 v46, v0
	v_mov_b32_e32 v47, v0
	v_mov_b32_e32 v52, v0
	v_mov_b32_e32 v53, v0
	v_mov_b32_e32 v54, v0
	v_mov_b32_e32 v55, v0
	v_mov_b32_e32 v56, v0
	v_mov_b32_e32 v57, v0
	v_mov_b32_e32 v58, v0
	v_mov_b32_e32 v59, v0
	v_mov_b32_e32 v60, v0
	v_mov_b32_e32 v61, v0
	v_mov_b32_e32 v62, v0
	v_mov_b32_e32 v63, v0
	v_mov_b32_e32 v64, v0
	v_mov_b32_e32 v65, v0
	v_mov_b32_e32 v66, v0
	v_mov_b32_e32 v67, v0
	v_mov_b32_e32 v68, v0
	v_mov_b32_e32 v69, v0
	v_mov_b32_e32 v70, v0
	v_mov_b32_e32 v71, v0
	v_mov_b32_e32 v72, v0
	v_mov_b32_e32 v73, v0
	v_mov_b32_e32 v74, v0
	v_mov_b32_e32 v75, v0
	v_mov_b32_e32 v80, v0
	v_mov_b32_e32 v81, v0
	v_mov_b32_e32 v82, v0
	v_mov_b32_e32 v83, v0
	v_mov_b32_e32 v88, v0
	v_mov_b32_e32 v89, v0
	v_mov_b32_e32 v90, v0
	v_mov_b32_e32 v91, v0
	v_mov_b32_e32 v96, v0
	v_mov_b32_e32 v97, v0
	v_mov_b32_e32 v98, v0
	v_mov_b32_e32 v99, v0
	v_mov_b32_e32 v104, v0
	v_mov_b32_e32 v105, v0
	v_mov_b32_e32 v106, v0
	v_mov_b32_e32 v107, v0
	v_mov_b32_e32 v112, v0
	v_mov_b32_e32 v113, v0
	v_mov_b32_e32 v114, v0
	v_mov_b32_e32 v115, v0
	v_mov_b32_e32 v76, v0
	v_mov_b32_e32 v77, v0
	v_mov_b32_e32 v78, v0
	v_mov_b32_e32 v79, v0
	v_mov_b32_e32 v84, v0
	v_mov_b32_e32 v85, v0
	v_mov_b32_e32 v86, v0
	v_mov_b32_e32 v87, v0
	v_mov_b32_e32 v92, v0
	v_mov_b32_e32 v93, v0
	v_mov_b32_e32 v94, v0
	v_mov_b32_e32 v95, v0
	v_mov_b32_e32 v100, v0
	v_mov_b32_e32 v101, v0
	v_mov_b32_e32 v102, v0
	v_mov_b32_e32 v103, v0
	v_mov_b32_e32 v108, v0
	v_mov_b32_e32 v109, v0
	v_mov_b32_e32 v110, v0
	v_mov_b32_e32 v111, v0
	v_mov_b32_e32 v116, v0
	v_mov_b32_e32 v117, v0
	v_mov_b32_e32 v118, v0
	v_mov_b32_e32 v119, v0
	v_mov_b32_e32 v120, v0
	v_mov_b32_e32 v121, v0
	v_mov_b32_e32 v122, v0
	v_mov_b32_e32 v123, v0
	v_mov_b32_e32 v124, v0
	v_mov_b32_e32 v125, v0
	v_mov_b32_e32 v126, v0
	v_mov_b32_e32 v127, v0
	s_cmpk_lt_u32 s97, 0x100
	s_cbranch_scc1 .Lmy_prio_skip2
	s_setprio 1
.Lmy_prio_skip2:
.LBB0_600:
	ds_read_b128 v[152:155], v149
	ds_read_b128 v[156:159], v149 offset:1024
	ds_read_b128 v[160:163], v149 offset:2048
	ds_read_b128 v[164:167], v149 offset:3072
	ds_read_b128 v[168:171], v150
	ds_read_b128 v[172:175], v150 offset:1024
	ds_read_b128 v[176:179], v150 offset:2048
	ds_read_b128 v[180:183], v150 offset:3072
	s_add_u32 s37, s48, 0xfff00080
	s_addc_u32 s38, s49, -1
	s_cmp_eq_u32 s36, 60
	s_cselect_b32 s53, s17, s38
	s_cselect_b32 s52, s66, s37
	s_cselect_b32 s51, s13, s35
	s_cselect_b32 s50, s67, s34
	v_lshl_add_u64 v[144:145], s[48:49], 0, v[136:137]
	s_add_i32 m0, s19, 0xc000
	ds_read_b128 v[184:187], v151
	ds_read_b128 v[188:191], v151 offset:1024
	ds_read_b128 v[192:195], v151 offset:2048
	ds_read_b128 v[196:199], v151 offset:3072
	ds_read_b128 v[200:203], v151 offset:4096
	ds_read_b128 v[204:207], v151 offset:5120
	ds_read_b128 v[208:211], v151 offset:6144
	ds_read_b128 v[212:215], v151 offset:7168
	global_load_lds_dwordx4 v[144:145], off
	v_lshl_add_u64 v[144:145], s[48:49], 0, v[138:139]
	s_add_i32 m0, s19, 0xe000
	s_nop 0
	global_load_lds_dwordx4 v[144:145], off
	s_waitcnt vmcnt(8)
	s_waitcnt lgkmcnt(0)
	s_barrier
	s_waitcnt lgkmcnt(0)
	v_mfma_f32_16x16x32_bf16 v[124:127], v[152:155], v[184:187], v[124:127]
	v_mfma_f32_16x16x32_bf16 v[120:123], v[160:163], v[184:187], v[120:123]
	v_mfma_f32_16x16x32_bf16 v[116:119], v[152:155], v[192:195], v[116:119]
	v_mfma_f32_16x16x32_bf16 v[108:111], v[160:163], v[192:195], v[108:111]
	v_mfma_f32_16x16x32_bf16 v[100:103], v[152:155], v[200:203], v[100:103]
	v_mfma_f32_16x16x32_bf16 v[92:95], v[160:163], v[200:203], v[92:95]
	v_mfma_f32_16x16x32_bf16 v[84:87], v[152:155], v[208:211], v[84:87]
	v_mfma_f32_16x16x32_bf16 v[76:79], v[160:163], v[208:211], v[76:79]
	v_mfma_f32_16x16x32_bf16 v[124:127], v[156:159], v[188:191], v[124:127]
	v_mfma_f32_16x16x32_bf16 v[120:123], v[164:167], v[188:191], v[120:123]
	v_mfma_f32_16x16x32_bf16 v[116:119], v[156:159], v[196:199], v[116:119]
	v_mfma_f32_16x16x32_bf16 v[108:111], v[164:167], v[196:199], v[108:111]
	v_mfma_f32_16x16x32_bf16 v[100:103], v[156:159], v[204:207], v[100:103]
	v_mfma_f32_16x16x32_bf16 v[92:95], v[164:167], v[204:207], v[92:95]
	v_mfma_f32_16x16x32_bf16 v[84:87], v[156:159], v[212:215], v[84:87]
	v_mfma_f32_16x16x32_bf16 v[76:79], v[164:167], v[212:215], v[76:79]
	v_mfma_f32_16x16x32_bf16 v[112:115], v[168:171], v[184:187], v[112:115]
	v_mfma_f32_16x16x32_bf16 v[104:107], v[176:179], v[184:187], v[104:107]
	v_mfma_f32_16x16x32_bf16 v[96:99], v[168:171], v[192:195], v[96:99]
	v_mfma_f32_16x16x32_bf16 v[88:91], v[176:179], v[192:195], v[88:91]
	v_mfma_f32_16x16x32_bf16 v[80:83], v[168:171], v[200:203], v[80:83]
	v_mfma_f32_16x16x32_bf16 v[72:75], v[176:179], v[200:203], v[72:75]
	v_mfma_f32_16x16x32_bf16 v[68:71], v[168:171], v[208:211], v[68:71]
	v_mfma_f32_16x16x32_bf16 v[64:67], v[176:179], v[208:211], v[64:67]
	v_mfma_f32_16x16x32_bf16 v[112:115], v[172:175], v[188:191], v[112:115]
	v_mfma_f32_16x16x32_bf16 v[104:107], v[180:183], v[188:191], v[104:107]
	v_mfma_f32_16x16x32_bf16 v[96:99], v[172:175], v[196:199], v[96:99]
	v_mfma_f32_16x16x32_bf16 v[88:91], v[180:183], v[196:199], v[88:91]
	v_mfma_f32_16x16x32_bf16 v[80:83], v[172:175], v[204:207], v[80:83]
	v_mfma_f32_16x16x32_bf16 v[72:75], v[180:183], v[204:207], v[72:75]
	v_mfma_f32_16x16x32_bf16 v[68:71], v[172:175], v[212:215], v[68:71]
	v_mfma_f32_16x16x32_bf16 v[64:67], v[180:183], v[212:215], v[64:67]
	s_barrier
	s_add_i32 s37, s63, s55
	v_lshl_add_u64 v[144:145], s[50:51], 0, v[130:131]
	s_mov_b32 m0, s37
	ds_read_b128 v[184:187], v151 offset:16384
	ds_read_b128 v[188:191], v151 offset:17408
	ds_read_b128 v[192:195], v151 offset:18432
	ds_read_b128 v[196:199], v151 offset:19456
	ds_read_b128 v[200:203], v151 offset:20480
	ds_read_b128 v[204:207], v151 offset:21504
	ds_read_b128 v[208:211], v151 offset:22528
	ds_read_b128 v[212:215], v151 offset:23552
	global_load_lds_dwordx4 v[144:145], off
	s_add_i32 m0, s37, 0x2000
	s_add_u32 s38, s50, 0x100000
	v_lshl_add_u64 v[216:217], s[50:51], 0, v[134:135]
	s_addc_u32 s39, s51, 0
	s_add_i32 s37, s64, s55
	global_load_lds_dwordx4 v[216:217], off
	v_lshl_add_u64 v[218:219], s[38:39], 0, v[130:131]
	s_mov_b32 m0, s37
	v_lshl_add_u64 v[220:221], s[52:53], 0, v[132:133]
	global_load_lds_dwordx4 v[218:219], off
	v_lshl_add_u64 v[218:219], s[38:39], 0, v[134:135]
	s_add_i32 m0, s37, 0x2000
	s_nop 0
	global_load_lds_dwordx4 v[218:219], off
	v_lshl_add_u64 v[218:219], s[52:53], 0, v[128:129]
	s_mov_b32 m0, s19
	s_nop 0
	global_load_lds_dwordx4 v[218:219], off
	s_mov_b32 m0, s56
	s_nop 0
	global_load_lds_dwordx4 v[220:221], off
	s_waitcnt vmcnt(8)
	s_waitcnt lgkmcnt(0)
	s_barrier
	s_waitcnt lgkmcnt(0)
	v_mfma_f32_16x16x32_bf16 v[60:63], v[152:155], v[184:187], v[60:63]
	v_mfma_f32_16x16x32_bf16 v[56:59], v[160:163], v[184:187], v[56:59]
	v_mfma_f32_16x16x32_bf16 v[52:55], v[152:155], v[192:195], v[52:55]
	v_mfma_f32_16x16x32_bf16 v[44:47], v[160:163], v[192:195], v[44:47]
	v_mfma_f32_16x16x32_bf16 v[36:39], v[152:155], v[200:203], v[36:39]
	v_mfma_f32_16x16x32_bf16 v[28:31], v[160:163], v[200:203], v[28:31]
	v_mfma_f32_16x16x32_bf16 v[20:23], v[152:155], v[208:211], v[20:23]
	v_mfma_f32_16x16x32_bf16 v[12:15], v[160:163], v[208:211], v[12:15]
	v_mfma_f32_16x16x32_bf16 v[60:63], v[156:159], v[188:191], v[60:63]
	v_mfma_f32_16x16x32_bf16 v[56:59], v[164:167], v[188:191], v[56:59]
	v_mfma_f32_16x16x32_bf16 v[52:55], v[156:159], v[196:199], v[52:55]
	v_mfma_f32_16x16x32_bf16 v[44:47], v[164:167], v[196:199], v[44:47]
	v_mfma_f32_16x16x32_bf16 v[36:39], v[156:159], v[204:207], v[36:39]
	v_mfma_f32_16x16x32_bf16 v[28:31], v[164:167], v[204:207], v[28:31]
	v_mfma_f32_16x16x32_bf16 v[20:23], v[156:159], v[212:215], v[20:23]
	v_mfma_f32_16x16x32_bf16 v[12:15], v[164:167], v[212:215], v[12:15]
	v_mfma_f32_16x16x32_bf16 v[48:51], v[168:171], v[184:187], v[48:51]
	v_mfma_f32_16x16x32_bf16 v[40:43], v[176:179], v[184:187], v[40:43]
	v_mfma_f32_16x16x32_bf16 v[32:35], v[168:171], v[192:195], v[32:35]
	v_mfma_f32_16x16x32_bf16 v[24:27], v[176:179], v[192:195], v[24:27]
	v_mfma_f32_16x16x32_bf16 v[16:19], v[168:171], v[200:203], v[16:19]
	v_mfma_f32_16x16x32_bf16 v[8:11], v[176:179], v[200:203], v[8:11]
	v_mfma_f32_16x16x32_bf16 v[4:7], v[168:171], v[208:211], v[4:7]
	v_mfma_f32_16x16x32_bf16 v[0:3], v[176:179], v[208:211], v[0:3]
	v_mfma_f32_16x16x32_bf16 v[48:51], v[172:175], v[188:191], v[48:51]
	v_mfma_f32_16x16x32_bf16 v[40:43], v[180:183], v[188:191], v[40:43]
	v_mfma_f32_16x16x32_bf16 v[32:35], v[172:175], v[196:199], v[32:35]
	v_mfma_f32_16x16x32_bf16 v[24:27], v[180:183], v[196:199], v[24:27]
	v_mfma_f32_16x16x32_bf16 v[16:19], v[172:175], v[204:207], v[16:19]
	v_mfma_f32_16x16x32_bf16 v[8:11], v[180:183], v[204:207], v[8:11]
	v_mfma_f32_16x16x32_bf16 v[4:7], v[172:175], v[212:215], v[4:7]
	v_mfma_f32_16x16x32_bf16 v[0:3], v[180:183], v[212:215], v[0:3]
	s_barrier
	s_add_i32 s37, 0, 0x18000
	s_add_i32 s40, 0, 0x1c000
	v_add_u32_e32 v164, s37, v147
	v_add_u32_e32 v180, s40, v147
	ds_read_b128 v[152:155], v164
	ds_read_b128 v[156:159], v164 offset:1024
	ds_read_b128 v[160:163], v164 offset:2048
	ds_read_b128 v[164:167], v164 offset:3072
	ds_read_b128 v[168:171], v180
	ds_read_b128 v[172:175], v180 offset:1024
	ds_read_b128 v[176:179], v180 offset:2048
	ds_read_b128 v[180:183], v180 offset:3072
	s_add_u32 s38, s52, 0x100000
	s_addc_u32 s39, s53, 0
	s_mov_b32 m0, s57
	v_lshl_add_u64 v[222:223], s[38:39], 0, v[128:129]
	ds_read_b128 v[184:187], v151 offset:32768
	ds_read_b128 v[188:191], v151 offset:33792
	ds_read_b128 v[192:195], v151 offset:34816
	ds_read_b128 v[196:199], v151 offset:35840
	ds_read_b128 v[200:203], v151 offset:36864
	ds_read_b128 v[204:207], v151 offset:37888
	ds_read_b128 v[208:211], v151 offset:38912
	ds_read_b128 v[212:215], v151 offset:39936
	global_load_lds_dwordx4 v[222:223], off
	v_lshl_add_u64 v[222:223], s[38:39], 0, v[132:133]
	s_mov_b32 m0, s58
	s_nop 0
	global_load_lds_dwordx4 v[222:223], off
	s_waitcnt vmcnt(8)
	s_waitcnt lgkmcnt(0)
	s_barrier
	s_waitcnt lgkmcnt(0)
	v_mfma_f32_16x16x32_bf16 v[124:127], v[152:155], v[184:187], v[124:127]
	v_mfma_f32_16x16x32_bf16 v[120:123], v[160:163], v[184:187], v[120:123]
	v_mfma_f32_16x16x32_bf16 v[116:119], v[152:155], v[192:195], v[116:119]
	v_mfma_f32_16x16x32_bf16 v[108:111], v[160:163], v[192:195], v[108:111]
	v_mfma_f32_16x16x32_bf16 v[100:103], v[152:155], v[200:203], v[100:103]
	v_mfma_f32_16x16x32_bf16 v[92:95], v[160:163], v[200:203], v[92:95]
	v_mfma_f32_16x16x32_bf16 v[84:87], v[152:155], v[208:211], v[84:87]
	v_mfma_f32_16x16x32_bf16 v[76:79], v[160:163], v[208:211], v[76:79]
	v_mfma_f32_16x16x32_bf16 v[124:127], v[156:159], v[188:191], v[124:127]
	v_mfma_f32_16x16x32_bf16 v[120:123], v[164:167], v[188:191], v[120:123]
	v_mfma_f32_16x16x32_bf16 v[116:119], v[156:159], v[196:199], v[116:119]
	v_mfma_f32_16x16x32_bf16 v[108:111], v[164:167], v[196:199], v[108:111]
	v_mfma_f32_16x16x32_bf16 v[100:103], v[156:159], v[204:207], v[100:103]
	v_mfma_f32_16x16x32_bf16 v[92:95], v[164:167], v[204:207], v[92:95]
	v_mfma_f32_16x16x32_bf16 v[84:87], v[156:159], v[212:215], v[84:87]
	v_mfma_f32_16x16x32_bf16 v[76:79], v[164:167], v[212:215], v[76:79]
	v_mfma_f32_16x16x32_bf16 v[112:115], v[168:171], v[184:187], v[112:115]
	v_mfma_f32_16x16x32_bf16 v[104:107], v[176:179], v[184:187], v[104:107]
	v_mfma_f32_16x16x32_bf16 v[96:99], v[168:171], v[192:195], v[96:99]
	v_mfma_f32_16x16x32_bf16 v[88:91], v[176:179], v[192:195], v[88:91]
	v_mfma_f32_16x16x32_bf16 v[80:83], v[168:171], v[200:203], v[80:83]
	v_mfma_f32_16x16x32_bf16 v[72:75], v[176:179], v[200:203], v[72:75]
	v_mfma_f32_16x16x32_bf16 v[68:71], v[168:171], v[208:211], v[68:71]
	v_mfma_f32_16x16x32_bf16 v[64:67], v[176:179], v[208:211], v[64:67]
	v_mfma_f32_16x16x32_bf16 v[112:115], v[172:175], v[188:191], v[112:115]
	v_mfma_f32_16x16x32_bf16 v[104:107], v[180:183], v[188:191], v[104:107]
	v_mfma_f32_16x16x32_bf16 v[96:99], v[172:175], v[196:199], v[96:99]
	v_mfma_f32_16x16x32_bf16 v[88:91], v[180:183], v[196:199], v[88:91]
	v_mfma_f32_16x16x32_bf16 v[80:83], v[172:175], v[204:207], v[80:83]
	v_mfma_f32_16x16x32_bf16 v[72:75], v[180:183], v[204:207], v[72:75]
	v_mfma_f32_16x16x32_bf16 v[68:71], v[172:175], v[212:215], v[68:71]
	v_mfma_f32_16x16x32_bf16 v[64:67], v[180:183], v[212:215], v[64:67]
	s_barrier
	s_add_i32 s37, s37, s55
	v_lshl_add_u64 v[144:145], v[144:145], 0, s[8:9]
	s_mov_b32 m0, s37
	ds_read_b128 v[184:187], v151 offset:49152
	ds_read_b128 v[188:191], v151 offset:50176
	ds_read_b128 v[192:195], v151 offset:51200
	ds_read_b128 v[196:199], v151 offset:52224
	ds_read_b128 v[200:203], v151 offset:53248
	ds_read_b128 v[204:207], v151 offset:54272
	ds_read_b128 v[208:211], v151 offset:55296
	ds_read_b128 v[212:215], v151 offset:56320
	global_load_lds_dwordx4 v[144:145], off
	s_add_i32 m0, s37, 0x2000
	s_add_u32 s38, s50, 0x100080
	v_lshl_add_u64 v[144:145], v[216:217], 0, s[8:9]
	s_addc_u32 s39, s51, 0
	s_add_i32 s37, s40, s55
	global_load_lds_dwordx4 v[144:145], off
	v_lshl_add_u64 v[144:145], s[38:39], 0, v[130:131]
	s_mov_b32 m0, s37
	s_nop 0
	global_load_lds_dwordx4 v[144:145], off
	v_lshl_add_u64 v[144:145], s[38:39], 0, v[134:135]
	s_add_i32 m0, s37, 0x2000
	s_nop 0
	global_load_lds_dwordx4 v[144:145], off
	v_lshl_add_u64 v[144:145], v[218:219], 0, s[8:9]
	s_mov_b32 m0, s60
	s_nop 0
	global_load_lds_dwordx4 v[144:145], off
	v_lshl_add_u64 v[144:145], v[220:221], 0, s[8:9]
	s_mov_b32 m0, s61
	s_nop 0
	global_load_lds_dwordx4 v[144:145], off
	s_waitcnt vmcnt(8)
	s_waitcnt lgkmcnt(0)
	s_barrier
	s_waitcnt lgkmcnt(0)
	v_mfma_f32_16x16x32_bf16 v[60:63], v[152:155], v[184:187], v[60:63]
	v_mfma_f32_16x16x32_bf16 v[56:59], v[160:163], v[184:187], v[56:59]
	v_mfma_f32_16x16x32_bf16 v[52:55], v[152:155], v[192:195], v[52:55]
	v_mfma_f32_16x16x32_bf16 v[44:47], v[160:163], v[192:195], v[44:47]
	v_mfma_f32_16x16x32_bf16 v[36:39], v[152:155], v[200:203], v[36:39]
	v_mfma_f32_16x16x32_bf16 v[28:31], v[160:163], v[200:203], v[28:31]
	v_mfma_f32_16x16x32_bf16 v[20:23], v[152:155], v[208:211], v[20:23]
	v_mfma_f32_16x16x32_bf16 v[12:15], v[160:163], v[208:211], v[12:15]
	v_mfma_f32_16x16x32_bf16 v[60:63], v[156:159], v[188:191], v[60:63]
	v_mfma_f32_16x16x32_bf16 v[56:59], v[164:167], v[188:191], v[56:59]
	v_mfma_f32_16x16x32_bf16 v[52:55], v[156:159], v[196:199], v[52:55]
	v_mfma_f32_16x16x32_bf16 v[44:47], v[164:167], v[196:199], v[44:47]
	v_mfma_f32_16x16x32_bf16 v[36:39], v[156:159], v[204:207], v[36:39]
	v_mfma_f32_16x16x32_bf16 v[28:31], v[164:167], v[204:207], v[28:31]
	v_mfma_f32_16x16x32_bf16 v[20:23], v[156:159], v[212:215], v[20:23]
	v_mfma_f32_16x16x32_bf16 v[12:15], v[164:167], v[212:215], v[12:15]
	v_mfma_f32_16x16x32_bf16 v[48:51], v[168:171], v[184:187], v[48:51]
	v_mfma_f32_16x16x32_bf16 v[40:43], v[176:179], v[184:187], v[40:43]
	v_mfma_f32_16x16x32_bf16 v[32:35], v[168:171], v[192:195], v[32:35]
	v_mfma_f32_16x16x32_bf16 v[24:27], v[176:179], v[192:195], v[24:27]
	v_mfma_f32_16x16x32_bf16 v[16:19], v[168:171], v[200:203], v[16:19]
	v_mfma_f32_16x16x32_bf16 v[8:11], v[176:179], v[200:203], v[8:11]
	v_mfma_f32_16x16x32_bf16 v[4:7], v[168:171], v[208:211], v[4:7]
	v_mfma_f32_16x16x32_bf16 v[0:3], v[176:179], v[208:211], v[0:3]
	v_mfma_f32_16x16x32_bf16 v[48:51], v[172:175], v[188:191], v[48:51]
	v_mfma_f32_16x16x32_bf16 v[40:43], v[180:183], v[188:191], v[40:43]
	v_mfma_f32_16x16x32_bf16 v[32:35], v[172:175], v[196:199], v[32:35]
	v_mfma_f32_16x16x32_bf16 v[24:27], v[180:183], v[196:199], v[24:27]
	v_mfma_f32_16x16x32_bf16 v[16:19], v[172:175], v[204:207], v[16:19]
	v_mfma_f32_16x16x32_bf16 v[8:11], v[180:183], v[204:207], v[8:11]
	v_mfma_f32_16x16x32_bf16 v[4:7], v[172:175], v[212:215], v[4:7]
	v_mfma_f32_16x16x32_bf16 v[0:3], v[180:183], v[212:215], v[0:3]
	s_barrier
	s_add_i32 s36, s36, 2
	s_add_u32 s48, s48, 0x100
	s_addc_u32 s49, s49, 0
	s_add_u32 s34, s34, 0x100
	s_addc_u32 s35, s35, 0
	s_cmp_gt_u32 s36, 61
	s_cbranch_scc0 .LBB0_600
	s_setprio 0
	s_and_b64 vcc, exec, s[10:11]
	s_cbranch_vccz .LBB0_603
	s_barrier

.LBB0_678:
	s_ashr_i32 s19, s18, 31
	s_lshl_b64 s[34:35], s[18:19], 21
	s_add_u32 s44, s86, s34
	s_addc_u32 s45, s87, s35
	s_and_b64 s[34:35], s[0:1], exec
	s_cselect_b32 s19, s45, s51
	s_cselect_b32 s66, s44, s50
	s_ashr_i32 s17, s16, 31
	s_lshl_b64 s[34:35], s[16:17], 21
	s_add_u32 s46, s88, s34
	s_addc_u32 s47, s90, s35
	s_and_b64 s[34:35], s[0:1], exec
	s_cselect_b32 s17, s47, s53
	s_cselect_b32 s67, s46, s52
	s_add_u32 s50, s50, 0x100080
	s_addc_u32 s51, s51, 0
	s_add_u32 s34, s52, 0x100
	v_mov_b32_e32 v0, 0
	s_addc_u32 s35, s53, 0
	s_mov_b32 s36, -2
	v_mov_b32_e32 v1, v0
	v_mov_b32_e32 v2, v0
	v_mov_b32_e32 v3, v0
	v_mov_b32_e32 v4, v0
	v_mov_b32_e32 v5, v0
	v_mov_b32_e32 v6, v0
	v_mov_b32_e32 v7, v0
	v_mov_b32_e32 v16, v0
	v_mov_b32_e32 v17, v0
	v_mov_b32_e32 v18, v0
	v_mov_b32_e32 v19, v0
	v_mov_b32_e32 v20, v0
	v_mov_b32_e32 v21, v0
	v_mov_b32_e32 v22, v0
	v_mov_b32_e32 v23, v0
	v_mov_b32_e32 v32, v0
	v_mov_b32_e32 v33, v0
	v_mov_b32_e32 v34, v0
	v_mov_b32_e32 v35, v0
	v_mov_b32_e32 v36, v0
	v_mov_b32_e32 v37, v0
	v_mov_b32_e32 v38, v0
	v_mov_b32_e32 v39, v0
	v_mov_b32_e32 v48, v0
	v_mov_b32_e32 v49, v0
	v_mov_b32_e32 v50, v0
	v_mov_b32_e32 v51, v0
	v_mov_b32_e32 v52, v0
	v_mov_b32_e32 v53, v0
	v_mov_b32_e32 v54, v0
	v_mov_b32_e32 v55, v0
	v_mov_b32_e32 v8, v0
	v_mov_b32_e32 v9, v0
	v_mov_b32_e32 v10, v0
	v_mov_b32_e32 v11, v0
	v_mov_b32_e32 v12, v0
	v_mov_b32_e32 v13, v0
	v_mov_b32_e32 v14, v0
	v_mov_b32_e32 v15, v0
	v_mov_b32_e32 v24, v0
	v_mov_b32_e32 v25, v0
	v_mov_b32_e32 v26, v0
	v_mov_b32_e32 v27, v0
	v_mov_b32_e32 v28, v0
	v_mov_b32_e32 v29, v0
	v_mov_b32_e32 v30, v0
	v_mov_b32_e32 v31, v0
	v_mov_b32_e32 v40, v0
	v_mov_b32_e32 v41, v0
	v_mov_b32_e32 v42, v0
	v_mov_b32_e32 v43, v0
	v_mov_b32_e32 v44, v0
	v_mov_b32_e32 v45, v0
	v_mov_b32_e32 v46, v0
	v_mov_b32_e32 v47, v0
	v_mov_b32_e32 v56, v0
	v_mov_b32_e32 v57, v0
	v_mov_b32_e32 v58, v0
	v_mov_b32_e32 v59, v0
	v_mov_b32_e32 v60, v0
	v_mov_b32_e32 v61, v0
	v_mov_b32_e32 v62, v0
	v_mov_b32_e32 v63, v0
	v_mov_b32_e32 v64, v0
	v_mov_b32_e32 v65, v0
	v_mov_b32_e32 v66, v0
	v_mov_b32_e32 v67, v0
	v_mov_b32_e32 v68, v0
	v_mov_b32_e32 v69, v0
	v_mov_b32_e32 v70, v0
	v_mov_b32_e32 v71, v0
	v_mov_b32_e32 v80, v0
	v_mov_b32_e32 v81, v0
	v_mov_b32_e32 v82, v0
	v_mov_b32_e32 v83, v0
	v_mov_b32_e32 v84, v0
	v_mov_b32_e32 v85, v0
	v_mov_b32_e32 v86, v0
	v_mov_b32_e32 v87, v0
	v_mov_b32_e32 v96, v0
	v_mov_b32_e32 v97, v0
	v_mov_b32_e32 v98, v0
	v_mov_b32_e32 v99, v0
	v_mov_b32_e32 v100, v0
	v_mov_b32_e32 v101, v0
	v_mov_b32_e32 v102, v0
	v_mov_b32_e32 v103, v0
	v_mov_b32_e32 v112, v0
	v_mov_b32_e32 v113, v0
	v_mov_b32_e32 v114, v0
	v_mov_b32_e32 v115, v0
	v_mov_b32_e32 v120, v0
	v_mov_b32_e32 v121, v0
	v_mov_b32_e32 v122, v0
	v_mov_b32_e32 v123, v0
	v_mov_b32_e32 v72, v0
	v_mov_b32_e32 v73, v0
	v_mov_b32_e32 v74, v0
	v_mov_b32_e32 v75, v0
	v_mov_b32_e32 v76, v0
	v_mov_b32_e32 v77, v0
	v_mov_b32_e32 v78, v0
	v_mov_b32_e32 v79, v0
	v_mov_b32_e32 v88, v0
	v_mov_b32_e32 v89, v0
	v_mov_b32_e32 v90, v0
	v_mov_b32_e32 v91, v0
	v_mov_b32_e32 v92, v0
	v_mov_b32_e32 v93, v0
	v_mov_b32_e32 v94, v0
	v_mov_b32_e32 v95, v0
	v_mov_b32_e32 v104, v0
	v_mov_b32_e32 v105, v0
	v_mov_b32_e32 v106, v0
	v_mov_b32_e32 v107, v0
	v_mov_b32_e32 v108, v0
	v_mov_b32_e32 v109, v0
	v_mov_b32_e32 v110, v0
	v_mov_b32_e32 v111, v0
	v_mov_b32_e32 v116, v0
	v_mov_b32_e32 v117, v0
	v_mov_b32_e32 v118, v0
	v_mov_b32_e32 v119, v0
	v_mov_b32_e32 v124, v0
	v_mov_b32_e32 v125, v0
	v_mov_b32_e32 v126, v0
	v_mov_b32_e32 v127, v0
	s_waitcnt vmcnt(0)
	s_cmpk_lt_u32 s97, 0x100
	s_cbranch_scc1 .Lmy_prio_skip3
	s_setprio 1
.Lmy_prio_skip3:
.LBB0_679:
	ds_read_b128 v[144:147], v151
	ds_read_b128 v[154:157], v151 offset:1024
	ds_read_b128 v[158:161], v151 offset:2048
	ds_read_b128 v[162:165], v151 offset:3072
	ds_read_b128 v[166:169], v152
	ds_read_b128 v[170:173], v152 offset:1024
	ds_read_b128 v[174:177], v152 offset:2048
	ds_read_b128 v[178:181], v152 offset:3072
	s_add_u32 s37, s50, 0xfff00080
	s_addc_u32 s38, s51, -1
	s_cmp_eq_u32 s36, 60
	s_cselect_b32 s55, s19, s38
	s_cselect_b32 s54, s66, s37
	s_cselect_b32 s53, s17, s35
	s_cselect_b32 s52, s67, s34
	v_lshl_add_u64 v[214:215], s[50:51], 0, v[136:137]
	s_add_i32 m0, s49, 0xc000
	ds_read_b128 v[182:185], v153
	ds_read_b128 v[186:189], v153 offset:1024
	ds_read_b128 v[190:193], v153 offset:2048
	ds_read_b128 v[194:197], v153 offset:3072
	ds_read_b128 v[198:201], v153 offset:4096
	ds_read_b128 v[202:205], v153 offset:5120
	ds_read_b128 v[206:209], v153 offset:6144
	ds_read_b128 v[210:213], v153 offset:7168
	global_load_lds_dwordx4 v[214:215], off
	v_lshl_add_u64 v[214:215], s[50:51], 0, v[138:139]
	s_add_i32 m0, s49, 0xe000
	s_nop 0
	global_load_lds_dwordx4 v[214:215], off
	s_waitcnt vmcnt(8)
	s_waitcnt lgkmcnt(0)
	s_barrier
	s_waitcnt lgkmcnt(0)
	v_mfma_f32_16x16x32_bf16 v[124:127], v[144:147], v[182:185], v[124:127]
	v_mfma_f32_16x16x32_bf16 v[116:119], v[158:161], v[182:185], v[116:119]
	v_mfma_f32_16x16x32_bf16 v[108:111], v[144:147], v[190:193], v[108:111]
	v_mfma_f32_16x16x32_bf16 v[104:107], v[158:161], v[190:193], v[104:107]
	v_mfma_f32_16x16x32_bf16 v[92:95], v[144:147], v[198:201], v[92:95]
	v_mfma_f32_16x16x32_bf16 v[88:91], v[158:161], v[198:201], v[88:91]
	v_mfma_f32_16x16x32_bf16 v[76:79], v[144:147], v[206:209], v[76:79]
	v_mfma_f32_16x16x32_bf16 v[72:75], v[158:161], v[206:209], v[72:75]
	v_mfma_f32_16x16x32_bf16 v[124:127], v[154:157], v[186:189], v[124:127]
	v_mfma_f32_16x16x32_bf16 v[116:119], v[162:165], v[186:189], v[116:119]
	v_mfma_f32_16x16x32_bf16 v[108:111], v[154:157], v[194:197], v[108:111]
	v_mfma_f32_16x16x32_bf16 v[104:107], v[162:165], v[194:197], v[104:107]
	v_mfma_f32_16x16x32_bf16 v[92:95], v[154:157], v[202:205], v[92:95]
	v_mfma_f32_16x16x32_bf16 v[88:91], v[162:165], v[202:205], v[88:91]
	v_mfma_f32_16x16x32_bf16 v[76:79], v[154:157], v[210:213], v[76:79]
	v_mfma_f32_16x16x32_bf16 v[72:75], v[162:165], v[210:213], v[72:75]
	v_mfma_f32_16x16x32_bf16 v[120:123], v[166:169], v[182:185], v[120:123]
	v_mfma_f32_16x16x32_bf16 v[112:115], v[174:177], v[182:185], v[112:115]
	v_mfma_f32_16x16x32_bf16 v[100:103], v[166:169], v[190:193], v[100:103]
	v_mfma_f32_16x16x32_bf16 v[96:99], v[174:177], v[190:193], v[96:99]
	v_mfma_f32_16x16x32_bf16 v[84:87], v[166:169], v[198:201], v[84:87]
	v_mfma_f32_16x16x32_bf16 v[80:83], v[174:177], v[198:201], v[80:83]
	v_mfma_f32_16x16x32_bf16 v[68:71], v[166:169], v[206:209], v[68:71]
	v_mfma_f32_16x16x32_bf16 v[64:67], v[174:177], v[206:209], v[64:67]
	v_mfma_f32_16x16x32_bf16 v[120:123], v[170:173], v[186:189], v[120:123]
	v_mfma_f32_16x16x32_bf16 v[112:115], v[178:181], v[186:189], v[112:115]
	v_mfma_f32_16x16x32_bf16 v[100:103], v[170:173], v[194:197], v[100:103]
	v_mfma_f32_16x16x32_bf16 v[96:99], v[178:181], v[194:197], v[96:99]
	v_mfma_f32_16x16x32_bf16 v[84:87], v[170:173], v[202:205], v[84:87]
	v_mfma_f32_16x16x32_bf16 v[80:83], v[178:181], v[202:205], v[80:83]
	v_mfma_f32_16x16x32_bf16 v[68:71], v[170:173], v[210:213], v[68:71]
	v_mfma_f32_16x16x32_bf16 v[64:67], v[178:181], v[210:213], v[64:67]
	s_barrier
	s_add_i32 s37, s63, s33
	v_lshl_add_u64 v[214:215], s[52:53], 0, v[130:131]
	s_mov_b32 m0, s37
	ds_read_b128 v[182:185], v153 offset:16384
	ds_read_b128 v[186:189], v153 offset:17408
	ds_read_b128 v[190:193], v153 offset:18432
	ds_read_b128 v[194:197], v153 offset:19456
	ds_read_b128 v[198:201], v153 offset:20480
	ds_read_b128 v[202:205], v153 offset:21504
	ds_read_b128 v[206:209], v153 offset:22528
	ds_read_b128 v[210:213], v153 offset:23552
	global_load_lds_dwordx4 v[214:215], off
	s_add_i32 m0, s37, 0x2000
	s_add_u32 s38, s52, 0x100000
	v_lshl_add_u64 v[216:217], s[52:53], 0, v[134:135]
	s_addc_u32 s39, s53, 0
	s_add_i32 s37, s64, s33
	global_load_lds_dwordx4 v[216:217], off
	v_lshl_add_u64 v[218:219], s[38:39], 0, v[130:131]
	s_mov_b32 m0, s37
	v_lshl_add_u64 v[220:221], s[54:55], 0, v[132:133]
	global_load_lds_dwordx4 v[218:219], off
	v_lshl_add_u64 v[218:219], s[38:39], 0, v[134:135]
	s_add_i32 m0, s37, 0x2000
	s_nop 0
	global_load_lds_dwordx4 v[218:219], off
	v_lshl_add_u64 v[218:219], s[54:55], 0, v[128:129]
	s_mov_b32 m0, s49
	s_nop 0
	global_load_lds_dwordx4 v[218:219], off
	s_mov_b32 m0, s56
	s_nop 0
	global_load_lds_dwordx4 v[220:221], off
	s_waitcnt vmcnt(8)
	s_waitcnt lgkmcnt(0)
	s_barrier
	s_waitcnt lgkmcnt(0)
	v_mfma_f32_16x16x32_bf16 v[60:63], v[144:147], v[182:185], v[60:63]
	v_mfma_f32_16x16x32_bf16 v[56:59], v[158:161], v[182:185], v[56:59]
	v_mfma_f32_16x16x32_bf16 v[44:47], v[144:147], v[190:193], v[44:47]
	v_mfma_f32_16x16x32_bf16 v[40:43], v[158:161], v[190:193], v[40:43]
	v_mfma_f32_16x16x32_bf16 v[28:31], v[144:147], v[198:201], v[28:31]
	v_mfma_f32_16x16x32_bf16 v[24:27], v[158:161], v[198:201], v[24:27]
	v_mfma_f32_16x16x32_bf16 v[12:15], v[144:147], v[206:209], v[12:15]
	v_mfma_f32_16x16x32_bf16 v[8:11], v[158:161], v[206:209], v[8:11]
	v_mfma_f32_16x16x32_bf16 v[60:63], v[154:157], v[186:189], v[60:63]
	v_mfma_f32_16x16x32_bf16 v[56:59], v[162:165], v[186:189], v[56:59]
	v_mfma_f32_16x16x32_bf16 v[44:47], v[154:157], v[194:197], v[44:47]
	v_mfma_f32_16x16x32_bf16 v[40:43], v[162:165], v[194:197], v[40:43]
	v_mfma_f32_16x16x32_bf16 v[28:31], v[154:157], v[202:205], v[28:31]
	v_mfma_f32_16x16x32_bf16 v[24:27], v[162:165], v[202:205], v[24:27]
	v_mfma_f32_16x16x32_bf16 v[12:15], v[154:157], v[210:213], v[12:15]
	v_mfma_f32_16x16x32_bf16 v[8:11], v[162:165], v[210:213], v[8:11]
	v_mfma_f32_16x16x32_bf16 v[52:55], v[166:169], v[182:185], v[52:55]
	v_mfma_f32_16x16x32_bf16 v[48:51], v[174:177], v[182:185], v[48:51]
	v_mfma_f32_16x16x32_bf16 v[36:39], v[166:169], v[190:193], v[36:39]
	v_mfma_f32_16x16x32_bf16 v[32:35], v[174:177], v[190:193], v[32:35]
	v_mfma_f32_16x16x32_bf16 v[20:23], v[166:169], v[198:201], v[20:23]
	v_mfma_f32_16x16x32_bf16 v[16:19], v[174:177], v[198:201], v[16:19]
	v_mfma_f32_16x16x32_bf16 v[4:7], v[166:169], v[206:209], v[4:7]
	v_mfma_f32_16x16x32_bf16 v[0:3], v[174:177], v[206:209], v[0:3]
	v_mfma_f32_16x16x32_bf16 v[52:55], v[170:173], v[186:189], v[52:55]
	v_mfma_f32_16x16x32_bf16 v[48:51], v[178:181], v[186:189], v[48:51]
	v_mfma_f32_16x16x32_bf16 v[36:39], v[170:173], v[194:197], v[36:39]
	v_mfma_f32_16x16x32_bf16 v[32:35], v[178:181], v[194:197], v[32:35]
	v_mfma_f32_16x16x32_bf16 v[20:23], v[170:173], v[202:205], v[20:23]
	v_mfma_f32_16x16x32_bf16 v[16:19], v[178:181], v[202:205], v[16:19]
	v_mfma_f32_16x16x32_bf16 v[4:7], v[170:173], v[210:213], v[4:7]
	v_mfma_f32_16x16x32_bf16 v[0:3], v[178:181], v[210:213], v[0:3]
	s_barrier
	s_add_i32 s37, 0, 0x18000
	s_add_i32 s40, 0, 0x1c000
	v_add_u32_e32 v162, s37, v149
	v_add_u32_e32 v178, s40, v149
	ds_read_b128 v[144:147], v162
	ds_read_b128 v[154:157], v162 offset:1024
	ds_read_b128 v[158:161], v162 offset:2048
	ds_read_b128 v[162:165], v162 offset:3072
	ds_read_b128 v[166:169], v178
	ds_read_b128 v[170:173], v178 offset:1024
	ds_read_b128 v[174:177], v178 offset:2048
	ds_read_b128 v[178:181], v178 offset:3072
	s_add_u32 s38, s54, 0x100000
	s_addc_u32 s39, s55, 0
	s_mov_b32 m0, s57
	v_lshl_add_u64 v[222:223], s[38:39], 0, v[128:129]
	ds_read_b128 v[182:185], v153 offset:32768
	ds_read_b128 v[186:189], v153 offset:33792
	ds_read_b128 v[190:193], v153 offset:34816
	ds_read_b128 v[194:197], v153 offset:35840
	ds_read_b128 v[198:201], v153 offset:36864
	ds_read_b128 v[202:205], v153 offset:37888
	ds_read_b128 v[206:209], v153 offset:38912
	ds_read_b128 v[210:213], v153 offset:39936
	global_load_lds_dwordx4 v[222:223], off
	v_lshl_add_u64 v[222:223], s[38:39], 0, v[132:133]
	s_mov_b32 m0, s58
	s_nop 0
	global_load_lds_dwordx4 v[222:223], off
	s_waitcnt vmcnt(8)
	s_waitcnt lgkmcnt(0)
	s_barrier
	s_waitcnt lgkmcnt(0)
	v_mfma_f32_16x16x32_bf16 v[124:127], v[144:147], v[182:185], v[124:127]
	v_mfma_f32_16x16x32_bf16 v[116:119], v[158:161], v[182:185], v[116:119]
	v_mfma_f32_16x16x32_bf16 v[108:111], v[144:147], v[190:193], v[108:111]
	v_mfma_f32_16x16x32_bf16 v[104:107], v[158:161], v[190:193], v[104:107]
	v_mfma_f32_16x16x32_bf16 v[92:95], v[144:147], v[198:201], v[92:95]
	v_mfma_f32_16x16x32_bf16 v[88:91], v[158:161], v[198:201], v[88:91]
	v_mfma_f32_16x16x32_bf16 v[76:79], v[144:147], v[206:209], v[76:79]
	v_mfma_f32_16x16x32_bf16 v[72:75], v[158:161], v[206:209], v[72:75]
	v_mfma_f32_16x16x32_bf16 v[124:127], v[154:157], v[186:189], v[124:127]
	v_mfma_f32_16x16x32_bf16 v[116:119], v[162:165], v[186:189], v[116:119]
	v_mfma_f32_16x16x32_bf16 v[108:111], v[154:157], v[194:197], v[108:111]
	v_mfma_f32_16x16x32_bf16 v[104:107], v[162:165], v[194:197], v[104:107]
	v_mfma_f32_16x16x32_bf16 v[92:95], v[154:157], v[202:205], v[92:95]
	v_mfma_f32_16x16x32_bf16 v[88:91], v[162:165], v[202:205], v[88:91]
	v_mfma_f32_16x16x32_bf16 v[76:79], v[154:157], v[210:213], v[76:79]
	v_mfma_f32_16x16x32_bf16 v[72:75], v[162:165], v[210:213], v[72:75]
	v_mfma_f32_16x16x32_bf16 v[120:123], v[166:169], v[182:185], v[120:123]
	v_mfma_f32_16x16x32_bf16 v[112:115], v[174:177], v[182:185], v[112:115]
	v_mfma_f32_16x16x32_bf16 v[100:103], v[166:169], v[190:193], v[100:103]
	v_mfma_f32_16x16x32_bf16 v[96:99], v[174:177], v[190:193], v[96:99]
	v_mfma_f32_16x16x32_bf16 v[84:87], v[166:169], v[198:201], v[84:87]
	v_mfma_f32_16x16x32_bf16 v[80:83], v[174:177], v[198:201], v[80:83]
	v_mfma_f32_16x16x32_bf16 v[68:71], v[166:169], v[206:209], v[68:71]
	v_mfma_f32_16x16x32_bf16 v[64:67], v[174:177], v[206:209], v[64:67]
	v_mfma_f32_16x16x32_bf16 v[120:123], v[170:173], v[186:189], v[120:123]
	v_mfma_f32_16x16x32_bf16 v[112:115], v[178:181], v[186:189], v[112:115]
	v_mfma_f32_16x16x32_bf16 v[100:103], v[170:173], v[194:197], v[100:103]
	v_mfma_f32_16x16x32_bf16 v[96:99], v[178:181], v[194:197], v[96:99]
	v_mfma_f32_16x16x32_bf16 v[84:87], v[170:173], v[202:205], v[84:87]
	v_mfma_f32_16x16x32_bf16 v[80:83], v[178:181], v[202:205], v[80:83]
	v_mfma_f32_16x16x32_bf16 v[68:71], v[170:173], v[210:213], v[68:71]
	v_mfma_f32_16x16x32_bf16 v[64:67], v[178:181], v[210:213], v[64:67]
	s_barrier
	s_add_i32 s37, s37, s33
	v_lshl_add_u64 v[214:215], v[214:215], 0, s[10:11]
	s_mov_b32 m0, s37
	ds_read_b128 v[182:185], v153 offset:49152
	ds_read_b128 v[186:189], v153 offset:50176
	ds_read_b128 v[190:193], v153 offset:51200
	ds_read_b128 v[194:197], v153 offset:52224
	ds_read_b128 v[198:201], v153 offset:53248
	ds_read_b128 v[202:205], v153 offset:54272
	ds_read_b128 v[206:209], v153 offset:55296
	ds_read_b128 v[210:213], v153 offset:56320
	global_load_lds_dwordx4 v[214:215], off
	s_add_i32 m0, s37, 0x2000
	s_add_u32 s38, s52, 0x100080
	v_lshl_add_u64 v[214:215], v[216:217], 0, s[10:11]
	s_addc_u32 s39, s53, 0
	s_add_i32 s37, s40, s33
	global_load_lds_dwordx4 v[214:215], off
	v_lshl_add_u64 v[214:215], s[38:39], 0, v[130:131]
	s_mov_b32 m0, s37
	s_nop 0
	global_load_lds_dwordx4 v[214:215], off
	v_lshl_add_u64 v[214:215], s[38:39], 0, v[134:135]
	s_add_i32 m0, s37, 0x2000
	s_nop 0
	global_load_lds_dwordx4 v[214:215], off
	v_lshl_add_u64 v[214:215], v[218:219], 0, s[10:11]
	s_mov_b32 m0, s60
	s_nop 0
	global_load_lds_dwordx4 v[214:215], off
	v_lshl_add_u64 v[214:215], v[220:221], 0, s[10:11]
	s_mov_b32 m0, s61
	s_nop 0
	global_load_lds_dwordx4 v[214:215], off
	s_waitcnt vmcnt(8)
	s_waitcnt lgkmcnt(0)
	s_barrier
	s_waitcnt lgkmcnt(0)
	v_mfma_f32_16x16x32_bf16 v[60:63], v[144:147], v[182:185], v[60:63]
	v_mfma_f32_16x16x32_bf16 v[56:59], v[158:161], v[182:185], v[56:59]
	v_mfma_f32_16x16x32_bf16 v[44:47], v[144:147], v[190:193], v[44:47]
	v_mfma_f32_16x16x32_bf16 v[40:43], v[158:161], v[190:193], v[40:43]
	v_mfma_f32_16x16x32_bf16 v[28:31], v[144:147], v[198:201], v[28:31]
	v_mfma_f32_16x16x32_bf16 v[24:27], v[158:161], v[198:201], v[24:27]
	v_mfma_f32_16x16x32_bf16 v[12:15], v[144:147], v[206:209], v[12:15]
	v_mfma_f32_16x16x32_bf16 v[8:11], v[158:161], v[206:209], v[8:11]
	v_mfma_f32_16x16x32_bf16 v[60:63], v[154:157], v[186:189], v[60:63]
	v_mfma_f32_16x16x32_bf16 v[56:59], v[162:165], v[186:189], v[56:59]
	v_mfma_f32_16x16x32_bf16 v[44:47], v[154:157], v[194:197], v[44:47]
	v_mfma_f32_16x16x32_bf16 v[40:43], v[162:165], v[194:197], v[40:43]
	v_mfma_f32_16x16x32_bf16 v[28:31], v[154:157], v[202:205], v[28:31]
	v_mfma_f32_16x16x32_bf16 v[24:27], v[162:165], v[202:205], v[24:27]
	v_mfma_f32_16x16x32_bf16 v[12:15], v[154:157], v[210:213], v[12:15]
	v_mfma_f32_16x16x32_bf16 v[8:11], v[162:165], v[210:213], v[8:11]
	v_mfma_f32_16x16x32_bf16 v[52:55], v[166:169], v[182:185], v[52:55]
	v_mfma_f32_16x16x32_bf16 v[48:51], v[174:177], v[182:185], v[48:51]
	v_mfma_f32_16x16x32_bf16 v[36:39], v[166:169], v[190:193], v[36:39]
	v_mfma_f32_16x16x32_bf16 v[32:35], v[174:177], v[190:193], v[32:35]
	v_mfma_f32_16x16x32_bf16 v[20:23], v[166:169], v[198:201], v[20:23]
	v_mfma_f32_16x16x32_bf16 v[16:19], v[174:177], v[198:201], v[16:19]
	v_mfma_f32_16x16x32_bf16 v[4:7], v[166:169], v[206:209], v[4:7]
	v_mfma_f32_16x16x32_bf16 v[0:3], v[174:177], v[206:209], v[0:3]
	v_mfma_f32_16x16x32_bf16 v[52:55], v[170:173], v[186:189], v[52:55]
	v_mfma_f32_16x16x32_bf16 v[48:51], v[178:181], v[186:189], v[48:51]
	v_mfma_f32_16x16x32_bf16 v[36:39], v[170:173], v[194:197], v[36:39]
	v_mfma_f32_16x16x32_bf16 v[32:35], v[178:181], v[194:197], v[32:35]
	v_mfma_f32_16x16x32_bf16 v[20:23], v[170:173], v[202:205], v[20:23]
	v_mfma_f32_16x16x32_bf16 v[16:19], v[178:181], v[202:205], v[16:19]
	v_mfma_f32_16x16x32_bf16 v[4:7], v[170:173], v[210:213], v[4:7]
	v_mfma_f32_16x16x32_bf16 v[0:3], v[178:181], v[210:213], v[0:3]
	s_barrier
	s_add_i32 s36, s36, 2
	s_add_u32 s50, s50, 0x100
	s_addc_u32 s51, s51, 0
	s_add_u32 s34, s34, 0x100
	s_addc_u32 s35, s35, 0
	s_cmp_gt_u32 s36, 61
	s_cbranch_scc0 .LBB0_679
	s_setprio 0
	s_and_b64 vcc, exec, s[12:13]
	s_cbranch_vccz .LBB0_682
	s_barrier

.LBB0_757:
	s_ashr_i32 s13, s12, 31
	s_lshl_b64 s[16:17], s[12:13], 21
	s_add_u32 s16, s33, s16
	s_addc_u32 s17, s66, s17
	s_and_b64 s[18:19], s[0:1], exec
	s_cselect_b32 s13, s17, s49
	s_cselect_b32 s64, s16, s48
	s_ashr_i32 s11, s10, 31
	s_lshl_b64 s[18:19], s[10:11], 21
	s_add_u32 s18, s91, s18
	s_addc_u32 s19, s85, s19
	s_and_b64 s[34:35], s[0:1], exec
	s_cselect_b32 s11, s19, s47
	s_cselect_b32 s65, s18, s46
	s_add_u32 s38, s48, 0x100080
	s_addc_u32 s39, s49, 0
	s_add_u32 s34, s46, 0x100
	v_mov_b32_e32 v0, 0
	s_addc_u32 s35, s47, 0
	s_mov_b32 s36, -2
	v_mov_b32_e32 v1, v0
	v_mov_b32_e32 v2, v0
	v_mov_b32_e32 v3, v0
	v_mov_b32_e32 v4, v0
	v_mov_b32_e32 v5, v0
	v_mov_b32_e32 v6, v0
	v_mov_b32_e32 v7, v0
	v_mov_b32_e32 v16, v0
	v_mov_b32_e32 v17, v0
	v_mov_b32_e32 v18, v0
	v_mov_b32_e32 v19, v0
	v_mov_b32_e32 v20, v0
	v_mov_b32_e32 v21, v0
	v_mov_b32_e32 v22, v0
	v_mov_b32_e32 v23, v0
	v_mov_b32_e32 v32, v0
	v_mov_b32_e32 v33, v0
	v_mov_b32_e32 v34, v0
	v_mov_b32_e32 v35, v0
	v_mov_b32_e32 v36, v0
	v_mov_b32_e32 v37, v0
	v_mov_b32_e32 v38, v0
	v_mov_b32_e32 v39, v0
	v_mov_b32_e32 v48, v0
	v_mov_b32_e32 v49, v0
	v_mov_b32_e32 v50, v0
	v_mov_b32_e32 v51, v0
	v_mov_b32_e32 v52, v0
	v_mov_b32_e32 v53, v0
	v_mov_b32_e32 v54, v0
	v_mov_b32_e32 v55, v0
	v_mov_b32_e32 v8, v0
	v_mov_b32_e32 v9, v0
	v_mov_b32_e32 v10, v0
	v_mov_b32_e32 v11, v0
	v_mov_b32_e32 v12, v0
	v_mov_b32_e32 v13, v0
	v_mov_b32_e32 v14, v0
	v_mov_b32_e32 v15, v0
	v_mov_b32_e32 v24, v0
	v_mov_b32_e32 v25, v0
	v_mov_b32_e32 v26, v0
	v_mov_b32_e32 v27, v0
	v_mov_b32_e32 v28, v0
	v_mov_b32_e32 v29, v0
	v_mov_b32_e32 v30, v0
	v_mov_b32_e32 v31, v0
	v_mov_b32_e32 v40, v0
	v_mov_b32_e32 v41, v0
	v_mov_b32_e32 v42, v0
	v_mov_b32_e32 v43, v0
	v_mov_b32_e32 v44, v0
	v_mov_b32_e32 v45, v0
	v_mov_b32_e32 v46, v0
	v_mov_b32_e32 v47, v0
	v_mov_b32_e32 v56, v0
	v_mov_b32_e32 v57, v0
	v_mov_b32_e32 v58, v0
	v_mov_b32_e32 v59, v0
	v_mov_b32_e32 v60, v0
	v_mov_b32_e32 v61, v0
	v_mov_b32_e32 v62, v0
	v_mov_b32_e32 v63, v0
	v_mov_b32_e32 v64, v0
	v_mov_b32_e32 v65, v0
	v_mov_b32_e32 v66, v0
	v_mov_b32_e32 v67, v0
	v_mov_b32_e32 v68, v0
	v_mov_b32_e32 v69, v0
	v_mov_b32_e32 v70, v0
	v_mov_b32_e32 v71, v0
	v_mov_b32_e32 v80, v0
	v_mov_b32_e32 v81, v0
	v_mov_b32_e32 v82, v0
	v_mov_b32_e32 v83, v0
	v_mov_b32_e32 v84, v0
	v_mov_b32_e32 v85, v0
	v_mov_b32_e32 v86, v0
	v_mov_b32_e32 v87, v0
	v_mov_b32_e32 v96, v0
	v_mov_b32_e32 v97, v0
	v_mov_b32_e32 v98, v0
	v_mov_b32_e32 v99, v0
	v_mov_b32_e32 v100, v0
	v_mov_b32_e32 v101, v0
	v_mov_b32_e32 v102, v0
	v_mov_b32_e32 v103, v0
	v_mov_b32_e32 v112, v0
	v_mov_b32_e32 v113, v0
	v_mov_b32_e32 v114, v0
	v_mov_b32_e32 v115, v0
	v_mov_b32_e32 v116, v0
	v_mov_b32_e32 v117, v0
	v_mov_b32_e32 v118, v0
	v_mov_b32_e32 v119, v0
	v_mov_b32_e32 v72, v0
	v_mov_b32_e32 v73, v0
	v_mov_b32_e32 v74, v0
	v_mov_b32_e32 v75, v0
	v_mov_b32_e32 v76, v0
	v_mov_b32_e32 v77, v0
	v_mov_b32_e32 v78, v0
	v_mov_b32_e32 v79, v0
	v_mov_b32_e32 v88, v0
	v_mov_b32_e32 v89, v0
	v_mov_b32_e32 v90, v0
	v_mov_b32_e32 v91, v0
	v_mov_b32_e32 v92, v0
	v_mov_b32_e32 v93, v0
	v_mov_b32_e32 v94, v0
	v_mov_b32_e32 v95, v0
	v_mov_b32_e32 v104, v0
	v_mov_b32_e32 v105, v0
	v_mov_b32_e32 v106, v0
	v_mov_b32_e32 v107, v0
	v_mov_b32_e32 v108, v0
	v_mov_b32_e32 v109, v0
	v_mov_b32_e32 v110, v0
	v_mov_b32_e32 v111, v0
	v_mov_b32_e32 v120, v0
	v_mov_b32_e32 v121, v0
	v_mov_b32_e32 v122, v0
	v_mov_b32_e32 v123, v0
	v_mov_b32_e32 v124, v0
	v_mov_b32_e32 v125, v0
	v_mov_b32_e32 v126, v0
	v_mov_b32_e32 v127, v0
	s_waitcnt vmcnt(0)
	s_cmpk_lt_u32 s97, 0x100
	s_cbranch_scc1 .Lmy_prio_skip4
	s_setprio 1
.Lmy_prio_skip4:
.LBB0_758:
	ds_read_b128 v[144:147], v153
	ds_read_b128 v[156:159], v153 offset:1024
	ds_read_b128 v[160:163], v153 offset:2048
	ds_read_b128 v[164:167], v153 offset:3072
	ds_read_b128 v[168:171], v154
	ds_read_b128 v[172:175], v154 offset:1024
	ds_read_b128 v[176:179], v154 offset:2048
	ds_read_b128 v[180:183], v154 offset:3072
	s_add_u32 s37, s38, 0xfff00080
	s_addc_u32 s40, s39, -1
	s_cmp_eq_u32 s36, 60
	s_cselect_b32 s49, s13, s40
	s_cselect_b32 s48, s64, s37
	s_cselect_b32 s47, s11, s35
	s_cselect_b32 s46, s65, s34
	v_lshl_add_u64 v[148:149], s[38:39], 0, v[136:137]
	s_add_i32 m0, s76, 0xc000
	ds_read_b128 v[184:187], v155
	ds_read_b128 v[188:191], v155 offset:1024
	ds_read_b128 v[192:195], v155 offset:2048
	ds_read_b128 v[196:199], v155 offset:3072
	ds_read_b128 v[200:203], v155 offset:4096
	ds_read_b128 v[204:207], v155 offset:5120
	ds_read_b128 v[208:211], v155 offset:6144
	ds_read_b128 v[212:215], v155 offset:7168
	global_load_lds_dwordx4 v[148:149], off
	v_lshl_add_u64 v[148:149], s[38:39], 0, v[138:139]
	s_add_i32 m0, s76, 0xe000
	s_nop 0
	global_load_lds_dwordx4 v[148:149], off
	s_waitcnt vmcnt(8)
	s_waitcnt lgkmcnt(0)
	s_barrier
	s_waitcnt lgkmcnt(0)
	v_mfma_f32_16x16x32_bf16 v[124:127], v[144:147], v[184:187], v[124:127]
	v_mfma_f32_16x16x32_bf16 v[120:123], v[160:163], v[184:187], v[120:123]
	v_mfma_f32_16x16x32_bf16 v[108:111], v[144:147], v[192:195], v[108:111]
	v_mfma_f32_16x16x32_bf16 v[104:107], v[160:163], v[192:195], v[104:107]
	v_mfma_f32_16x16x32_bf16 v[92:95], v[144:147], v[200:203], v[92:95]
	v_mfma_f32_16x16x32_bf16 v[88:91], v[160:163], v[200:203], v[88:91]
	v_mfma_f32_16x16x32_bf16 v[76:79], v[144:147], v[208:211], v[76:79]
	v_mfma_f32_16x16x32_bf16 v[72:75], v[160:163], v[208:211], v[72:75]
	v_mfma_f32_16x16x32_bf16 v[124:127], v[156:159], v[188:191], v[124:127]
	v_mfma_f32_16x16x32_bf16 v[120:123], v[164:167], v[188:191], v[120:123]
	v_mfma_f32_16x16x32_bf16 v[108:111], v[156:159], v[196:199], v[108:111]
	v_mfma_f32_16x16x32_bf16 v[104:107], v[164:167], v[196:199], v[104:107]
	v_mfma_f32_16x16x32_bf16 v[92:95], v[156:159], v[204:207], v[92:95]
	v_mfma_f32_16x16x32_bf16 v[88:91], v[164:167], v[204:207], v[88:91]
	v_mfma_f32_16x16x32_bf16 v[76:79], v[156:159], v[212:215], v[76:79]
	v_mfma_f32_16x16x32_bf16 v[72:75], v[164:167], v[212:215], v[72:75]
	v_mfma_f32_16x16x32_bf16 v[116:119], v[168:171], v[184:187], v[116:119]
	v_mfma_f32_16x16x32_bf16 v[112:115], v[176:179], v[184:187], v[112:115]
	v_mfma_f32_16x16x32_bf16 v[100:103], v[168:171], v[192:195], v[100:103]
	v_mfma_f32_16x16x32_bf16 v[96:99], v[176:179], v[192:195], v[96:99]
	v_mfma_f32_16x16x32_bf16 v[84:87], v[168:171], v[200:203], v[84:87]
	v_mfma_f32_16x16x32_bf16 v[80:83], v[176:179], v[200:203], v[80:83]
	v_mfma_f32_16x16x32_bf16 v[68:71], v[168:171], v[208:211], v[68:71]
	v_mfma_f32_16x16x32_bf16 v[64:67], v[176:179], v[208:211], v[64:67]
	v_mfma_f32_16x16x32_bf16 v[116:119], v[172:175], v[188:191], v[116:119]
	v_mfma_f32_16x16x32_bf16 v[112:115], v[180:183], v[188:191], v[112:115]
	v_mfma_f32_16x16x32_bf16 v[100:103], v[172:175], v[196:199], v[100:103]
	v_mfma_f32_16x16x32_bf16 v[96:99], v[180:183], v[196:199], v[96:99]
	v_mfma_f32_16x16x32_bf16 v[84:87], v[172:175], v[204:207], v[84:87]
	v_mfma_f32_16x16x32_bf16 v[80:83], v[180:183], v[204:207], v[80:83]
	v_mfma_f32_16x16x32_bf16 v[68:71], v[172:175], v[212:215], v[68:71]
	v_mfma_f32_16x16x32_bf16 v[64:67], v[180:183], v[212:215], v[64:67]
	s_barrier
	s_add_i32 s37, s61, s67
	v_lshl_add_u64 v[148:149], s[46:47], 0, v[130:131]
	s_mov_b32 m0, s37
	ds_read_b128 v[184:187], v155 offset:16384
	ds_read_b128 v[188:191], v155 offset:17408
	ds_read_b128 v[192:195], v155 offset:18432
	ds_read_b128 v[196:199], v155 offset:19456
	ds_read_b128 v[200:203], v155 offset:20480
	ds_read_b128 v[204:207], v155 offset:21504
	ds_read_b128 v[208:211], v155 offset:22528
	ds_read_b128 v[212:215], v155 offset:23552
	global_load_lds_dwordx4 v[148:149], off
	s_add_i32 m0, s37, 0x2000
	s_add_u32 s40, s46, 0x100000
	v_lshl_add_u64 v[216:217], s[46:47], 0, v[134:135]
	s_addc_u32 s41, s47, 0
	s_add_i32 s37, s62, s67
	global_load_lds_dwordx4 v[216:217], off
	v_lshl_add_u64 v[218:219], s[40:41], 0, v[130:131]
	s_mov_b32 m0, s37
	v_lshl_add_u64 v[220:221], s[48:49], 0, v[132:133]
	global_load_lds_dwordx4 v[218:219], off
	v_lshl_add_u64 v[218:219], s[40:41], 0, v[134:135]
	s_add_i32 m0, s37, 0x2000
	s_nop 0
	global_load_lds_dwordx4 v[218:219], off
	v_lshl_add_u64 v[218:219], s[48:49], 0, v[128:129]
	s_mov_b32 m0, s76
	s_nop 0
	global_load_lds_dwordx4 v[218:219], off
	s_mov_b32 m0, s52
	s_nop 0
	global_load_lds_dwordx4 v[220:221], off
	s_waitcnt vmcnt(8)
	s_waitcnt lgkmcnt(0)
	s_barrier
	s_waitcnt lgkmcnt(0)
	v_mfma_f32_16x16x32_bf16 v[60:63], v[144:147], v[184:187], v[60:63]
	v_mfma_f32_16x16x32_bf16 v[56:59], v[160:163], v[184:187], v[56:59]
	v_mfma_f32_16x16x32_bf16 v[44:47], v[144:147], v[192:195], v[44:47]
	v_mfma_f32_16x16x32_bf16 v[40:43], v[160:163], v[192:195], v[40:43]
	v_mfma_f32_16x16x32_bf16 v[28:31], v[144:147], v[200:203], v[28:31]
	v_mfma_f32_16x16x32_bf16 v[24:27], v[160:163], v[200:203], v[24:27]
	v_mfma_f32_16x16x32_bf16 v[12:15], v[144:147], v[208:211], v[12:15]
	v_mfma_f32_16x16x32_bf16 v[8:11], v[160:163], v[208:211], v[8:11]
	v_mfma_f32_16x16x32_bf16 v[60:63], v[156:159], v[188:191], v[60:63]
	v_mfma_f32_16x16x32_bf16 v[56:59], v[164:167], v[188:191], v[56:59]
	v_mfma_f32_16x16x32_bf16 v[44:47], v[156:159], v[196:199], v[44:47]
	v_mfma_f32_16x16x32_bf16 v[40:43], v[164:167], v[196:199], v[40:43]
	v_mfma_f32_16x16x32_bf16 v[28:31], v[156:159], v[204:207], v[28:31]
	v_mfma_f32_16x16x32_bf16 v[24:27], v[164:167], v[204:207], v[24:27]
	v_mfma_f32_16x16x32_bf16 v[12:15], v[156:159], v[212:215], v[12:15]
	v_mfma_f32_16x16x32_bf16 v[8:11], v[164:167], v[212:215], v[8:11]
	v_mfma_f32_16x16x32_bf16 v[52:55], v[168:171], v[184:187], v[52:55]
	v_mfma_f32_16x16x32_bf16 v[48:51], v[176:179], v[184:187], v[48:51]
	v_mfma_f32_16x16x32_bf16 v[36:39], v[168:171], v[192:195], v[36:39]
	v_mfma_f32_16x16x32_bf16 v[32:35], v[176:179], v[192:195], v[32:35]
	v_mfma_f32_16x16x32_bf16 v[20:23], v[168:171], v[200:203], v[20:23]
	v_mfma_f32_16x16x32_bf16 v[16:19], v[176:179], v[200:203], v[16:19]
	v_mfma_f32_16x16x32_bf16 v[4:7], v[168:171], v[208:211], v[4:7]
	v_mfma_f32_16x16x32_bf16 v[0:3], v[176:179], v[208:211], v[0:3]
	v_mfma_f32_16x16x32_bf16 v[52:55], v[172:175], v[188:191], v[52:55]
	v_mfma_f32_16x16x32_bf16 v[48:51], v[180:183], v[188:191], v[48:51]
	v_mfma_f32_16x16x32_bf16 v[36:39], v[172:175], v[196:199], v[36:39]
	v_mfma_f32_16x16x32_bf16 v[32:35], v[180:183], v[196:199], v[32:35]
	v_mfma_f32_16x16x32_bf16 v[20:23], v[172:175], v[204:207], v[20:23]
	v_mfma_f32_16x16x32_bf16 v[16:19], v[180:183], v[204:207], v[16:19]
	v_mfma_f32_16x16x32_bf16 v[4:7], v[172:175], v[212:215], v[4:7]
	v_mfma_f32_16x16x32_bf16 v[0:3], v[180:183], v[212:215], v[0:3]
	s_barrier
	s_add_i32 s37, 0, 0x18000
	s_add_i32 s42, 0, 0x1c000
	v_add_u32_e32 v164, s37, v151
	v_add_u32_e32 v180, s42, v151
	ds_read_b128 v[144:147], v164
	ds_read_b128 v[156:159], v164 offset:1024
	ds_read_b128 v[160:163], v164 offset:2048
	ds_read_b128 v[164:167], v164 offset:3072
	ds_read_b128 v[168:171], v180
	ds_read_b128 v[172:175], v180 offset:1024
	ds_read_b128 v[176:179], v180 offset:2048
	ds_read_b128 v[180:183], v180 offset:3072
	s_add_u32 s40, s48, 0x100000
	s_addc_u32 s41, s49, 0
	s_mov_b32 m0, s53
	v_lshl_add_u64 v[222:223], s[40:41], 0, v[128:129]
	ds_read_b128 v[184:187], v155 offset:32768
	ds_read_b128 v[188:191], v155 offset:33792
	ds_read_b128 v[192:195], v155 offset:34816
	ds_read_b128 v[196:199], v155 offset:35840
	ds_read_b128 v[200:203], v155 offset:36864
	ds_read_b128 v[204:207], v155 offset:37888
	ds_read_b128 v[208:211], v155 offset:38912
	ds_read_b128 v[212:215], v155 offset:39936
	global_load_lds_dwordx4 v[222:223], off
	v_lshl_add_u64 v[222:223], s[40:41], 0, v[132:133]
	s_mov_b32 m0, s54
	s_nop 0
	global_load_lds_dwordx4 v[222:223], off
	s_waitcnt vmcnt(8)
	s_waitcnt lgkmcnt(0)
	s_barrier
	s_waitcnt lgkmcnt(0)
	v_mfma_f32_16x16x32_bf16 v[124:127], v[144:147], v[184:187], v[124:127]
	v_mfma_f32_16x16x32_bf16 v[120:123], v[160:163], v[184:187], v[120:123]
	v_mfma_f32_16x16x32_bf16 v[108:111], v[144:147], v[192:195], v[108:111]
	v_mfma_f32_16x16x32_bf16 v[104:107], v[160:163], v[192:195], v[104:107]
	v_mfma_f32_16x16x32_bf16 v[92:95], v[144:147], v[200:203], v[92:95]
	v_mfma_f32_16x16x32_bf16 v[88:91], v[160:163], v[200:203], v[88:91]
	v_mfma_f32_16x16x32_bf16 v[76:79], v[144:147], v[208:211], v[76:79]
	v_mfma_f32_16x16x32_bf16 v[72:75], v[160:163], v[208:211], v[72:75]
	v_mfma_f32_16x16x32_bf16 v[124:127], v[156:159], v[188:191], v[124:127]
	v_mfma_f32_16x16x32_bf16 v[120:123], v[164:167], v[188:191], v[120:123]
	v_mfma_f32_16x16x32_bf16 v[108:111], v[156:159], v[196:199], v[108:111]
	v_mfma_f32_16x16x32_bf16 v[104:107], v[164:167], v[196:199], v[104:107]
	v_mfma_f32_16x16x32_bf16 v[92:95], v[156:159], v[204:207], v[92:95]
	v_mfma_f32_16x16x32_bf16 v[88:91], v[164:167], v[204:207], v[88:91]
	v_mfma_f32_16x16x32_bf16 v[76:79], v[156:159], v[212:215], v[76:79]
	v_mfma_f32_16x16x32_bf16 v[72:75], v[164:167], v[212:215], v[72:75]
	v_mfma_f32_16x16x32_bf16 v[116:119], v[168:171], v[184:187], v[116:119]
	v_mfma_f32_16x16x32_bf16 v[112:115], v[176:179], v[184:187], v[112:115]
	v_mfma_f32_16x16x32_bf16 v[100:103], v[168:171], v[192:195], v[100:103]
	v_mfma_f32_16x16x32_bf16 v[96:99], v[176:179], v[192:195], v[96:99]
	v_mfma_f32_16x16x32_bf16 v[84:87], v[168:171], v[200:203], v[84:87]
	v_mfma_f32_16x16x32_bf16 v[80:83], v[176:179], v[200:203], v[80:83]
	v_mfma_f32_16x16x32_bf16 v[68:71], v[168:171], v[208:211], v[68:71]
	v_mfma_f32_16x16x32_bf16 v[64:67], v[176:179], v[208:211], v[64:67]
	v_mfma_f32_16x16x32_bf16 v[116:119], v[172:175], v[188:191], v[116:119]
	v_mfma_f32_16x16x32_bf16 v[112:115], v[180:183], v[188:191], v[112:115]
	v_mfma_f32_16x16x32_bf16 v[100:103], v[172:175], v[196:199], v[100:103]
	v_mfma_f32_16x16x32_bf16 v[96:99], v[180:183], v[196:199], v[96:99]
	v_mfma_f32_16x16x32_bf16 v[84:87], v[172:175], v[204:207], v[84:87]
	v_mfma_f32_16x16x32_bf16 v[80:83], v[180:183], v[204:207], v[80:83]
	v_mfma_f32_16x16x32_bf16 v[68:71], v[172:175], v[212:215], v[68:71]
	v_mfma_f32_16x16x32_bf16 v[64:67], v[180:183], v[212:215], v[64:67]
	s_barrier
	s_add_i32 s37, s37, s67
	v_lshl_add_u64 v[148:149], v[148:149], 0, s[6:7]
	s_mov_b32 m0, s37
	ds_read_b128 v[184:187], v155 offset:49152
	ds_read_b128 v[188:191], v155 offset:50176
	ds_read_b128 v[192:195], v155 offset:51200
	ds_read_b128 v[196:199], v155 offset:52224
	ds_read_b128 v[200:203], v155 offset:53248
	ds_read_b128 v[204:207], v155 offset:54272
	ds_read_b128 v[208:211], v155 offset:55296
	ds_read_b128 v[212:215], v155 offset:56320
	global_load_lds_dwordx4 v[148:149], off
	s_add_i32 m0, s37, 0x2000
	s_add_u32 s40, s46, 0x100080
	v_lshl_add_u64 v[148:149], v[216:217], 0, s[6:7]
	s_addc_u32 s41, s47, 0
	s_add_i32 s37, s42, s67
	global_load_lds_dwordx4 v[148:149], off
	v_lshl_add_u64 v[148:149], s[40:41], 0, v[130:131]
	s_mov_b32 m0, s37
	s_nop 0
	global_load_lds_dwordx4 v[148:149], off
	v_lshl_add_u64 v[148:149], s[40:41], 0, v[134:135]
	s_add_i32 m0, s37, 0x2000
	s_nop 0
	global_load_lds_dwordx4 v[148:149], off
	v_lshl_add_u64 v[148:149], v[218:219], 0, s[6:7]
	s_mov_b32 m0, s56
	s_nop 0
	global_load_lds_dwordx4 v[148:149], off
	v_lshl_add_u64 v[148:149], v[220:221], 0, s[6:7]
	s_mov_b32 m0, s57
	s_nop 0
	global_load_lds_dwordx4 v[148:149], off
	s_waitcnt vmcnt(8)
	s_waitcnt lgkmcnt(0)
	s_barrier
	s_waitcnt lgkmcnt(0)
	v_mfma_f32_16x16x32_bf16 v[60:63], v[144:147], v[184:187], v[60:63]
	v_mfma_f32_16x16x32_bf16 v[56:59], v[160:163], v[184:187], v[56:59]
	v_mfma_f32_16x16x32_bf16 v[44:47], v[144:147], v[192:195], v[44:47]
	v_mfma_f32_16x16x32_bf16 v[40:43], v[160:163], v[192:195], v[40:43]
	v_mfma_f32_16x16x32_bf16 v[28:31], v[144:147], v[200:203], v[28:31]
	v_mfma_f32_16x16x32_bf16 v[24:27], v[160:163], v[200:203], v[24:27]
	v_mfma_f32_16x16x32_bf16 v[12:15], v[144:147], v[208:211], v[12:15]
	v_mfma_f32_16x16x32_bf16 v[8:11], v[160:163], v[208:211], v[8:11]
	v_mfma_f32_16x16x32_bf16 v[60:63], v[156:159], v[188:191], v[60:63]
	v_mfma_f32_16x16x32_bf16 v[56:59], v[164:167], v[188:191], v[56:59]
	v_mfma_f32_16x16x32_bf16 v[44:47], v[156:159], v[196:199], v[44:47]
	v_mfma_f32_16x16x32_bf16 v[40:43], v[164:167], v[196:199], v[40:43]
	v_mfma_f32_16x16x32_bf16 v[28:31], v[156:159], v[204:207], v[28:31]
	v_mfma_f32_16x16x32_bf16 v[24:27], v[164:167], v[204:207], v[24:27]
	v_mfma_f32_16x16x32_bf16 v[12:15], v[156:159], v[212:215], v[12:15]
	v_mfma_f32_16x16x32_bf16 v[8:11], v[164:167], v[212:215], v[8:11]
	v_mfma_f32_16x16x32_bf16 v[52:55], v[168:171], v[184:187], v[52:55]
	v_mfma_f32_16x16x32_bf16 v[48:51], v[176:179], v[184:187], v[48:51]
	v_mfma_f32_16x16x32_bf16 v[36:39], v[168:171], v[192:195], v[36:39]
	v_mfma_f32_16x16x32_bf16 v[32:35], v[176:179], v[192:195], v[32:35]
	v_mfma_f32_16x16x32_bf16 v[20:23], v[168:171], v[200:203], v[20:23]
	v_mfma_f32_16x16x32_bf16 v[16:19], v[176:179], v[200:203], v[16:19]
	v_mfma_f32_16x16x32_bf16 v[4:7], v[168:171], v[208:211], v[4:7]
	v_mfma_f32_16x16x32_bf16 v[0:3], v[176:179], v[208:211], v[0:3]
	v_mfma_f32_16x16x32_bf16 v[52:55], v[172:175], v[188:191], v[52:55]
	v_mfma_f32_16x16x32_bf16 v[48:51], v[180:183], v[188:191], v[48:51]
	v_mfma_f32_16x16x32_bf16 v[36:39], v[172:175], v[196:199], v[36:39]
	v_mfma_f32_16x16x32_bf16 v[32:35], v[180:183], v[196:199], v[32:35]
	v_mfma_f32_16x16x32_bf16 v[20:23], v[172:175], v[204:207], v[20:23]
	v_mfma_f32_16x16x32_bf16 v[16:19], v[180:183], v[204:207], v[16:19]
	v_mfma_f32_16x16x32_bf16 v[4:7], v[172:175], v[212:215], v[4:7]
	v_mfma_f32_16x16x32_bf16 v[0:3], v[180:183], v[212:215], v[0:3]
	s_barrier
	s_add_i32 s36, s36, 2
	s_add_u32 s38, s38, 0x100
	s_addc_u32 s39, s39, 0
	s_add_u32 s34, s34, 0x100
	s_addc_u32 s35, s35, 0
	s_cmp_gt_u32 s36, 61
	s_cbranch_scc0 .LBB0_758
	s_setprio 0
	s_and_b64 vcc, exec, s[8:9]
	s_cbranch_vccz .LBB0_761
	s_barrier

.LBB0_913:
	s_ashr_i32 s41, s40, 31
	s_lshl_b64 s[34:35], s[40:41], 21
	v_cmp_lt_i64_e32 vcc, s[42:43], v[174:175]
	s_add_u32 s42, s86, s34
	s_addc_u32 s43, s87, s35
	s_and_b64 s[34:35], vcc, exec
	s_cselect_b32 s41, s43, s51
	s_cselect_b32 s47, s42, s50
	s_ashr_i32 s39, s38, 31
	s_lshl_b64 s[34:35], s[38:39], 21
	s_add_u32 s44, s54, s34
	s_addc_u32 s45, s64, s35
	s_and_b64 s[34:35], vcc, exec
	s_cselect_b32 s39, s45, s53
	s_cselect_b32 s34, s44, s52
	s_add_u32 s35, s52, 0x100
	v_mov_b32_e32 v0, 0
	s_mov_b32 s16, s54
	s_addc_u32 s49, s53, 0
	s_mov_b32 s96, -2
	v_mov_b32_e32 v1, v0
	v_mov_b32_e32 v2, v0
	v_mov_b32_e32 v3, v0
	v_mov_b32_e32 v64, v0
	v_mov_b32_e32 v65, v0
	v_mov_b32_e32 v66, v0
	v_mov_b32_e32 v67, v0
	v_mov_b32_e32 v4, v0
	v_mov_b32_e32 v5, v0
	v_mov_b32_e32 v6, v0
	v_mov_b32_e32 v7, v0
	v_mov_b32_e32 v68, v0
	v_mov_b32_e32 v69, v0
	v_mov_b32_e32 v70, v0
	v_mov_b32_e32 v71, v0
	v_mov_b32_e32 v16, v0
	v_mov_b32_e32 v17, v0
	v_mov_b32_e32 v18, v0
	v_mov_b32_e32 v19, v0
	v_mov_b32_e32 v80, v0
	v_mov_b32_e32 v81, v0
	v_mov_b32_e32 v82, v0
	v_mov_b32_e32 v83, v0
	v_mov_b32_e32 v20, v0
	v_mov_b32_e32 v21, v0
	v_mov_b32_e32 v22, v0
	v_mov_b32_e32 v23, v0
	v_mov_b32_e32 v88, v0
	v_mov_b32_e32 v89, v0
	v_mov_b32_e32 v90, v0
	v_mov_b32_e32 v91, v0
	v_mov_b32_e32 v8, v0
	v_mov_b32_e32 v9, v0
	v_mov_b32_e32 v10, v0
	v_mov_b32_e32 v11, v0
	v_mov_b32_e32 v72, v0
	v_mov_b32_e32 v73, v0
	v_mov_b32_e32 v74, v0
	v_mov_b32_e32 v75, v0
	v_mov_b32_e32 v12, v0
	v_mov_b32_e32 v13, v0
	v_mov_b32_e32 v14, v0
	v_mov_b32_e32 v15, v0
	v_mov_b32_e32 v76, v0
	v_mov_b32_e32 v77, v0
	v_mov_b32_e32 v78, v0
	v_mov_b32_e32 v79, v0
	v_mov_b32_e32 v24, v0
	v_mov_b32_e32 v25, v0
	v_mov_b32_e32 v26, v0
	v_mov_b32_e32 v27, v0
	v_mov_b32_e32 v84, v0
	v_mov_b32_e32 v85, v0
	v_mov_b32_e32 v86, v0
	v_mov_b32_e32 v87, v0
	v_mov_b32_e32 v28, v0
	v_mov_b32_e32 v29, v0
	v_mov_b32_e32 v30, v0
	v_mov_b32_e32 v31, v0
	v_mov_b32_e32 v92, v0
	v_mov_b32_e32 v93, v0
	v_mov_b32_e32 v94, v0
	v_mov_b32_e32 v95, v0
	v_mov_b32_e32 v32, v0
	v_mov_b32_e32 v33, v0
	v_mov_b32_e32 v34, v0
	v_mov_b32_e32 v35, v0
	v_mov_b32_e32 v96, v0
	v_mov_b32_e32 v97, v0
	v_mov_b32_e32 v98, v0
	v_mov_b32_e32 v99, v0
	v_mov_b32_e32 v36, v0
	v_mov_b32_e32 v37, v0
	v_mov_b32_e32 v38, v0
	v_mov_b32_e32 v39, v0
	v_mov_b32_e32 v100, v0
	v_mov_b32_e32 v101, v0
	v_mov_b32_e32 v102, v0
	v_mov_b32_e32 v103, v0
	v_mov_b32_e32 v48, v0
	v_mov_b32_e32 v49, v0
	v_mov_b32_e32 v50, v0
	v_mov_b32_e32 v51, v0
	v_mov_b32_e32 v112, v0
	v_mov_b32_e32 v113, v0
	v_mov_b32_e32 v114, v0
	v_mov_b32_e32 v115, v0
	v_mov_b32_e32 v52, v0
	v_mov_b32_e32 v53, v0
	v_mov_b32_e32 v54, v0
	v_mov_b32_e32 v55, v0
	v_mov_b32_e32 v120, v0
	v_mov_b32_e32 v121, v0
	v_mov_b32_e32 v122, v0
	v_mov_b32_e32 v123, v0
	v_mov_b32_e32 v40, v0
	v_mov_b32_e32 v41, v0
	v_mov_b32_e32 v42, v0
	v_mov_b32_e32 v43, v0
	v_mov_b32_e32 v104, v0
	v_mov_b32_e32 v105, v0
	v_mov_b32_e32 v106, v0
	v_mov_b32_e32 v107, v0
	v_mov_b32_e32 v44, v0
	v_mov_b32_e32 v45, v0
	v_mov_b32_e32 v46, v0
	v_mov_b32_e32 v47, v0
	v_mov_b32_e32 v108, v0
	v_mov_b32_e32 v109, v0
	v_mov_b32_e32 v110, v0
	v_mov_b32_e32 v111, v0
	v_mov_b32_e32 v56, v0
	v_mov_b32_e32 v57, v0
	v_mov_b32_e32 v58, v0
	v_mov_b32_e32 v59, v0
	v_mov_b32_e32 v116, v0
	v_mov_b32_e32 v117, v0
	v_mov_b32_e32 v118, v0
	v_mov_b32_e32 v119, v0
	v_mov_b32_e32 v60, v0
	v_mov_b32_e32 v61, v0
	v_mov_b32_e32 v62, v0
	v_mov_b32_e32 v63, v0
	v_mov_b32_e32 v124, v0
	v_mov_b32_e32 v125, v0
	v_mov_b32_e32 v126, v0
	v_mov_b32_e32 v127, v0
	s_cmpk_lt_u32 s97, 0x100
	s_cbranch_scc1 .Lmy_prio_skip5
	s_setprio 1
.Lmy_prio_skip5:
.LBB0_914:
	ds_read_b128 v[128:131], v187
	ds_read_b128 v[132:135], v187 offset:1024
	ds_read_b128 v[136:139], v187 offset:2048
	ds_read_b128 v[140:143], v187 offset:3072
	ds_read_b128 v[144:147], v188
	ds_read_b128 v[148:151], v188 offset:1024
	ds_read_b128 v[152:155], v188 offset:2048
	ds_read_b128 v[156:159], v188 offset:3072
	s_add_u32 s52, s50, 0x100
	s_addc_u32 s53, s51, 0
	s_cmp_eq_u32 s96, 60
	s_cselect_b32 s57, s41, s53
	s_cselect_b32 s56, s47, s52
	s_cselect_b32 s55, s39, s49
	s_cselect_b32 s54, s34, s35
	v_lshl_add_u64 v[160:161], s[50:51], 0, v[170:171]
	s_add_i32 m0, s67, 0xc000
	ds_read_b128 v[178:181], v189
	ds_read_b128 v[192:195], v189 offset:1024
	ds_read_b128 v[196:199], v189 offset:2048
	ds_read_b128 v[200:203], v189 offset:3072
	ds_read_b128 v[204:207], v189 offset:4096
	ds_read_b128 v[208:211], v189 offset:5120
	ds_read_b128 v[212:215], v189 offset:6144
	ds_read_b128 v[216:219], v189 offset:7168
	global_load_lds_dwordx4 v[160:161], off
	v_lshl_add_u64 v[160:161], s[50:51], 0, v[172:173]
	s_add_i32 m0, s67, 0xe000
	s_nop 0
	global_load_lds_dwordx4 v[160:161], off
	s_waitcnt vmcnt(8)
	s_waitcnt lgkmcnt(0)
	s_barrier
	s_waitcnt lgkmcnt(0)
	v_mfma_f32_16x16x32_bf16 v[124:127], v[128:131], v[178:181], v[124:127]
	v_mfma_f32_16x16x32_bf16 v[60:63], v[136:139], v[178:181], v[60:63]
	v_mfma_f32_16x16x32_bf16 v[116:119], v[128:131], v[196:199], v[116:119]
	v_mfma_f32_16x16x32_bf16 v[56:59], v[136:139], v[196:199], v[56:59]
	v_mfma_f32_16x16x32_bf16 v[108:111], v[128:131], v[204:207], v[108:111]
	v_mfma_f32_16x16x32_bf16 v[44:47], v[136:139], v[204:207], v[44:47]
	v_mfma_f32_16x16x32_bf16 v[104:107], v[128:131], v[212:215], v[104:107]
	v_mfma_f32_16x16x32_bf16 v[40:43], v[136:139], v[212:215], v[40:43]
	v_mfma_f32_16x16x32_bf16 v[124:127], v[132:135], v[192:195], v[124:127]
	v_mfma_f32_16x16x32_bf16 v[60:63], v[140:143], v[192:195], v[60:63]
	v_mfma_f32_16x16x32_bf16 v[116:119], v[132:135], v[200:203], v[116:119]
	v_mfma_f32_16x16x32_bf16 v[56:59], v[140:143], v[200:203], v[56:59]
	v_mfma_f32_16x16x32_bf16 v[108:111], v[132:135], v[208:211], v[108:111]
	v_mfma_f32_16x16x32_bf16 v[44:47], v[140:143], v[208:211], v[44:47]
	v_mfma_f32_16x16x32_bf16 v[104:107], v[132:135], v[216:219], v[104:107]
	v_mfma_f32_16x16x32_bf16 v[40:43], v[140:143], v[216:219], v[40:43]
	v_mfma_f32_16x16x32_bf16 v[120:123], v[144:147], v[178:181], v[120:123]
	v_mfma_f32_16x16x32_bf16 v[52:55], v[152:155], v[178:181], v[52:55]
	v_mfma_f32_16x16x32_bf16 v[112:115], v[144:147], v[196:199], v[112:115]
	v_mfma_f32_16x16x32_bf16 v[48:51], v[152:155], v[196:199], v[48:51]
	v_mfma_f32_16x16x32_bf16 v[100:103], v[144:147], v[204:207], v[100:103]
	v_mfma_f32_16x16x32_bf16 v[36:39], v[152:155], v[204:207], v[36:39]
	v_mfma_f32_16x16x32_bf16 v[96:99], v[144:147], v[212:215], v[96:99]
	v_mfma_f32_16x16x32_bf16 v[32:35], v[152:155], v[212:215], v[32:35]
	v_mfma_f32_16x16x32_bf16 v[120:123], v[148:151], v[192:195], v[120:123]
	v_mfma_f32_16x16x32_bf16 v[52:55], v[156:159], v[192:195], v[52:55]
	v_mfma_f32_16x16x32_bf16 v[112:115], v[148:151], v[200:203], v[112:115]
	v_mfma_f32_16x16x32_bf16 v[48:51], v[156:159], v[200:203], v[48:51]
	v_mfma_f32_16x16x32_bf16 v[100:103], v[148:151], v[208:211], v[100:103]
	v_mfma_f32_16x16x32_bf16 v[36:39], v[156:159], v[208:211], v[36:39]
	v_mfma_f32_16x16x32_bf16 v[96:99], v[148:151], v[216:219], v[96:99]
	v_mfma_f32_16x16x32_bf16 v[32:35], v[156:159], v[216:219], v[32:35]
	s_barrier
	s_add_i32 s50, s92, s66
	v_lshl_add_u64 v[160:161], s[54:55], 0, v[164:165]
	s_mov_b32 m0, s50
	ds_read_b128 v[178:181], v189 offset:16384
	ds_read_b128 v[192:195], v189 offset:17408
	ds_read_b128 v[196:199], v189 offset:18432
	ds_read_b128 v[200:203], v189 offset:19456
	ds_read_b128 v[204:207], v189 offset:20480
	ds_read_b128 v[208:211], v189 offset:21504
	ds_read_b128 v[212:215], v189 offset:22528
	ds_read_b128 v[216:219], v189 offset:23552
	global_load_lds_dwordx4 v[160:161], off
	s_add_i32 m0, s50, 0x2000
	s_add_u32 s50, s54, 0x100000
	v_lshl_add_u64 v[182:183], s[54:55], 0, v[168:169]
	s_addc_u32 s51, s55, 0
	s_add_i32 s97, s93, s66
	global_load_lds_dwordx4 v[182:183], off
	v_lshl_add_u64 v[220:221], s[50:51], 0, v[164:165]
	s_mov_b32 m0, s97
	v_lshl_add_u64 v[222:223], s[56:57], 0, v[166:167]
	global_load_lds_dwordx4 v[220:221], off
	v_lshl_add_u64 v[220:221], s[50:51], 0, v[168:169]
	s_add_i32 m0, s97, 0x2000
	s_nop 0
	global_load_lds_dwordx4 v[220:221], off
	v_lshl_add_u64 v[220:221], s[56:57], 0, v[162:163]
	s_mov_b32 m0, s67
	s_nop 0
	global_load_lds_dwordx4 v[220:221], off
	s_mov_b32 m0, s68
	s_nop 0
	global_load_lds_dwordx4 v[222:223], off
	s_waitcnt vmcnt(8)
	s_waitcnt lgkmcnt(0)
	s_barrier
	s_waitcnt lgkmcnt(0)
	v_mfma_f32_16x16x32_bf16 v[92:95], v[128:131], v[178:181], v[92:95]
	v_mfma_f32_16x16x32_bf16 v[28:31], v[136:139], v[178:181], v[28:31]
	v_mfma_f32_16x16x32_bf16 v[84:87], v[128:131], v[196:199], v[84:87]
	v_mfma_f32_16x16x32_bf16 v[24:27], v[136:139], v[196:199], v[24:27]
	v_mfma_f32_16x16x32_bf16 v[76:79], v[128:131], v[204:207], v[76:79]
	v_mfma_f32_16x16x32_bf16 v[12:15], v[136:139], v[204:207], v[12:15]
	v_mfma_f32_16x16x32_bf16 v[72:75], v[128:131], v[212:215], v[72:75]
	v_mfma_f32_16x16x32_bf16 v[8:11], v[136:139], v[212:215], v[8:11]
	v_mfma_f32_16x16x32_bf16 v[92:95], v[132:135], v[192:195], v[92:95]
	v_mfma_f32_16x16x32_bf16 v[28:31], v[140:143], v[192:195], v[28:31]
	v_mfma_f32_16x16x32_bf16 v[84:87], v[132:135], v[200:203], v[84:87]
	v_mfma_f32_16x16x32_bf16 v[24:27], v[140:143], v[200:203], v[24:27]
	v_mfma_f32_16x16x32_bf16 v[76:79], v[132:135], v[208:211], v[76:79]
	v_mfma_f32_16x16x32_bf16 v[12:15], v[140:143], v[208:211], v[12:15]
	v_mfma_f32_16x16x32_bf16 v[72:75], v[132:135], v[216:219], v[72:75]
	v_mfma_f32_16x16x32_bf16 v[8:11], v[140:143], v[216:219], v[8:11]
	v_mfma_f32_16x16x32_bf16 v[88:91], v[144:147], v[178:181], v[88:91]
	v_mfma_f32_16x16x32_bf16 v[20:23], v[152:155], v[178:181], v[20:23]
	v_mfma_f32_16x16x32_bf16 v[80:83], v[144:147], v[196:199], v[80:83]
	v_mfma_f32_16x16x32_bf16 v[16:19], v[152:155], v[196:199], v[16:19]
	v_mfma_f32_16x16x32_bf16 v[68:71], v[144:147], v[204:207], v[68:71]
	v_mfma_f32_16x16x32_bf16 v[4:7], v[152:155], v[204:207], v[4:7]
	v_mfma_f32_16x16x32_bf16 v[64:67], v[144:147], v[212:215], v[64:67]
	v_mfma_f32_16x16x32_bf16 v[0:3], v[152:155], v[212:215], v[0:3]
	v_mfma_f32_16x16x32_bf16 v[88:91], v[148:151], v[192:195], v[88:91]
	v_mfma_f32_16x16x32_bf16 v[20:23], v[156:159], v[192:195], v[20:23]
	v_mfma_f32_16x16x32_bf16 v[80:83], v[148:151], v[200:203], v[80:83]
	v_mfma_f32_16x16x32_bf16 v[16:19], v[156:159], v[200:203], v[16:19]
	v_mfma_f32_16x16x32_bf16 v[68:71], v[148:151], v[208:211], v[68:71]
	v_mfma_f32_16x16x32_bf16 v[4:7], v[156:159], v[208:211], v[4:7]
	v_mfma_f32_16x16x32_bf16 v[64:67], v[148:151], v[216:219], v[64:67]
	v_mfma_f32_16x16x32_bf16 v[0:3], v[156:159], v[216:219], v[0:3]
	s_barrier
	s_add_i32 s97, 0, 0x18000
	s_add_i32 vcc_lo, 0, 0x1c000
	v_add_u32_e32 v140, s97, v184
	v_add_u32_e32 v156, vcc_lo, v184
	ds_read_b128 v[128:131], v140
	ds_read_b128 v[132:135], v140 offset:1024
	ds_read_b128 v[136:139], v140 offset:2048
	ds_read_b128 v[140:143], v140 offset:3072
	ds_read_b128 v[144:147], v156
	ds_read_b128 v[148:151], v156 offset:1024
	ds_read_b128 v[152:155], v156 offset:2048
	ds_read_b128 v[156:159], v156 offset:3072
	s_add_u32 s50, s56, 0x100000
	s_addc_u32 s51, s57, 0
	s_mov_b32 m0, s69
	v_lshl_add_u64 v[226:227], s[50:51], 0, v[162:163]
	ds_read_b128 v[178:181], v189 offset:32768
	ds_read_b128 v[192:195], v189 offset:33792
	ds_read_b128 v[196:199], v189 offset:34816
	ds_read_b128 v[200:203], v189 offset:35840
	ds_read_b128 v[204:207], v189 offset:36864
	ds_read_b128 v[208:211], v189 offset:37888
	ds_read_b128 v[212:215], v189 offset:38912
	ds_read_b128 v[216:219], v189 offset:39936
	global_load_lds_dwordx4 v[226:227], off
	v_lshl_add_u64 v[226:227], s[50:51], 0, v[166:167]
	s_mov_b32 m0, s76
	s_nop 0
	global_load_lds_dwordx4 v[226:227], off
	s_waitcnt vmcnt(8)
	s_waitcnt lgkmcnt(0)
	s_barrier
	s_waitcnt lgkmcnt(0)
	v_mfma_f32_16x16x32_bf16 v[124:127], v[128:131], v[178:181], v[124:127]
	v_mfma_f32_16x16x32_bf16 v[60:63], v[136:139], v[178:181], v[60:63]
	v_mfma_f32_16x16x32_bf16 v[116:119], v[128:131], v[196:199], v[116:119]
	v_mfma_f32_16x16x32_bf16 v[56:59], v[136:139], v[196:199], v[56:59]
	v_mfma_f32_16x16x32_bf16 v[108:111], v[128:131], v[204:207], v[108:111]
	v_mfma_f32_16x16x32_bf16 v[44:47], v[136:139], v[204:207], v[44:47]
	v_mfma_f32_16x16x32_bf16 v[104:107], v[128:131], v[212:215], v[104:107]
	v_mfma_f32_16x16x32_bf16 v[40:43], v[136:139], v[212:215], v[40:43]
	v_mfma_f32_16x16x32_bf16 v[124:127], v[132:135], v[192:195], v[124:127]
	v_mfma_f32_16x16x32_bf16 v[60:63], v[140:143], v[192:195], v[60:63]
	v_mfma_f32_16x16x32_bf16 v[116:119], v[132:135], v[200:203], v[116:119]
	v_mfma_f32_16x16x32_bf16 v[56:59], v[140:143], v[200:203], v[56:59]
	v_mfma_f32_16x16x32_bf16 v[108:111], v[132:135], v[208:211], v[108:111]
	v_mfma_f32_16x16x32_bf16 v[44:47], v[140:143], v[208:211], v[44:47]
	v_mfma_f32_16x16x32_bf16 v[104:107], v[132:135], v[216:219], v[104:107]
	v_mfma_f32_16x16x32_bf16 v[40:43], v[140:143], v[216:219], v[40:43]
	v_mfma_f32_16x16x32_bf16 v[120:123], v[144:147], v[178:181], v[120:123]
	v_mfma_f32_16x16x32_bf16 v[52:55], v[152:155], v[178:181], v[52:55]
	v_mfma_f32_16x16x32_bf16 v[112:115], v[144:147], v[196:199], v[112:115]
	v_mfma_f32_16x16x32_bf16 v[48:51], v[152:155], v[196:199], v[48:51]
	v_mfma_f32_16x16x32_bf16 v[100:103], v[144:147], v[204:207], v[100:103]
	v_mfma_f32_16x16x32_bf16 v[36:39], v[152:155], v[204:207], v[36:39]
	v_mfma_f32_16x16x32_bf16 v[96:99], v[144:147], v[212:215], v[96:99]
	v_mfma_f32_16x16x32_bf16 v[32:35], v[152:155], v[212:215], v[32:35]
	v_mfma_f32_16x16x32_bf16 v[120:123], v[148:151], v[192:195], v[120:123]
	v_mfma_f32_16x16x32_bf16 v[52:55], v[156:159], v[192:195], v[52:55]
	v_mfma_f32_16x16x32_bf16 v[112:115], v[148:151], v[200:203], v[112:115]
	v_mfma_f32_16x16x32_bf16 v[48:51], v[156:159], v[200:203], v[48:51]
	v_mfma_f32_16x16x32_bf16 v[100:103], v[148:151], v[208:211], v[100:103]
	v_mfma_f32_16x16x32_bf16 v[36:39], v[156:159], v[208:211], v[36:39]
	v_mfma_f32_16x16x32_bf16 v[96:99], v[148:151], v[216:219], v[96:99]
	v_mfma_f32_16x16x32_bf16 v[32:35], v[156:159], v[216:219], v[32:35]
	s_barrier
	s_add_i32 s50, s97, s66
	v_lshl_add_u64 v[160:161], v[160:161], 0, s[10:11]
	s_mov_b32 m0, s50
	ds_read_b128 v[178:181], v189 offset:49152
	ds_read_b128 v[192:195], v189 offset:50176
	ds_read_b128 v[196:199], v189 offset:51200
	ds_read_b128 v[200:203], v189 offset:52224
	ds_read_b128 v[204:207], v189 offset:53248
	ds_read_b128 v[208:211], v189 offset:54272
	ds_read_b128 v[212:215], v189 offset:55296
	ds_read_b128 v[216:219], v189 offset:56320
	global_load_lds_dwordx4 v[160:161], off
	s_add_i32 m0, s50, 0x2000
	s_add_u32 s50, s54, 0x100080
	v_lshl_add_u64 v[160:161], v[182:183], 0, s[10:11]
	s_addc_u32 s51, s55, 0
	s_add_i32 s54, vcc_lo, s66
	global_load_lds_dwordx4 v[160:161], off
	v_lshl_add_u64 v[160:161], s[50:51], 0, v[164:165]
	s_mov_b32 m0, s54
	s_nop 0
	global_load_lds_dwordx4 v[160:161], off
	v_lshl_add_u64 v[160:161], s[50:51], 0, v[168:169]
	s_add_i32 m0, s54, 0x2000
	s_nop 0
	global_load_lds_dwordx4 v[160:161], off
	v_lshl_add_u64 v[160:161], v[220:221], 0, s[10:11]
	s_mov_b32 m0, s84
	s_nop 0
	global_load_lds_dwordx4 v[160:161], off
	v_lshl_add_u64 v[160:161], v[222:223], 0, s[10:11]
	s_mov_b32 m0, s85
	s_nop 0
	global_load_lds_dwordx4 v[160:161], off
	s_waitcnt vmcnt(8)
	s_waitcnt lgkmcnt(0)
	s_barrier
	s_waitcnt lgkmcnt(0)
	v_mfma_f32_16x16x32_bf16 v[92:95], v[128:131], v[178:181], v[92:95]
	v_mfma_f32_16x16x32_bf16 v[28:31], v[136:139], v[178:181], v[28:31]
	v_mfma_f32_16x16x32_bf16 v[84:87], v[128:131], v[196:199], v[84:87]
	v_mfma_f32_16x16x32_bf16 v[24:27], v[136:139], v[196:199], v[24:27]
	v_mfma_f32_16x16x32_bf16 v[76:79], v[128:131], v[204:207], v[76:79]
	v_mfma_f32_16x16x32_bf16 v[12:15], v[136:139], v[204:207], v[12:15]
	v_mfma_f32_16x16x32_bf16 v[72:75], v[128:131], v[212:215], v[72:75]
	v_mfma_f32_16x16x32_bf16 v[8:11], v[136:139], v[212:215], v[8:11]
	v_mfma_f32_16x16x32_bf16 v[92:95], v[132:135], v[192:195], v[92:95]
	v_mfma_f32_16x16x32_bf16 v[28:31], v[140:143], v[192:195], v[28:31]
	v_mfma_f32_16x16x32_bf16 v[84:87], v[132:135], v[200:203], v[84:87]
	v_mfma_f32_16x16x32_bf16 v[24:27], v[140:143], v[200:203], v[24:27]
	v_mfma_f32_16x16x32_bf16 v[76:79], v[132:135], v[208:211], v[76:79]
	v_mfma_f32_16x16x32_bf16 v[12:15], v[140:143], v[208:211], v[12:15]
	v_mfma_f32_16x16x32_bf16 v[72:75], v[132:135], v[216:219], v[72:75]
	v_mfma_f32_16x16x32_bf16 v[8:11], v[140:143], v[216:219], v[8:11]
	v_mfma_f32_16x16x32_bf16 v[88:91], v[144:147], v[178:181], v[88:91]
	v_mfma_f32_16x16x32_bf16 v[20:23], v[152:155], v[178:181], v[20:23]
	v_mfma_f32_16x16x32_bf16 v[80:83], v[144:147], v[196:199], v[80:83]
	v_mfma_f32_16x16x32_bf16 v[16:19], v[152:155], v[196:199], v[16:19]
	v_mfma_f32_16x16x32_bf16 v[68:71], v[144:147], v[204:207], v[68:71]
	v_mfma_f32_16x16x32_bf16 v[4:7], v[152:155], v[204:207], v[4:7]
	v_mfma_f32_16x16x32_bf16 v[64:67], v[144:147], v[212:215], v[64:67]
	v_mfma_f32_16x16x32_bf16 v[0:3], v[152:155], v[212:215], v[0:3]
	v_mfma_f32_16x16x32_bf16 v[88:91], v[148:151], v[192:195], v[88:91]
	v_mfma_f32_16x16x32_bf16 v[20:23], v[156:159], v[192:195], v[20:23]
	v_mfma_f32_16x16x32_bf16 v[80:83], v[148:151], v[200:203], v[80:83]
	v_mfma_f32_16x16x32_bf16 v[16:19], v[156:159], v[200:203], v[16:19]
	v_mfma_f32_16x16x32_bf16 v[68:71], v[148:151], v[208:211], v[68:71]
	v_mfma_f32_16x16x32_bf16 v[4:7], v[156:159], v[208:211], v[4:7]
	v_mfma_f32_16x16x32_bf16 v[64:67], v[148:151], v[216:219], v[64:67]
	v_mfma_f32_16x16x32_bf16 v[0:3], v[156:159], v[216:219], v[0:3]
	s_barrier
	s_add_i32 s96, s96, 2
	s_add_u32 s35, s35, 0x100
	s_addc_u32 s49, s49, 0
	s_cmp_gt_u32 s96, 61
	s_mov_b64 s[50:51], s[52:53]
	s_cbranch_scc0 .LBB0_914
	s_setprio 0
	s_lshl_b32 s34, s46, 2
	v_lshl_or_b32 v178, s48, 7, v186
	s_add_i32 s34, s34, s65
	v_ashrrev_i32_e32 v179, 31, v178
	s_mul_hi_i32 s35, s34, 0x30000
	s_mul_i32 s39, s34, 0x30000
	s_and_saveexec_b64 s[48:49], s[0:1]
	s_cbranch_execz .LBB0_917
	s_add_u32 s50, s79, s39
	s_addc_u32 s51, s81, s35
	v_lshl_add_u64 v[132:133], v[178:179], 1, s[50:51]
	v_add_co_u32_e32 v134, vcc, s78, v132
	s_nop 2
	v_cvt_pk_bf16_f32 v128, v124, v125
	s_nop 2
	v_cvt_pk_bf16_f32 v129, v126, v127
	s_nop 2
	v_cvt_pk_bf16_f32 v130, v60, v61
	s_nop 2
	v_cvt_pk_bf16_f32 v131, v62, v63
	s_nop 1
	v_addc_co_u32_e32 v135, vcc, 0, v133, vcc
	s_mov_b32 s17, 0xc000
	global_store_dwordx4 v[132:133], v[128:131], off
	s_nop 1
	s_nop 2
	v_cvt_pk_bf16_f32 v128, v120, v121
	s_nop 2
	v_cvt_pk_bf16_f32 v129, v122, v123
	s_nop 2
	v_cvt_pk_bf16_f32 v130, v52, v53
	s_nop 2
	v_cvt_pk_bf16_f32 v131, v54, v55
	global_store_dwordx4 v[134:135], v[128:131], off
	v_add_co_u32_e32 v134, vcc, s17, v132
	s_nop 0
	s_nop 2
	v_cvt_pk_bf16_f32 v128, v116, v117
	s_nop 2
	v_cvt_pk_bf16_f32 v129, v118, v119
	s_nop 2
	v_cvt_pk_bf16_f32 v130, v56, v57
	s_nop 2
	v_cvt_pk_bf16_f32 v131, v58, v59
	s_nop 0
	v_addc_co_u32_e32 v135, vcc, 0, v133, vcc
	v_add_co_u32_e32 v132, vcc, 0x12000, v132
	global_store_dwordx4 v[134:135], v[128:131], off
	s_nop 0
	v_addc_co_u32_e32 v133, vcc, 0, v133, vcc
	s_nop 2
	v_cvt_pk_bf16_f32 v128, v112, v113
	s_nop 2
	v_cvt_pk_bf16_f32 v129, v114, v115
	s_nop 2
	v_cvt_pk_bf16_f32 v130, v48, v49
	s_nop 2
	v_cvt_pk_bf16_f32 v131, v50, v51
	global_store_dwordx4 v[132:133], v[128:131], off

.LBB0_1076:
	s_add_u32 s34, s28, 0x100
	v_mov_b32_e32 v0, 0
	s_addc_u32 s35, s29, 0
	s_mov_b32 s53, -2
	v_mov_b32_e32 v1, v0
	v_mov_b32_e32 v2, v0
	v_mov_b32_e32 v3, v0
	v_mov_b32_e32 v4, v0
	v_mov_b32_e32 v5, v0
	v_mov_b32_e32 v6, v0
	v_mov_b32_e32 v7, v0
	v_mov_b32_e32 v16, v0
	v_mov_b32_e32 v17, v0
	v_mov_b32_e32 v18, v0
	v_mov_b32_e32 v19, v0
	v_mov_b32_e32 v20, v0
	v_mov_b32_e32 v21, v0
	v_mov_b32_e32 v22, v0
	v_mov_b32_e32 v23, v0
	v_mov_b32_e32 v32, v0
	v_mov_b32_e32 v33, v0
	v_mov_b32_e32 v34, v0
	v_mov_b32_e32 v35, v0
	v_mov_b32_e32 v36, v0
	v_mov_b32_e32 v37, v0
	v_mov_b32_e32 v38, v0
	v_mov_b32_e32 v39, v0
	v_mov_b32_e32 v48, v0
	v_mov_b32_e32 v49, v0
	v_mov_b32_e32 v50, v0
	v_mov_b32_e32 v51, v0
	v_mov_b32_e32 v52, v0
	v_mov_b32_e32 v53, v0
	v_mov_b32_e32 v54, v0
	v_mov_b32_e32 v55, v0
	v_mov_b32_e32 v8, v0
	v_mov_b32_e32 v9, v0
	v_mov_b32_e32 v10, v0
	v_mov_b32_e32 v11, v0
	v_mov_b32_e32 v12, v0
	v_mov_b32_e32 v13, v0
	v_mov_b32_e32 v14, v0
	v_mov_b32_e32 v15, v0
	v_mov_b32_e32 v24, v0
	v_mov_b32_e32 v25, v0
	v_mov_b32_e32 v26, v0
	v_mov_b32_e32 v27, v0
	v_mov_b32_e32 v28, v0
	v_mov_b32_e32 v29, v0
	v_mov_b32_e32 v30, v0
	v_mov_b32_e32 v31, v0
	v_mov_b32_e32 v40, v0
	v_mov_b32_e32 v41, v0
	v_mov_b32_e32 v42, v0
	v_mov_b32_e32 v43, v0
	v_mov_b32_e32 v44, v0
	v_mov_b32_e32 v45, v0
	v_mov_b32_e32 v46, v0
	v_mov_b32_e32 v47, v0
	v_mov_b32_e32 v56, v0
	v_mov_b32_e32 v57, v0
	v_mov_b32_e32 v58, v0
	v_mov_b32_e32 v59, v0
	v_mov_b32_e32 v60, v0
	v_mov_b32_e32 v61, v0
	v_mov_b32_e32 v62, v0
	v_mov_b32_e32 v63, v0
	v_mov_b32_e32 v64, v0
	v_mov_b32_e32 v65, v0
	v_mov_b32_e32 v66, v0
	v_mov_b32_e32 v67, v0
	v_mov_b32_e32 v68, v0
	v_mov_b32_e32 v69, v0
	v_mov_b32_e32 v70, v0
	v_mov_b32_e32 v71, v0
	v_mov_b32_e32 v80, v0
	v_mov_b32_e32 v81, v0
	v_mov_b32_e32 v82, v0
	v_mov_b32_e32 v83, v0
	v_mov_b32_e32 v84, v0
	v_mov_b32_e32 v85, v0
	v_mov_b32_e32 v86, v0
	v_mov_b32_e32 v87, v0
	v_mov_b32_e32 v96, v0
	v_mov_b32_e32 v97, v0
	v_mov_b32_e32 v98, v0
	v_mov_b32_e32 v99, v0
	v_mov_b32_e32 v100, v0
	v_mov_b32_e32 v101, v0
	v_mov_b32_e32 v102, v0
	v_mov_b32_e32 v103, v0
	v_mov_b32_e32 v112, v0
	v_mov_b32_e32 v113, v0
	v_mov_b32_e32 v114, v0
	v_mov_b32_e32 v115, v0
	v_mov_b32_e32 v116, v0
	v_mov_b32_e32 v117, v0
	v_mov_b32_e32 v118, v0
	v_mov_b32_e32 v119, v0
	v_mov_b32_e32 v72, v0
	v_mov_b32_e32 v73, v0
	v_mov_b32_e32 v74, v0
	v_mov_b32_e32 v75, v0
	v_mov_b32_e32 v76, v0
	v_mov_b32_e32 v77, v0
	v_mov_b32_e32 v78, v0
	v_mov_b32_e32 v79, v0
	v_mov_b32_e32 v88, v0
	v_mov_b32_e32 v89, v0
	v_mov_b32_e32 v90, v0
	v_mov_b32_e32 v91, v0
	v_mov_b32_e32 v92, v0
	v_mov_b32_e32 v93, v0
	v_mov_b32_e32 v94, v0
	v_mov_b32_e32 v95, v0
	v_mov_b32_e32 v104, v0
	v_mov_b32_e32 v105, v0
	v_mov_b32_e32 v106, v0
	v_mov_b32_e32 v107, v0
	v_mov_b32_e32 v108, v0
	v_mov_b32_e32 v109, v0
	v_mov_b32_e32 v110, v0
	v_mov_b32_e32 v111, v0
	v_mov_b32_e32 v120, v0
	v_mov_b32_e32 v121, v0
	v_mov_b32_e32 v122, v0
	v_mov_b32_e32 v123, v0
	v_mov_b32_e32 v124, v0
	v_mov_b32_e32 v125, v0
	v_mov_b32_e32 v126, v0
	v_mov_b32_e32 v127, v0
	s_cmpk_lt_u32 s97, 0x100
	s_cbranch_scc1 .Lmy_prio_skip6
	s_setprio 1
.Lmy_prio_skip6:
.LBB0_1077:
	ds_read_b128 v[144:147], v153
	ds_read_b128 v[156:159], v153 offset:1024
	ds_read_b128 v[160:163], v153 offset:2048
	ds_read_b128 v[164:167], v153 offset:3072
	ds_read_b128 v[168:171], v154
	ds_read_b128 v[172:175], v154 offset:1024
	ds_read_b128 v[176:179], v154 offset:2048
	ds_read_b128 v[180:183], v154 offset:3072
	s_add_u32 s28, s26, 0x100
	s_addc_u32 s29, s27, 0
	s_cmpk_eq_i32 s53, 0xbc
	s_cselect_b32 s37, s3, s29
	s_cselect_b32 s36, s2, s28
	s_cselect_b32 s31, s25, s35
	s_cselect_b32 s30, s24, s34
	v_lshl_add_u64 v[148:149], s[26:27], 0, v[136:137]
	s_add_i32 m0, s39, 0xc000
	ds_read_b128 v[184:187], v155
	ds_read_b128 v[188:191], v155 offset:1024
	ds_read_b128 v[192:195], v155 offset:2048
	ds_read_b128 v[196:199], v155 offset:3072
	ds_read_b128 v[200:203], v155 offset:4096
	ds_read_b128 v[204:207], v155 offset:5120
	ds_read_b128 v[208:211], v155 offset:6144
	ds_read_b128 v[212:215], v155 offset:7168
	global_load_lds_dwordx4 v[148:149], off
	v_lshl_add_u64 v[148:149], s[26:27], 0, v[138:139]
	s_add_i32 m0, s39, 0xe000
	s_nop 0
	global_load_lds_dwordx4 v[148:149], off
	s_waitcnt vmcnt(8)
	s_waitcnt lgkmcnt(0)
	s_barrier
	s_waitcnt lgkmcnt(0)
	v_mfma_f32_16x16x32_bf16 v[124:127], v[144:147], v[184:187], v[124:127]
	v_mfma_f32_16x16x32_bf16 v[120:123], v[160:163], v[184:187], v[120:123]
	v_mfma_f32_16x16x32_bf16 v[108:111], v[144:147], v[192:195], v[108:111]
	v_mfma_f32_16x16x32_bf16 v[104:107], v[160:163], v[192:195], v[104:107]
	v_mfma_f32_16x16x32_bf16 v[92:95], v[144:147], v[200:203], v[92:95]
	v_mfma_f32_16x16x32_bf16 v[88:91], v[160:163], v[200:203], v[88:91]
	v_mfma_f32_16x16x32_bf16 v[76:79], v[144:147], v[208:211], v[76:79]
	v_mfma_f32_16x16x32_bf16 v[72:75], v[160:163], v[208:211], v[72:75]
	v_mfma_f32_16x16x32_bf16 v[124:127], v[156:159], v[188:191], v[124:127]
	v_mfma_f32_16x16x32_bf16 v[120:123], v[164:167], v[188:191], v[120:123]
	v_mfma_f32_16x16x32_bf16 v[108:111], v[156:159], v[196:199], v[108:111]
	v_mfma_f32_16x16x32_bf16 v[104:107], v[164:167], v[196:199], v[104:107]
	v_mfma_f32_16x16x32_bf16 v[92:95], v[156:159], v[204:207], v[92:95]
	v_mfma_f32_16x16x32_bf16 v[88:91], v[164:167], v[204:207], v[88:91]
	v_mfma_f32_16x16x32_bf16 v[76:79], v[156:159], v[212:215], v[76:79]
	v_mfma_f32_16x16x32_bf16 v[72:75], v[164:167], v[212:215], v[72:75]
	v_mfma_f32_16x16x32_bf16 v[116:119], v[168:171], v[184:187], v[116:119]
	v_mfma_f32_16x16x32_bf16 v[112:115], v[176:179], v[184:187], v[112:115]
	v_mfma_f32_16x16x32_bf16 v[100:103], v[168:171], v[192:195], v[100:103]
	v_mfma_f32_16x16x32_bf16 v[96:99], v[176:179], v[192:195], v[96:99]
	v_mfma_f32_16x16x32_bf16 v[84:87], v[168:171], v[200:203], v[84:87]
	v_mfma_f32_16x16x32_bf16 v[80:83], v[176:179], v[200:203], v[80:83]
	v_mfma_f32_16x16x32_bf16 v[68:71], v[168:171], v[208:211], v[68:71]
	v_mfma_f32_16x16x32_bf16 v[64:67], v[176:179], v[208:211], v[64:67]
	v_mfma_f32_16x16x32_bf16 v[116:119], v[172:175], v[188:191], v[116:119]
	v_mfma_f32_16x16x32_bf16 v[112:115], v[180:183], v[188:191], v[112:115]
	v_mfma_f32_16x16x32_bf16 v[100:103], v[172:175], v[196:199], v[100:103]
	v_mfma_f32_16x16x32_bf16 v[96:99], v[180:183], v[196:199], v[96:99]
	v_mfma_f32_16x16x32_bf16 v[84:87], v[172:175], v[204:207], v[84:87]
	v_mfma_f32_16x16x32_bf16 v[80:83], v[180:183], v[204:207], v[80:83]
	v_mfma_f32_16x16x32_bf16 v[68:71], v[172:175], v[212:215], v[68:71]
	v_mfma_f32_16x16x32_bf16 v[64:67], v[180:183], v[212:215], v[64:67]
	s_barrier
	s_add_i32 s26, s47, s38
	v_lshl_add_u64 v[148:149], s[30:31], 0, v[130:131]
	s_mov_b32 m0, s26
	ds_read_b128 v[184:187], v155 offset:16384
	ds_read_b128 v[188:191], v155 offset:17408
	ds_read_b128 v[192:195], v155 offset:18432
	ds_read_b128 v[196:199], v155 offset:19456
	ds_read_b128 v[200:203], v155 offset:20480
	ds_read_b128 v[204:207], v155 offset:21504
	ds_read_b128 v[208:211], v155 offset:22528
	ds_read_b128 v[212:215], v155 offset:23552
	global_load_lds_dwordx4 v[148:149], off
	s_add_i32 m0, s26, 0x2000
	s_add_u32 s26, s30, 0x300000
	v_lshl_add_u64 v[216:217], s[30:31], 0, v[134:135]
	s_addc_u32 s27, s31, 0
	s_add_i32 s54, s48, s38
	global_load_lds_dwordx4 v[216:217], off
	v_lshl_add_u64 v[218:219], s[26:27], 0, v[130:131]
	s_mov_b32 m0, s54
	v_lshl_add_u64 v[220:221], s[36:37], 0, v[132:133]
	global_load_lds_dwordx4 v[218:219], off
	v_lshl_add_u64 v[218:219], s[26:27], 0, v[134:135]
	s_add_i32 m0, s54, 0x2000
	s_nop 0
	global_load_lds_dwordx4 v[218:219], off
	v_lshl_add_u64 v[218:219], s[36:37], 0, v[128:129]
	s_mov_b32 m0, s39
	s_nop 0
	global_load_lds_dwordx4 v[218:219], off
	s_mov_b32 m0, s40
	s_nop 0
	global_load_lds_dwordx4 v[220:221], off
	s_waitcnt vmcnt(8)
	s_waitcnt lgkmcnt(0)
	s_barrier
	s_waitcnt lgkmcnt(0)
	v_mfma_f32_16x16x32_bf16 v[60:63], v[144:147], v[184:187], v[60:63]
	v_mfma_f32_16x16x32_bf16 v[56:59], v[160:163], v[184:187], v[56:59]
	v_mfma_f32_16x16x32_bf16 v[44:47], v[144:147], v[192:195], v[44:47]
	v_mfma_f32_16x16x32_bf16 v[40:43], v[160:163], v[192:195], v[40:43]
	v_mfma_f32_16x16x32_bf16 v[28:31], v[144:147], v[200:203], v[28:31]
	v_mfma_f32_16x16x32_bf16 v[24:27], v[160:163], v[200:203], v[24:27]
	v_mfma_f32_16x16x32_bf16 v[12:15], v[144:147], v[208:211], v[12:15]
	v_mfma_f32_16x16x32_bf16 v[8:11], v[160:163], v[208:211], v[8:11]
	v_mfma_f32_16x16x32_bf16 v[60:63], v[156:159], v[188:191], v[60:63]
	v_mfma_f32_16x16x32_bf16 v[56:59], v[164:167], v[188:191], v[56:59]
	v_mfma_f32_16x16x32_bf16 v[44:47], v[156:159], v[196:199], v[44:47]
	v_mfma_f32_16x16x32_bf16 v[40:43], v[164:167], v[196:199], v[40:43]
	v_mfma_f32_16x16x32_bf16 v[28:31], v[156:159], v[204:207], v[28:31]
	v_mfma_f32_16x16x32_bf16 v[24:27], v[164:167], v[204:207], v[24:27]
	v_mfma_f32_16x16x32_bf16 v[12:15], v[156:159], v[212:215], v[12:15]
	v_mfma_f32_16x16x32_bf16 v[8:11], v[164:167], v[212:215], v[8:11]
	v_mfma_f32_16x16x32_bf16 v[52:55], v[168:171], v[184:187], v[52:55]
	v_mfma_f32_16x16x32_bf16 v[48:51], v[176:179], v[184:187], v[48:51]
	v_mfma_f32_16x16x32_bf16 v[36:39], v[168:171], v[192:195], v[36:39]
	v_mfma_f32_16x16x32_bf16 v[32:35], v[176:179], v[192:195], v[32:35]
	v_mfma_f32_16x16x32_bf16 v[20:23], v[168:171], v[200:203], v[20:23]
	v_mfma_f32_16x16x32_bf16 v[16:19], v[176:179], v[200:203], v[16:19]
	v_mfma_f32_16x16x32_bf16 v[4:7], v[168:171], v[208:211], v[4:7]
	v_mfma_f32_16x16x32_bf16 v[0:3], v[176:179], v[208:211], v[0:3]
	v_mfma_f32_16x16x32_bf16 v[52:55], v[172:175], v[188:191], v[52:55]
	v_mfma_f32_16x16x32_bf16 v[48:51], v[180:183], v[188:191], v[48:51]
	v_mfma_f32_16x16x32_bf16 v[36:39], v[172:175], v[196:199], v[36:39]
	v_mfma_f32_16x16x32_bf16 v[32:35], v[180:183], v[196:199], v[32:35]
	v_mfma_f32_16x16x32_bf16 v[20:23], v[172:175], v[204:207], v[20:23]
	v_mfma_f32_16x16x32_bf16 v[16:19], v[180:183], v[204:207], v[16:19]
	v_mfma_f32_16x16x32_bf16 v[4:7], v[172:175], v[212:215], v[4:7]
	v_mfma_f32_16x16x32_bf16 v[0:3], v[180:183], v[212:215], v[0:3]
	s_barrier
	s_add_i32 s54, 0, 0x18000
	s_add_i32 s55, 0, 0x1c000
	v_add_u32_e32 v164, s54, v151
	v_add_u32_e32 v180, s55, v151
	ds_read_b128 v[144:147], v164
	ds_read_b128 v[156:159], v164 offset:1024
	ds_read_b128 v[160:163], v164 offset:2048
	ds_read_b128 v[164:167], v164 offset:3072
	ds_read_b128 v[168:171], v180
	ds_read_b128 v[172:175], v180 offset:1024
	ds_read_b128 v[176:179], v180 offset:2048
	ds_read_b128 v[180:183], v180 offset:3072
	s_add_u32 s26, s36, 0x300000
	s_addc_u32 s27, s37, 0
	s_mov_b32 m0, s41
	v_lshl_add_u64 v[222:223], s[26:27], 0, v[128:129]
	ds_read_b128 v[184:187], v155 offset:32768
	ds_read_b128 v[188:191], v155 offset:33792
	ds_read_b128 v[192:195], v155 offset:34816
	ds_read_b128 v[196:199], v155 offset:35840
	ds_read_b128 v[200:203], v155 offset:36864
	ds_read_b128 v[204:207], v155 offset:37888
	ds_read_b128 v[208:211], v155 offset:38912
	ds_read_b128 v[212:215], v155 offset:39936
	global_load_lds_dwordx4 v[222:223], off
	v_lshl_add_u64 v[222:223], s[26:27], 0, v[132:133]
	s_mov_b32 m0, s42
	s_nop 0
	global_load_lds_dwordx4 v[222:223], off
	s_waitcnt vmcnt(8)
	s_waitcnt lgkmcnt(0)
	s_barrier
	s_waitcnt lgkmcnt(0)
	v_mfma_f32_16x16x32_bf16 v[124:127], v[144:147], v[184:187], v[124:127]
	v_mfma_f32_16x16x32_bf16 v[120:123], v[160:163], v[184:187], v[120:123]
	v_mfma_f32_16x16x32_bf16 v[108:111], v[144:147], v[192:195], v[108:111]
	v_mfma_f32_16x16x32_bf16 v[104:107], v[160:163], v[192:195], v[104:107]
	v_mfma_f32_16x16x32_bf16 v[92:95], v[144:147], v[200:203], v[92:95]
	v_mfma_f32_16x16x32_bf16 v[88:91], v[160:163], v[200:203], v[88:91]
	v_mfma_f32_16x16x32_bf16 v[76:79], v[144:147], v[208:211], v[76:79]
	v_mfma_f32_16x16x32_bf16 v[72:75], v[160:163], v[208:211], v[72:75]
	v_mfma_f32_16x16x32_bf16 v[124:127], v[156:159], v[188:191], v[124:127]
	v_mfma_f32_16x16x32_bf16 v[120:123], v[164:167], v[188:191], v[120:123]
	v_mfma_f32_16x16x32_bf16 v[108:111], v[156:159], v[196:199], v[108:111]
	v_mfma_f32_16x16x32_bf16 v[104:107], v[164:167], v[196:199], v[104:107]
	v_mfma_f32_16x16x32_bf16 v[92:95], v[156:159], v[204:207], v[92:95]
	v_mfma_f32_16x16x32_bf16 v[88:91], v[164:167], v[204:207], v[88:91]
	v_mfma_f32_16x16x32_bf16 v[76:79], v[156:159], v[212:215], v[76:79]
	v_mfma_f32_16x16x32_bf16 v[72:75], v[164:167], v[212:215], v[72:75]
	v_mfma_f32_16x16x32_bf16 v[116:119], v[168:171], v[184:187], v[116:119]
	v_mfma_f32_16x16x32_bf16 v[112:115], v[176:179], v[184:187], v[112:115]
	v_mfma_f32_16x16x32_bf16 v[100:103], v[168:171], v[192:195], v[100:103]
	v_mfma_f32_16x16x32_bf16 v[96:99], v[176:179], v[192:195], v[96:99]
	v_mfma_f32_16x16x32_bf16 v[84:87], v[168:171], v[200:203], v[84:87]
	v_mfma_f32_16x16x32_bf16 v[80:83], v[176:179], v[200:203], v[80:83]
	v_mfma_f32_16x16x32_bf16 v[68:71], v[168:171], v[208:211], v[68:71]
	v_mfma_f32_16x16x32_bf16 v[64:67], v[176:179], v[208:211], v[64:67]
	v_mfma_f32_16x16x32_bf16 v[116:119], v[172:175], v[188:191], v[116:119]
	v_mfma_f32_16x16x32_bf16 v[112:115], v[180:183], v[188:191], v[112:115]
	v_mfma_f32_16x16x32_bf16 v[100:103], v[172:175], v[196:199], v[100:103]
	v_mfma_f32_16x16x32_bf16 v[96:99], v[180:183], v[196:199], v[96:99]
	v_mfma_f32_16x16x32_bf16 v[84:87], v[172:175], v[204:207], v[84:87]
	v_mfma_f32_16x16x32_bf16 v[80:83], v[180:183], v[204:207], v[80:83]
	v_mfma_f32_16x16x32_bf16 v[68:71], v[172:175], v[212:215], v[68:71]
	v_mfma_f32_16x16x32_bf16 v[64:67], v[180:183], v[212:215], v[64:67]
	s_barrier
	s_add_i32 s26, s54, s38
	v_lshl_add_u64 v[148:149], v[148:149], 0, s[10:11]
	s_mov_b32 m0, s26
	ds_read_b128 v[184:187], v155 offset:49152
	ds_read_b128 v[188:191], v155 offset:50176
	ds_read_b128 v[192:195], v155 offset:51200
	ds_read_b128 v[196:199], v155 offset:52224
	ds_read_b128 v[200:203], v155 offset:53248
	ds_read_b128 v[204:207], v155 offset:54272
	ds_read_b128 v[208:211], v155 offset:55296
	ds_read_b128 v[212:215], v155 offset:56320
	global_load_lds_dwordx4 v[148:149], off
	s_add_i32 m0, s26, 0x2000
	s_add_u32 s26, s30, 0x300080
	v_lshl_add_u64 v[148:149], v[216:217], 0, s[10:11]
	s_addc_u32 s27, s31, 0
	s_add_i32 s30, s55, s38
	global_load_lds_dwordx4 v[148:149], off
	v_lshl_add_u64 v[148:149], s[26:27], 0, v[130:131]
	s_mov_b32 m0, s30
	s_nop 0
	global_load_lds_dwordx4 v[148:149], off
	v_lshl_add_u64 v[148:149], s[26:27], 0, v[134:135]
	s_add_i32 m0, s30, 0x2000
	s_nop 0
	global_load_lds_dwordx4 v[148:149], off
	v_lshl_add_u64 v[148:149], v[218:219], 0, s[10:11]
	s_mov_b32 m0, s44
	s_nop 0
	global_load_lds_dwordx4 v[148:149], off
	v_lshl_add_u64 v[148:149], v[220:221], 0, s[10:11]
	s_mov_b32 m0, s45
	s_nop 0
	global_load_lds_dwordx4 v[148:149], off
	s_waitcnt vmcnt(8)
	s_waitcnt lgkmcnt(0)
	s_barrier
	s_waitcnt lgkmcnt(0)
	v_mfma_f32_16x16x32_bf16 v[60:63], v[144:147], v[184:187], v[60:63]
	v_mfma_f32_16x16x32_bf16 v[56:59], v[160:163], v[184:187], v[56:59]
	v_mfma_f32_16x16x32_bf16 v[44:47], v[144:147], v[192:195], v[44:47]
	v_mfma_f32_16x16x32_bf16 v[40:43], v[160:163], v[192:195], v[40:43]
	v_mfma_f32_16x16x32_bf16 v[28:31], v[144:147], v[200:203], v[28:31]
	v_mfma_f32_16x16x32_bf16 v[24:27], v[160:163], v[200:203], v[24:27]
	v_mfma_f32_16x16x32_bf16 v[12:15], v[144:147], v[208:211], v[12:15]
	v_mfma_f32_16x16x32_bf16 v[8:11], v[160:163], v[208:211], v[8:11]
	v_mfma_f32_16x16x32_bf16 v[60:63], v[156:159], v[188:191], v[60:63]
	v_mfma_f32_16x16x32_bf16 v[56:59], v[164:167], v[188:191], v[56:59]
	v_mfma_f32_16x16x32_bf16 v[44:47], v[156:159], v[196:199], v[44:47]
	v_mfma_f32_16x16x32_bf16 v[40:43], v[164:167], v[196:199], v[40:43]
	v_mfma_f32_16x16x32_bf16 v[28:31], v[156:159], v[204:207], v[28:31]
	v_mfma_f32_16x16x32_bf16 v[24:27], v[164:167], v[204:207], v[24:27]
	v_mfma_f32_16x16x32_bf16 v[12:15], v[156:159], v[212:215], v[12:15]
	v_mfma_f32_16x16x32_bf16 v[8:11], v[164:167], v[212:215], v[8:11]
	v_mfma_f32_16x16x32_bf16 v[52:55], v[168:171], v[184:187], v[52:55]
	v_mfma_f32_16x16x32_bf16 v[48:51], v[176:179], v[184:187], v[48:51]
	v_mfma_f32_16x16x32_bf16 v[36:39], v[168:171], v[192:195], v[36:39]
	v_mfma_f32_16x16x32_bf16 v[32:35], v[176:179], v[192:195], v[32:35]
	v_mfma_f32_16x16x32_bf16 v[20:23], v[168:171], v[200:203], v[20:23]
	v_mfma_f32_16x16x32_bf16 v[16:19], v[176:179], v[200:203], v[16:19]
	v_mfma_f32_16x16x32_bf16 v[4:7], v[168:171], v[208:211], v[4:7]
	v_mfma_f32_16x16x32_bf16 v[0:3], v[176:179], v[208:211], v[0:3]
	v_mfma_f32_16x16x32_bf16 v[52:55], v[172:175], v[188:191], v[52:55]
	v_mfma_f32_16x16x32_bf16 v[48:51], v[180:183], v[188:191], v[48:51]
	v_mfma_f32_16x16x32_bf16 v[36:39], v[172:175], v[196:199], v[36:39]
	v_mfma_f32_16x16x32_bf16 v[32:35], v[180:183], v[196:199], v[32:35]
	v_mfma_f32_16x16x32_bf16 v[20:23], v[172:175], v[204:207], v[20:23]
	v_mfma_f32_16x16x32_bf16 v[16:19], v[180:183], v[204:207], v[16:19]
	v_mfma_f32_16x16x32_bf16 v[4:7], v[172:175], v[212:215], v[4:7]
	v_mfma_f32_16x16x32_bf16 v[0:3], v[180:183], v[212:215], v[0:3]
	s_barrier
	s_add_i32 s53, s53, 2
	s_add_u32 s34, s34, 0x100
	s_addc_u32 s35, s35, 0
	s_cmpk_gt_u32 s53, 0xbd
	s_mov_b64 s[26:27], s[28:29]
	s_cbranch_scc0 .LBB0_1077
	s_setprio 0
	s_and_b64 vcc, exec, s[12:13]
	s_cbranch_vccz .LBB0_1080
	s_barrier

.LBB0_1312:
	s_ashr_i32 s29, s28, 31
	s_lshl_b64 s[30:31], s[28:29], 21
	s_add_u32 s30, s86, s30
	s_addc_u32 s31, s87, s31
	s_and_b64 s[34:35], s[4:5], exec
	s_cselect_b32 s14, s31, s41
	s_cselect_b32 s29, s30, s40
	s_ashr_i32 s27, s26, 31
	s_lshl_b64 s[34:35], s[26:27], 21
	v_readlane_b32 s27, v254, 0
	s_add_u32 s36, s27, s34
	s_addc_u32 s37, s33, s35
	s_and_b64 s[34:35], s[4:5], exec
	s_cselect_b32 s27, s37, s43
	s_cselect_b32 s39, s36, s42
	s_add_u32 s40, s40, 0x100080
	s_addc_u32 s41, s41, 0
	s_add_u32 s34, s42, 0x100
	v_mov_b32_e32 v0, 0
	s_addc_u32 s35, s43, 0
	s_mov_b32 s60, -2
	s_waitcnt lgkmcnt(0)
	v_mov_b32_e32 v1, v0
	v_mov_b32_e32 v2, v0
	v_mov_b32_e32 v3, v0
	v_mov_b32_e32 v4, v0
	v_mov_b32_e32 v5, v0
	v_mov_b32_e32 v6, v0
	v_mov_b32_e32 v7, v0
	v_mov_b32_e32 v16, v0
	v_mov_b32_e32 v17, v0
	v_mov_b32_e32 v18, v0
	v_mov_b32_e32 v19, v0
	v_mov_b32_e32 v20, v0
	v_mov_b32_e32 v21, v0
	v_mov_b32_e32 v22, v0
	v_mov_b32_e32 v23, v0
	v_mov_b32_e32 v32, v0
	v_mov_b32_e32 v33, v0
	v_mov_b32_e32 v34, v0
	v_mov_b32_e32 v35, v0
	v_mov_b32_e32 v36, v0
	v_mov_b32_e32 v37, v0
	v_mov_b32_e32 v38, v0
	v_mov_b32_e32 v39, v0
	v_mov_b32_e32 v64, v0
	v_mov_b32_e32 v65, v0
	v_mov_b32_e32 v66, v0
	v_mov_b32_e32 v67, v0
	v_mov_b32_e32 v68, v0
	v_mov_b32_e32 v69, v0
	v_mov_b32_e32 v70, v0
	v_mov_b32_e32 v71, v0
	v_mov_b32_e32 v8, v0
	v_mov_b32_e32 v9, v0
	v_mov_b32_e32 v10, v0
	v_mov_b32_e32 v11, v0
	v_mov_b32_e32 v12, v0
	v_mov_b32_e32 v13, v0
	v_mov_b32_e32 v14, v0
	v_mov_b32_e32 v15, v0
	v_mov_b32_e32 v24, v0
	v_mov_b32_e32 v25, v0
	v_mov_b32_e32 v26, v0
	v_mov_b32_e32 v27, v0
	v_mov_b32_e32 v28, v0
	v_mov_b32_e32 v29, v0
	v_mov_b32_e32 v30, v0
	v_mov_b32_e32 v31, v0
	v_mov_b32_e32 v56, v0
	v_mov_b32_e32 v57, v0
	v_mov_b32_e32 v58, v0
	v_mov_b32_e32 v59, v0
	v_mov_b32_e32 v60, v0
	v_mov_b32_e32 v61, v0
	v_mov_b32_e32 v62, v0
	v_mov_b32_e32 v63, v0
	v_mov_b32_e32 v72, v0
	v_mov_b32_e32 v73, v0
	v_mov_b32_e32 v74, v0
	v_mov_b32_e32 v75, v0
	v_mov_b32_e32 v76, v0
	v_mov_b32_e32 v77, v0
	v_mov_b32_e32 v78, v0
	v_mov_b32_e32 v79, v0
	v_mov_b32_e32 v80, v0
	v_mov_b32_e32 v81, v0
	v_mov_b32_e32 v82, v0
	v_mov_b32_e32 v83, v0
	v_mov_b32_e32 v84, v0
	v_mov_b32_e32 v85, v0
	v_mov_b32_e32 v86, v0
	v_mov_b32_e32 v87, v0
	v_mov_b32_e32 v96, v0
	v_mov_b32_e32 v97, v0
	v_mov_b32_e32 v98, v0
	v_mov_b32_e32 v99, v0
	v_mov_b32_e32 v100, v0
	v_mov_b32_e32 v101, v0
	v_mov_b32_e32 v102, v0
	v_mov_b32_e32 v103, v0
	v_mov_b32_e32 v112, v0
	v_mov_b32_e32 v113, v0
	v_mov_b32_e32 v114, v0
	v_mov_b32_e32 v115, v0
	v_mov_b32_e32 v116, v0
	v_mov_b32_e32 v117, v0
	v_mov_b32_e32 v118, v0
	v_mov_b32_e32 v119, v0
	v_mov_b32_e32 v128, v0
	v_mov_b32_e32 v129, v0
	v_mov_b32_e32 v130, v0
	v_mov_b32_e32 v131, v0
	v_mov_b32_e32 v132, v0
	v_mov_b32_e32 v133, v0
	v_mov_b32_e32 v134, v0
	v_mov_b32_e32 v135, v0
	v_mov_b32_e32 v88, v0
	v_mov_b32_e32 v89, v0
	v_mov_b32_e32 v90, v0
	v_mov_b32_e32 v91, v0
	v_mov_b32_e32 v92, v0
	v_mov_b32_e32 v93, v0
	v_mov_b32_e32 v94, v0
	v_mov_b32_e32 v95, v0
	v_mov_b32_e32 v104, v0
	v_mov_b32_e32 v105, v0
	v_mov_b32_e32 v106, v0
	v_mov_b32_e32 v107, v0
	v_mov_b32_e32 v108, v0
	v_mov_b32_e32 v109, v0
	v_mov_b32_e32 v110, v0
	v_mov_b32_e32 v111, v0
	v_mov_b32_e32 v120, v0
	v_mov_b32_e32 v121, v0
	v_mov_b32_e32 v122, v0
	v_mov_b32_e32 v123, v0
	v_mov_b32_e32 v124, v0
	v_mov_b32_e32 v125, v0
	v_mov_b32_e32 v126, v0
	v_mov_b32_e32 v127, v0
	v_mov_b32_e32 v40, v0
	v_mov_b32_e32 v41, v0
	v_mov_b32_e32 v42, v0
	v_mov_b32_e32 v43, v0
	v_mov_b32_e32 v44, v0
	v_mov_b32_e32 v45, v0
	v_mov_b32_e32 v46, v0
	v_mov_b32_e32 v47, v0
	s_cmpk_lt_u32 s97, 0x100
	s_cbranch_scc1 .Lmy_prio_skip7
	s_setprio 1
.Lmy_prio_skip7:
.LBB0_1313:
	ds_read_b128 v[48:51], v163
	ds_read_b128 v[52:55], v163 offset:1024
	ds_read_b128 v[152:155], v163 offset:2048
	ds_read_b128 v[156:159], v163 offset:3072
	ds_read_b128 v[168:171], v164
	ds_read_b128 v[172:175], v164 offset:1024
	ds_read_b128 v[176:179], v164 offset:2048
	ds_read_b128 v[180:183], v164 offset:3072
	s_add_u32 s42, s40, 0xfff00080
	s_addc_u32 s43, s41, -1
	s_cmp_eq_u32 s60, 60
	s_cselect_b32 s45, s14, s43
	s_cselect_b32 s44, s29, s42
	s_cselect_b32 s43, s27, s35
	s_cselect_b32 s42, s39, s34
	v_lshl_add_u64 v[216:217], s[40:41], 0, v[144:145]
	s_add_i32 m0, s47, 0xc000
	ds_read_b128 v[184:187], v165
	ds_read_b128 v[188:191], v165 offset:1024
	ds_read_b128 v[192:195], v165 offset:2048
	ds_read_b128 v[196:199], v165 offset:3072
	ds_read_b128 v[200:203], v165 offset:4096
	ds_read_b128 v[204:207], v165 offset:5120
	ds_read_b128 v[208:211], v165 offset:6144
	ds_read_b128 v[212:215], v165 offset:7168
	global_load_lds_dwordx4 v[216:217], off
	v_lshl_add_u64 v[216:217], s[40:41], 0, v[146:147]
	s_add_i32 m0, s47, 0xe000
	s_nop 0
	global_load_lds_dwordx4 v[216:217], off
	s_waitcnt vmcnt(8)
	s_waitcnt lgkmcnt(0)
	s_barrier
	s_waitcnt lgkmcnt(0)
	v_mfma_f32_16x16x32_bf16 v[44:47], v[48:51], v[184:187], v[44:47]
	v_mfma_f32_16x16x32_bf16 v[40:43], v[152:155], v[184:187], v[40:43]
	v_mfma_f32_16x16x32_bf16 v[124:127], v[48:51], v[192:195], v[124:127]
	v_mfma_f32_16x16x32_bf16 v[120:123], v[152:155], v[192:195], v[120:123]
	v_mfma_f32_16x16x32_bf16 v[108:111], v[48:51], v[200:203], v[108:111]
	v_mfma_f32_16x16x32_bf16 v[104:107], v[152:155], v[200:203], v[104:107]
	v_mfma_f32_16x16x32_bf16 v[92:95], v[48:51], v[208:211], v[92:95]
	v_mfma_f32_16x16x32_bf16 v[88:91], v[152:155], v[208:211], v[88:91]
	v_mfma_f32_16x16x32_bf16 v[44:47], v[52:55], v[188:191], v[44:47]
	v_mfma_f32_16x16x32_bf16 v[40:43], v[156:159], v[188:191], v[40:43]
	v_mfma_f32_16x16x32_bf16 v[124:127], v[52:55], v[196:199], v[124:127]
	v_mfma_f32_16x16x32_bf16 v[120:123], v[156:159], v[196:199], v[120:123]
	v_mfma_f32_16x16x32_bf16 v[108:111], v[52:55], v[204:207], v[108:111]
	v_mfma_f32_16x16x32_bf16 v[104:107], v[156:159], v[204:207], v[104:107]
	v_mfma_f32_16x16x32_bf16 v[92:95], v[52:55], v[212:215], v[92:95]
	v_mfma_f32_16x16x32_bf16 v[88:91], v[156:159], v[212:215], v[88:91]
	v_mfma_f32_16x16x32_bf16 v[132:135], v[168:171], v[184:187], v[132:135]
	v_mfma_f32_16x16x32_bf16 v[128:131], v[176:179], v[184:187], v[128:131]
	v_mfma_f32_16x16x32_bf16 v[116:119], v[168:171], v[192:195], v[116:119]
	v_mfma_f32_16x16x32_bf16 v[112:115], v[176:179], v[192:195], v[112:115]
	v_mfma_f32_16x16x32_bf16 v[100:103], v[168:171], v[200:203], v[100:103]
	v_mfma_f32_16x16x32_bf16 v[96:99], v[176:179], v[200:203], v[96:99]
	v_mfma_f32_16x16x32_bf16 v[84:87], v[168:171], v[208:211], v[84:87]
	v_mfma_f32_16x16x32_bf16 v[80:83], v[176:179], v[208:211], v[80:83]
	v_mfma_f32_16x16x32_bf16 v[132:135], v[172:175], v[188:191], v[132:135]
	v_mfma_f32_16x16x32_bf16 v[128:131], v[180:183], v[188:191], v[128:131]
	v_mfma_f32_16x16x32_bf16 v[116:119], v[172:175], v[196:199], v[116:119]
	v_mfma_f32_16x16x32_bf16 v[112:115], v[180:183], v[196:199], v[112:115]
	v_mfma_f32_16x16x32_bf16 v[100:103], v[172:175], v[204:207], v[100:103]
	v_mfma_f32_16x16x32_bf16 v[96:99], v[180:183], v[204:207], v[96:99]
	v_mfma_f32_16x16x32_bf16 v[84:87], v[172:175], v[212:215], v[84:87]
	v_mfma_f32_16x16x32_bf16 v[80:83], v[180:183], v[212:215], v[80:83]
	s_barrier
	s_add_i32 s61, s56, s46
	v_lshl_add_u64 v[216:217], s[42:43], 0, v[138:139]
	s_mov_b32 m0, s61
	ds_read_b128 v[184:187], v165 offset:16384
	ds_read_b128 v[188:191], v165 offset:17408
	ds_read_b128 v[192:195], v165 offset:18432
	ds_read_b128 v[196:199], v165 offset:19456
	ds_read_b128 v[200:203], v165 offset:20480
	ds_read_b128 v[204:207], v165 offset:21504
	ds_read_b128 v[208:211], v165 offset:22528
	ds_read_b128 v[212:215], v165 offset:23552
	global_load_lds_dwordx4 v[216:217], off
	s_add_i32 m0, s61, 0x2000
	s_add_u32 s62, s42, 0x100000
	v_lshl_add_u64 v[218:219], s[42:43], 0, v[142:143]
	s_addc_u32 s63, s43, 0
	s_add_i32 s61, s57, s46
	global_load_lds_dwordx4 v[218:219], off
	v_lshl_add_u64 v[220:221], s[62:63], 0, v[138:139]
	s_mov_b32 m0, s61
	v_lshl_add_u64 v[222:223], s[44:45], 0, v[140:141]
	global_load_lds_dwordx4 v[220:221], off
	v_lshl_add_u64 v[220:221], s[62:63], 0, v[142:143]
	s_add_i32 m0, s61, 0x2000
	s_nop 0
	global_load_lds_dwordx4 v[220:221], off
	v_lshl_add_u64 v[220:221], s[44:45], 0, v[136:137]
	s_mov_b32 m0, s47
	s_nop 0
	global_load_lds_dwordx4 v[220:221], off
	s_mov_b32 m0, s48
	s_nop 0
	global_load_lds_dwordx4 v[222:223], off
	s_waitcnt vmcnt(8)
	s_waitcnt lgkmcnt(0)
	s_barrier
	s_waitcnt lgkmcnt(0)
	v_mfma_f32_16x16x32_bf16 v[76:79], v[48:51], v[184:187], v[76:79]
	v_mfma_f32_16x16x32_bf16 v[72:75], v[152:155], v[184:187], v[72:75]
	v_mfma_f32_16x16x32_bf16 v[60:63], v[48:51], v[192:195], v[60:63]
	v_mfma_f32_16x16x32_bf16 v[56:59], v[152:155], v[192:195], v[56:59]
	v_mfma_f32_16x16x32_bf16 v[28:31], v[48:51], v[200:203], v[28:31]
	v_mfma_f32_16x16x32_bf16 v[24:27], v[152:155], v[200:203], v[24:27]
	v_mfma_f32_16x16x32_bf16 v[12:15], v[48:51], v[208:211], v[12:15]
	v_mfma_f32_16x16x32_bf16 v[8:11], v[152:155], v[208:211], v[8:11]
	v_mfma_f32_16x16x32_bf16 v[76:79], v[52:55], v[188:191], v[76:79]
	v_mfma_f32_16x16x32_bf16 v[72:75], v[156:159], v[188:191], v[72:75]
	v_mfma_f32_16x16x32_bf16 v[60:63], v[52:55], v[196:199], v[60:63]
	v_mfma_f32_16x16x32_bf16 v[56:59], v[156:159], v[196:199], v[56:59]
	v_mfma_f32_16x16x32_bf16 v[28:31], v[52:55], v[204:207], v[28:31]
	v_mfma_f32_16x16x32_bf16 v[24:27], v[156:159], v[204:207], v[24:27]
	v_mfma_f32_16x16x32_bf16 v[12:15], v[52:55], v[212:215], v[12:15]
	v_mfma_f32_16x16x32_bf16 v[8:11], v[156:159], v[212:215], v[8:11]
	v_mfma_f32_16x16x32_bf16 v[36:39], v[168:171], v[192:195], v[36:39]
	v_mfma_f32_16x16x32_bf16 v[32:35], v[176:179], v[192:195], v[32:35]
	v_mfma_f32_16x16x32_bf16 v[20:23], v[168:171], v[200:203], v[20:23]
	v_mfma_f32_16x16x32_bf16 v[16:19], v[176:179], v[200:203], v[16:19]
	v_mfma_f32_16x16x32_bf16 v[4:7], v[168:171], v[208:211], v[4:7]
	v_mfma_f32_16x16x32_bf16 v[0:3], v[176:179], v[208:211], v[0:3]
	v_mfma_f32_16x16x32_bf16 v[48:51], v[168:171], v[184:187], v[68:71]
	v_mfma_f32_16x16x32_bf16 v[52:55], v[176:179], v[184:187], v[64:67]
	v_mfma_f32_16x16x32_bf16 v[36:39], v[172:175], v[196:199], v[36:39]
	v_mfma_f32_16x16x32_bf16 v[32:35], v[180:183], v[196:199], v[32:35]
	v_mfma_f32_16x16x32_bf16 v[20:23], v[172:175], v[204:207], v[20:23]
	v_mfma_f32_16x16x32_bf16 v[16:19], v[180:183], v[204:207], v[16:19]
	v_mfma_f32_16x16x32_bf16 v[4:7], v[172:175], v[212:215], v[4:7]
	v_mfma_f32_16x16x32_bf16 v[0:3], v[180:183], v[212:215], v[0:3]
	v_mfma_f32_16x16x32_bf16 v[48:51], v[172:175], v[188:191], v[48:51]
	v_mfma_f32_16x16x32_bf16 v[52:55], v[180:183], v[188:191], v[52:55]
	s_barrier
	s_add_i32 s61, 0, 0x18000
	s_add_i32 s62, 0, 0x1c000
	v_add_u32_e32 v156, s61, v161
	v_add_u32_e32 v167, s62, v161
	ds_read_b128 v[64:67], v156
	ds_read_b128 v[68:71], v156 offset:1024
	ds_read_b128 v[152:155], v156 offset:2048
	ds_read_b128 v[156:159], v156 offset:3072
	ds_read_b128 v[168:171], v167
	ds_read_b128 v[172:175], v167 offset:1024
	ds_read_b128 v[176:179], v167 offset:2048
	ds_read_b128 v[180:183], v167 offset:3072
	s_add_u32 s44, s44, 0x100000
	s_addc_u32 s45, s45, 0
	s_mov_b32 m0, s49
	v_lshl_add_u64 v[226:227], s[44:45], 0, v[136:137]
	ds_read_b128 v[184:187], v165 offset:32768
	ds_read_b128 v[188:191], v165 offset:33792
	ds_read_b128 v[192:195], v165 offset:34816
	ds_read_b128 v[196:199], v165 offset:35840
	ds_read_b128 v[200:203], v165 offset:36864
	ds_read_b128 v[204:207], v165 offset:37888
	ds_read_b128 v[208:211], v165 offset:38912
	ds_read_b128 v[212:215], v165 offset:39936
	global_load_lds_dwordx4 v[226:227], off
	v_lshl_add_u64 v[226:227], s[44:45], 0, v[140:141]
	s_mov_b32 m0, s50
	s_nop 0
	global_load_lds_dwordx4 v[226:227], off
	s_waitcnt vmcnt(8)
	s_waitcnt lgkmcnt(0)
	s_barrier
	s_waitcnt lgkmcnt(0)
	v_mfma_f32_16x16x32_bf16 v[44:47], v[64:67], v[184:187], v[44:47]
	v_mfma_f32_16x16x32_bf16 v[40:43], v[152:155], v[184:187], v[40:43]
	v_mfma_f32_16x16x32_bf16 v[124:127], v[64:67], v[192:195], v[124:127]
	v_mfma_f32_16x16x32_bf16 v[120:123], v[152:155], v[192:195], v[120:123]
	v_mfma_f32_16x16x32_bf16 v[108:111], v[64:67], v[200:203], v[108:111]
	v_mfma_f32_16x16x32_bf16 v[104:107], v[152:155], v[200:203], v[104:107]
	v_mfma_f32_16x16x32_bf16 v[92:95], v[64:67], v[208:211], v[92:95]
	v_mfma_f32_16x16x32_bf16 v[88:91], v[152:155], v[208:211], v[88:91]
	v_mfma_f32_16x16x32_bf16 v[44:47], v[68:71], v[188:191], v[44:47]
	v_mfma_f32_16x16x32_bf16 v[40:43], v[156:159], v[188:191], v[40:43]
	v_mfma_f32_16x16x32_bf16 v[124:127], v[68:71], v[196:199], v[124:127]
	v_mfma_f32_16x16x32_bf16 v[120:123], v[156:159], v[196:199], v[120:123]
	v_mfma_f32_16x16x32_bf16 v[108:111], v[68:71], v[204:207], v[108:111]
	v_mfma_f32_16x16x32_bf16 v[104:107], v[156:159], v[204:207], v[104:107]
	v_mfma_f32_16x16x32_bf16 v[92:95], v[68:71], v[212:215], v[92:95]
	v_mfma_f32_16x16x32_bf16 v[88:91], v[156:159], v[212:215], v[88:91]
	v_mfma_f32_16x16x32_bf16 v[132:135], v[168:171], v[184:187], v[132:135]
	v_mfma_f32_16x16x32_bf16 v[128:131], v[176:179], v[184:187], v[128:131]
	v_mfma_f32_16x16x32_bf16 v[116:119], v[168:171], v[192:195], v[116:119]
	v_mfma_f32_16x16x32_bf16 v[112:115], v[176:179], v[192:195], v[112:115]
	v_mfma_f32_16x16x32_bf16 v[100:103], v[168:171], v[200:203], v[100:103]
	v_mfma_f32_16x16x32_bf16 v[96:99], v[176:179], v[200:203], v[96:99]
	v_mfma_f32_16x16x32_bf16 v[84:87], v[168:171], v[208:211], v[84:87]
	v_mfma_f32_16x16x32_bf16 v[80:83], v[176:179], v[208:211], v[80:83]
	v_mfma_f32_16x16x32_bf16 v[132:135], v[172:175], v[188:191], v[132:135]
	v_mfma_f32_16x16x32_bf16 v[128:131], v[180:183], v[188:191], v[128:131]
	v_mfma_f32_16x16x32_bf16 v[116:119], v[172:175], v[196:199], v[116:119]
	v_mfma_f32_16x16x32_bf16 v[112:115], v[180:183], v[196:199], v[112:115]
	v_mfma_f32_16x16x32_bf16 v[100:103], v[172:175], v[204:207], v[100:103]
	v_mfma_f32_16x16x32_bf16 v[96:99], v[180:183], v[204:207], v[96:99]
	v_mfma_f32_16x16x32_bf16 v[84:87], v[172:175], v[212:215], v[84:87]
	v_mfma_f32_16x16x32_bf16 v[80:83], v[180:183], v[212:215], v[80:83]
	s_barrier
	s_add_i32 s44, s61, s46
	v_lshl_add_u64 v[216:217], v[216:217], 0, s[22:23]
	s_mov_b32 m0, s44
	ds_read_b128 v[184:187], v165 offset:49152
	ds_read_b128 v[188:191], v165 offset:50176
	ds_read_b128 v[192:195], v165 offset:51200
	ds_read_b128 v[196:199], v165 offset:52224
	ds_read_b128 v[200:203], v165 offset:53248
	ds_read_b128 v[204:207], v165 offset:54272
	ds_read_b128 v[208:211], v165 offset:55296
	ds_read_b128 v[212:215], v165 offset:56320
	global_load_lds_dwordx4 v[216:217], off
	s_add_i32 m0, s44, 0x2000
	s_add_u32 s42, s42, 0x100080
	v_lshl_add_u64 v[216:217], v[218:219], 0, s[22:23]
	s_addc_u32 s43, s43, 0
	s_add_i32 s44, s62, s46
	global_load_lds_dwordx4 v[216:217], off
	v_lshl_add_u64 v[216:217], s[42:43], 0, v[138:139]
	s_mov_b32 m0, s44
	s_nop 0
	global_load_lds_dwordx4 v[216:217], off
	v_lshl_add_u64 v[216:217], s[42:43], 0, v[142:143]
	s_add_i32 m0, s44, 0x2000
	s_nop 0
	global_load_lds_dwordx4 v[216:217], off
	v_lshl_add_u64 v[216:217], v[220:221], 0, s[22:23]
	s_mov_b32 m0, s52
	s_nop 0
	global_load_lds_dwordx4 v[216:217], off
	v_lshl_add_u64 v[216:217], v[222:223], 0, s[22:23]
	s_mov_b32 m0, s53
	s_nop 0
	global_load_lds_dwordx4 v[216:217], off
	s_waitcnt vmcnt(8)
	s_waitcnt lgkmcnt(0)
	s_barrier
	s_waitcnt lgkmcnt(0)
	v_mfma_f32_16x16x32_bf16 v[76:79], v[64:67], v[184:187], v[76:79]
	v_mfma_f32_16x16x32_bf16 v[72:75], v[152:155], v[184:187], v[72:75]
	v_mfma_f32_16x16x32_bf16 v[60:63], v[64:67], v[192:195], v[60:63]
	v_mfma_f32_16x16x32_bf16 v[56:59], v[152:155], v[192:195], v[56:59]
	v_mfma_f32_16x16x32_bf16 v[28:31], v[64:67], v[200:203], v[28:31]
	v_mfma_f32_16x16x32_bf16 v[24:27], v[152:155], v[200:203], v[24:27]
	v_mfma_f32_16x16x32_bf16 v[12:15], v[64:67], v[208:211], v[12:15]
	v_mfma_f32_16x16x32_bf16 v[8:11], v[152:155], v[208:211], v[8:11]
	v_mfma_f32_16x16x32_bf16 v[76:79], v[68:71], v[188:191], v[76:79]
	v_mfma_f32_16x16x32_bf16 v[72:75], v[156:159], v[188:191], v[72:75]
	v_mfma_f32_16x16x32_bf16 v[60:63], v[68:71], v[196:199], v[60:63]
	v_mfma_f32_16x16x32_bf16 v[56:59], v[156:159], v[196:199], v[56:59]
	v_mfma_f32_16x16x32_bf16 v[28:31], v[68:71], v[204:207], v[28:31]
	v_mfma_f32_16x16x32_bf16 v[24:27], v[156:159], v[204:207], v[24:27]
	v_mfma_f32_16x16x32_bf16 v[12:15], v[68:71], v[212:215], v[12:15]
	v_mfma_f32_16x16x32_bf16 v[8:11], v[156:159], v[212:215], v[8:11]
	v_mfma_f32_16x16x32_bf16 v[48:51], v[168:171], v[184:187], v[48:51]
	v_mfma_f32_16x16x32_bf16 v[68:71], v[172:175], v[188:191], v[48:51]
	v_mfma_f32_16x16x32_bf16 v[48:51], v[176:179], v[184:187], v[52:55]
	v_mfma_f32_16x16x32_bf16 v[36:39], v[168:171], v[192:195], v[36:39]
	v_mfma_f32_16x16x32_bf16 v[32:35], v[176:179], v[192:195], v[32:35]
	v_mfma_f32_16x16x32_bf16 v[20:23], v[168:171], v[200:203], v[20:23]
	v_mfma_f32_16x16x32_bf16 v[16:19], v[176:179], v[200:203], v[16:19]
	v_mfma_f32_16x16x32_bf16 v[4:7], v[168:171], v[208:211], v[4:7]
	v_mfma_f32_16x16x32_bf16 v[0:3], v[176:179], v[208:211], v[0:3]
	v_mfma_f32_16x16x32_bf16 v[64:67], v[180:183], v[188:191], v[48:51]
	v_mfma_f32_16x16x32_bf16 v[36:39], v[172:175], v[196:199], v[36:39]
	v_mfma_f32_16x16x32_bf16 v[32:35], v[180:183], v[196:199], v[32:35]
	v_mfma_f32_16x16x32_bf16 v[20:23], v[172:175], v[204:207], v[20:23]
	v_mfma_f32_16x16x32_bf16 v[16:19], v[180:183], v[204:207], v[16:19]
	v_mfma_f32_16x16x32_bf16 v[4:7], v[172:175], v[212:215], v[4:7]
	v_mfma_f32_16x16x32_bf16 v[0:3], v[180:183], v[212:215], v[0:3]
	s_barrier
	s_add_i32 s60, s60, 2
	s_add_u32 s40, s40, 0x100
	s_addc_u32 s41, s41, 0
	s_add_u32 s34, s34, 0x100
	s_addc_u32 s35, s35, 0
	s_cmp_gt_u32 s60, 61
	s_cbranch_scc0 .LBB0_1313
	s_setprio 0
	s_and_b64 vcc, exec, s[24:25]
	s_cbranch_vccz .LBB0_1316
	s_barrier
